# K-loops without the s_setprio flips (the loading wave has no VALU left to arbitrate against)
# baseline (speedup 1.0000x reference)
; #define PG8_STAGEA(bufoff, gbase, voff) PG8_STAGE_X(bufoff, gbase, voff, AUXA)
; #define PG8_STAGEB(bufoff, gbase, voff) PG8_STAGE_X(bufoff, gbase, voff, AUXB)
; #define PG8_LDA(dst, b, h) do { _Pragma("unroll") for (int m = 0; m < 4; ++m) _Pragma("unroll") for (int k = 0; k < 2; ++k) dst[m][k] = *(const PG8_LAS bf16x8*)(lds + PG8_SA(b, h) + aoff + m * 2048 + k * 1024); } while (0)
; #define PG8_LDB(dst, b, h) do { _Pragma("unroll") for (int n = 0; n < 2; ++n) _Pragma("unroll") for (int k = 0; k < 2; ++k) dst[n][k] = *(const PG8_LAS bf16x8*)(lds + PG8_SB(b, h) + boff + n * 2048 + k * 1024); } while (0)
; #define PG8_MMA(ai, bj, At, Bt) do { if (GEMM_PRIO_MODE == 0) __builtin_amdgcn_s_setprio(1); PG8_MMA_LOOPS \
;         acc[ai][bj][m][n] = __builtin_amdgcn_mfma_f32_16x16x32_bf16(Bt[n][k], At[m][k], acc[ai][bj][m][n], 0, 0, 0); if (GEMM_PRIO_MODE == 0) __builtin_amdgcn_s_setprio(0); } while (0)
; #define PG8_WAIT_V(n) asm volatile("s_waitcnt vmcnt(" #n ")" ::: "memory")
; #define PG8_WAIT_VR(n, nr, flag) asm volatile("s_cmp_eq_u32 %0, 0\n\ts_cbranch_scc1 .Lpg8s%=\n\ts_waitcnt vmcnt(" #nr ")\n\ts_branch .Lpg8d%=\n.Lpg8s%=:\n\ts_waitcnt vmcnt(" #n ")\n.Lpg8d%=:" :: "s"(flag) : "memory", "scc")
; #define PG8_WAIT_L(n) asm volatile("s_waitcnt lgkmcnt(" #n ")" ::: "memory")
; #define PG8_BAR __builtin_amdgcn_s_barrier()
; #define PG8_SCHED __builtin_amdgcn_sched_barrier(0)
;     ...
;             PG8_LDB(B0, 0, 0); PG8_LDB(B1, 0, 1); PG8_SCHED; PG8_LDA(At, 0, 0); PG8_STAGEA(PG8_SA(1, 1), a1 + hstepA, voffA);
;     ...
;             const int relax = __builtin_amdgcn_readfirstlane((t == 0 && ui > 0) ? 1 : 0);
;             PG8_WAIT_VR(8, 24, relax); PG8_WAIT_L(0); PG8_BAR; PG8_MMA(0, 0, At, B0); PG8_MMA(0, 1, At, B1); PG8_BAR; PG8_SCHED;
;     ...
;             PG8_WAIT_V(8); PG8_WAIT_L(0); PG8_BAR; PG8_MMA(0, 0, At, B0); PG8_MMA(0, 1, At, B1); PG8_BAR; PG8_SCHED;
;     ...
;             PG8_LDA(At, 0, 1); PG8_STAGEB(PG8_SB(0, 0), b2, voffB); PG8_STAGEB(PG8_SB(0, 1), b2 + hstepB, voffB); PG8_STAGEA(PG8_SA(0, 0), a2, voffA);
;     ...
;             PG8_WAIT_VR(8, 24, relax); PG8_WAIT_L(0); PG8_BAR; PG8_MMA(1, 0, At, B0); PG8_MMA(1, 1, At, B1); PG8_BAR; PG8_SCHED;
;     ...
;             PG8_WAIT_V(8); PG8_WAIT_L(0); PG8_BAR; PG8_MMA(1, 0, At, B0); PG8_MMA(1, 1, At, B1); PG8_BAR; PG8_SCHED;
.LBB0_128:
	s_ashr_i32 s37, s36, 31
	s_lshl_b64 s[4:5], s[36:37], 21
	s_add_u32 s38, s56, s4
	s_addc_u32 s39, s57, s5
	s_and_b64 s[4:5], s[6:7], exec
	s_cselect_b32 s4, s39, s1
	s_cselect_b32 s5, s38, s0
	s_ashr_i32 s27, s26, 31
	s_lshl_b64 s[8:9], s[26:27], 21
	s_add_u32 s40, s43, s8
	s_addc_u32 s41, s50, s9
	s_and_b64 s[8:9], s[6:7], exec
	s_cselect_b32 s16, s41, s11
	s_cselect_b32 s17, s40, s10
	s_add_u32 s8, s0, 0x100080
	s_addc_u32 s9, s1, 0
	s_add_u32 s0, s10, 0x100
	s_addc_u32 s1, s11, 0
	s_mov_b32 s27, -2
	s_add_u32 s10, s8, 0xfff00080
	s_addc_u32 s11, s9, -1
	s_add_i32 s18, 0, 0x10000
	s_cmp_eq_u32 s27, 60
	s_cselect_b32 s15, s4, s11
	s_cselect_b32 s14, s5, s10
	v_add_u32_e32 v16, s18, v167
	s_cselect_b32 s11, s16, s1
	s_cselect_b32 s10, s17, s0
	s_add_i32 s20, 0, 0x14000
	s_waitcnt lgkmcnt(0)
	ds_read_b128 v[130:133], v16
	ds_read_b128 v[134:137], v16 offset:1024
	ds_read_b128 v[152:155], v16 offset:2048
	ds_read_b128 v[156:159], v16 offset:3072
	v_add_u32_e32 v16, s20, v167
	ds_read_b128 v[160:163], v16
	ds_read_b128 v[174:177], v16 offset:1024
	ds_read_b128 v[178:181], v16 offset:2048
	ds_read_b128 v[182:185], v16 offset:3072
	v_lshl_add_u64 v[164:165], s[8:9], 0, v[148:149]
	s_add_i32 m0, s51, 0xc000
	ds_read_b128 v[186:189], v172
	ds_read_b128 v[190:193], v172 offset:1024
	ds_read_b128 v[194:197], v172 offset:2048
	ds_read_b128 v[198:201], v172 offset:3072
	ds_read_b128 v[202:205], v172 offset:4096
	ds_read_b128 v[206:209], v172 offset:5120
	ds_read_b128 v[210:213], v172 offset:6144
	ds_read_b128 v[214:217], v172 offset:7168
	global_load_lds_dwordx4 v[164:165], off
	v_lshl_add_u64 v[164:165], s[8:9], 0, v[150:151]
	s_add_i32 m0, s51, 0xe000
	s_nop 0
	global_load_lds_dwordx4 v[164:165], off
	s_waitcnt vmcnt(8)
	s_waitcnt lgkmcnt(0)
	s_nop 0
	s_barrier
	v_mfma_f32_16x16x32_bf16 v[126:129], v[130:133], v[186:189], 0
	v_mfma_f32_16x16x32_bf16 v[122:125], v[152:155], v[186:189], 0
	v_mfma_f32_16x16x32_bf16 v[110:113], v[130:133], v[194:197], 0
	v_mfma_f32_16x16x32_bf16 v[106:109], v[152:155], v[194:197], 0
	v_mfma_f32_16x16x32_bf16 v[94:97], v[130:133], v[202:205], 0
	v_mfma_f32_16x16x32_bf16 v[90:93], v[152:155], v[202:205], 0
	v_mfma_f32_16x16x32_bf16 v[78:81], v[130:133], v[210:213], 0
	v_mfma_f32_16x16x32_bf16 v[74:77], v[152:155], v[210:213], 0
	v_mfma_f32_16x16x32_bf16 v[126:129], v[134:137], v[190:193], v[126:129]
	v_mfma_f32_16x16x32_bf16 v[122:125], v[156:159], v[190:193], v[122:125]
	v_mfma_f32_16x16x32_bf16 v[110:113], v[134:137], v[198:201], v[110:113]
	v_mfma_f32_16x16x32_bf16 v[106:109], v[156:159], v[198:201], v[106:109]
	v_mfma_f32_16x16x32_bf16 v[94:97], v[134:137], v[206:209], v[94:97]
	v_mfma_f32_16x16x32_bf16 v[90:93], v[156:159], v[206:209], v[90:93]
	v_mfma_f32_16x16x32_bf16 v[78:81], v[134:137], v[214:217], v[78:81]
	v_mfma_f32_16x16x32_bf16 v[74:77], v[156:159], v[214:217], v[74:77]
	v_mfma_f32_16x16x32_bf16 v[118:121], v[160:163], v[186:189], 0
	v_mfma_f32_16x16x32_bf16 v[114:117], v[178:181], v[186:189], 0
	v_mfma_f32_16x16x32_bf16 v[102:105], v[160:163], v[194:197], 0
	v_mfma_f32_16x16x32_bf16 v[98:101], v[178:181], v[194:197], 0
	v_mfma_f32_16x16x32_bf16 v[86:89], v[160:163], v[202:205], 0
	v_mfma_f32_16x16x32_bf16 v[82:85], v[178:181], v[202:205], 0
	v_mfma_f32_16x16x32_bf16 v[70:73], v[160:163], v[210:213], 0
	v_mfma_f32_16x16x32_bf16 v[66:69], v[178:181], v[210:213], 0
	v_mfma_f32_16x16x32_bf16 v[118:121], v[174:177], v[190:193], v[118:121]
	v_mfma_f32_16x16x32_bf16 v[114:117], v[182:185], v[190:193], v[114:117]
	v_mfma_f32_16x16x32_bf16 v[102:105], v[174:177], v[198:201], v[102:105]
	v_mfma_f32_16x16x32_bf16 v[98:101], v[182:185], v[198:201], v[98:101]
	v_mfma_f32_16x16x32_bf16 v[86:89], v[174:177], v[206:209], v[86:89]
	v_mfma_f32_16x16x32_bf16 v[82:85], v[182:185], v[206:209], v[82:85]
	v_mfma_f32_16x16x32_bf16 v[70:73], v[174:177], v[214:217], v[70:73]
	v_mfma_f32_16x16x32_bf16 v[66:69], v[182:185], v[214:217], v[66:69]
	s_barrier
	s_add_i32 s18, s18, s42
	v_lshl_add_u64 v[164:165], s[10:11], 0, v[142:143]
	s_mov_b32 m0, s18
	ds_read_b128 v[186:189], v172 offset:16384
	ds_read_b128 v[190:193], v172 offset:17408
	ds_read_b128 v[194:197], v172 offset:18432
	ds_read_b128 v[198:201], v172 offset:19456
	ds_read_b128 v[202:205], v172 offset:20480
	ds_read_b128 v[206:209], v172 offset:21504
	ds_read_b128 v[210:213], v172 offset:22528
	ds_read_b128 v[214:217], v172 offset:23552
	global_load_lds_dwordx4 v[164:165], off
	s_add_i32 m0, s18, 0x2000
	s_add_u32 s18, s10, 0x100000
	v_lshl_add_u64 v[218:219], s[10:11], 0, v[138:139]
	s_addc_u32 s19, s11, 0
	s_add_i32 s20, s20, s42
	global_load_lds_dwordx4 v[218:219], off
	v_lshl_add_u64 v[220:221], s[18:19], 0, v[142:143]
	s_mov_b32 m0, s20
	v_lshl_add_u64 v[222:223], s[14:15], 0, v[140:141]
	global_load_lds_dwordx4 v[220:221], off
	v_lshl_add_u64 v[220:221], s[18:19], 0, v[138:139]
	s_add_i32 m0, s20, 0x2000
	s_nop 0
	global_load_lds_dwordx4 v[220:221], off
	v_lshl_add_u64 v[220:221], s[14:15], 0, v[144:145]
	s_mov_b32 m0, s51
	s_nop 0
	global_load_lds_dwordx4 v[220:221], off
	s_mov_b32 m0, s68
	s_nop 0
	global_load_lds_dwordx4 v[222:223], off
	s_waitcnt vmcnt(8)
	s_waitcnt lgkmcnt(0)
	s_barrier
; #define PG8_STAGEA(bufoff, gbase, voff) PG8_STAGE_X(bufoff, gbase, voff, AUXA)
; #define PG8_LDA(dst, b, h) do { _Pragma("unroll") for (int m = 0; m < 4; ++m) _Pragma("unroll") for (int k = 0; k < 2; ++k) dst[m][k] = *(const PG8_LAS bf16x8*)(lds + PG8_SA(b, h) + aoff + m * 2048 + k * 1024); } while (0)
; #define PG8_LDB(dst, b, h) do { _Pragma("unroll") for (int n = 0; n < 2; ++n) _Pragma("unroll") for (int k = 0; k < 2; ++k) dst[n][k] = *(const PG8_LAS bf16x8*)(lds + PG8_SB(b, h) + boff + n * 2048 + k * 1024); } while (0)
; #define PG8_MMA(ai, bj, At, Bt) do { if (GEMM_PRIO_MODE == 0) __builtin_amdgcn_s_setprio(1); PG8_MMA_LOOPS \
;         acc[ai][bj][m][n] = __builtin_amdgcn_mfma_f32_16x16x32_bf16(Bt[n][k], At[m][k], acc[ai][bj][m][n], 0, 0, 0); if (GEMM_PRIO_MODE == 0) __builtin_amdgcn_s_setprio(0); } while (0)
; #define PG8_WAIT_V(n) asm volatile("s_waitcnt vmcnt(" #n ")" ::: "memory")
; #define PG8_WAIT_L(n) asm volatile("s_waitcnt lgkmcnt(" #n ")" ::: "memory")
; #define PG8_BAR __builtin_amdgcn_s_barrier()
; #define PG8_SCHED __builtin_amdgcn_sched_barrier(0)
;     ...
;             PG8_WAIT_V(8); PG8_WAIT_L(0); PG8_BAR; PG8_MMA(1, 0, At, B0); PG8_MMA(1, 1, At, B1); PG8_BAR; PG8_SCHED;
;     ...
;             PG8_LDB(B0, 1, 0); PG8_LDB(B1, 1, 1); PG8_SCHED; PG8_LDA(At, 1, 0); PG8_STAGEA(PG8_SA(0, 1), a2 + hstepA, voffA);
;             PG8_WAIT_V(8); PG8_WAIT_L(0); PG8_BAR; PG8_MMA(0, 0, At, B0); PG8_MMA(0, 1, At, B1); PG8_BAR; PG8_SCHED;
	v_mfma_f32_16x16x32_bf16 v[62:65], v[130:133], v[186:189], 0
	v_mfma_f32_16x16x32_bf16 v[58:61], v[152:155], v[186:189], 0
	v_mfma_f32_16x16x32_bf16 v[46:49], v[130:133], v[194:197], 0
	v_mfma_f32_16x16x32_bf16 v[42:45], v[152:155], v[194:197], 0
	v_mfma_f32_16x16x32_bf16 v[30:33], v[130:133], v[202:205], 0
	v_mfma_f32_16x16x32_bf16 v[26:29], v[152:155], v[202:205], 0
	v_mfma_f32_16x16x32_bf16 v[12:15], v[130:133], v[210:213], 0
	v_mfma_f32_16x16x32_bf16 v[8:11], v[152:155], v[210:213], 0
	v_mfma_f32_16x16x32_bf16 v[62:65], v[134:137], v[190:193], v[62:65]
	v_mfma_f32_16x16x32_bf16 v[58:61], v[156:159], v[190:193], v[58:61]
	v_mfma_f32_16x16x32_bf16 v[46:49], v[134:137], v[198:201], v[46:49]
	v_mfma_f32_16x16x32_bf16 v[42:45], v[156:159], v[198:201], v[42:45]
	v_mfma_f32_16x16x32_bf16 v[30:33], v[134:137], v[206:209], v[30:33]
	v_mfma_f32_16x16x32_bf16 v[26:29], v[156:159], v[206:209], v[26:29]
	v_mfma_f32_16x16x32_bf16 v[12:15], v[134:137], v[214:217], v[12:15]
	v_mfma_f32_16x16x32_bf16 v[8:11], v[156:159], v[214:217], v[8:11]
	v_mfma_f32_16x16x32_bf16 v[54:57], v[160:163], v[186:189], 0
	v_mfma_f32_16x16x32_bf16 v[50:53], v[178:181], v[186:189], 0
	v_mfma_f32_16x16x32_bf16 v[38:41], v[160:163], v[194:197], 0
	v_mfma_f32_16x16x32_bf16 v[34:37], v[178:181], v[194:197], 0
	v_mfma_f32_16x16x32_bf16 v[22:25], v[160:163], v[202:205], 0
	v_mfma_f32_16x16x32_bf16 v[18:21], v[178:181], v[202:205], 0
	v_mfma_f32_16x16x32_bf16 v[4:7], v[160:163], v[210:213], 0
	v_mfma_f32_16x16x32_bf16 v[0:3], v[178:181], v[210:213], 0
	v_mfma_f32_16x16x32_bf16 v[54:57], v[174:177], v[190:193], v[54:57]
	v_mfma_f32_16x16x32_bf16 v[50:53], v[182:185], v[190:193], v[50:53]
	v_mfma_f32_16x16x32_bf16 v[38:41], v[174:177], v[198:201], v[38:41]
	v_mfma_f32_16x16x32_bf16 v[34:37], v[182:185], v[198:201], v[34:37]
	v_mfma_f32_16x16x32_bf16 v[22:25], v[174:177], v[206:209], v[22:25]
	v_mfma_f32_16x16x32_bf16 v[18:21], v[182:185], v[206:209], v[18:21]
	v_mfma_f32_16x16x32_bf16 v[4:7], v[174:177], v[214:217], v[4:7]
	v_mfma_f32_16x16x32_bf16 v[0:3], v[182:185], v[214:217], v[0:3]
	s_barrier
	s_add_i32 s18, 0, 0x18000
	v_add_u32_e32 v16, s18, v167
	s_add_i32 s19, 0, 0x1c000
	ds_read_b128 v[130:133], v16
	ds_read_b128 v[134:137], v16 offset:1024
	ds_read_b128 v[152:155], v16 offset:2048
	ds_read_b128 v[156:159], v16 offset:3072
	v_add_u32_e32 v16, s19, v167
	ds_read_b128 v[160:163], v16
	ds_read_b128 v[174:177], v16 offset:1024
	ds_read_b128 v[178:181], v16 offset:2048
	ds_read_b128 v[182:185], v16 offset:3072
	s_add_u32 s14, s14, 0x100000
	s_addc_u32 s15, s15, 0
	s_mov_b32 m0, s69
	v_lshl_add_u64 v[224:225], s[14:15], 0, v[144:145]
	ds_read_b128 v[186:189], v172 offset:32768
	ds_read_b128 v[190:193], v172 offset:33792
	ds_read_b128 v[194:197], v172 offset:34816
	ds_read_b128 v[198:201], v172 offset:35840
	ds_read_b128 v[202:205], v172 offset:36864
	ds_read_b128 v[206:209], v172 offset:37888
	ds_read_b128 v[210:213], v172 offset:38912
	ds_read_b128 v[214:217], v172 offset:39936
	global_load_lds_dwordx4 v[224:225], off
	v_lshl_add_u64 v[224:225], s[14:15], 0, v[140:141]
	s_mov_b32 m0, s72
	s_nop 0
	global_load_lds_dwordx4 v[224:225], off
	s_waitcnt vmcnt(8)
	s_waitcnt lgkmcnt(0)
	s_barrier
	v_mfma_f32_16x16x32_bf16 v[126:129], v[130:133], v[186:189], v[126:129]
	v_mfma_f32_16x16x32_bf16 v[122:125], v[152:155], v[186:189], v[122:125]
	v_mfma_f32_16x16x32_bf16 v[110:113], v[130:133], v[194:197], v[110:113]
	v_mfma_f32_16x16x32_bf16 v[106:109], v[152:155], v[194:197], v[106:109]
	v_mfma_f32_16x16x32_bf16 v[94:97], v[130:133], v[202:205], v[94:97]
	v_mfma_f32_16x16x32_bf16 v[90:93], v[152:155], v[202:205], v[90:93]
	v_mfma_f32_16x16x32_bf16 v[78:81], v[130:133], v[210:213], v[78:81]
	v_mfma_f32_16x16x32_bf16 v[74:77], v[152:155], v[210:213], v[74:77]
	v_mfma_f32_16x16x32_bf16 v[126:129], v[134:137], v[190:193], v[126:129]
	v_mfma_f32_16x16x32_bf16 v[122:125], v[156:159], v[190:193], v[122:125]
	v_mfma_f32_16x16x32_bf16 v[110:113], v[134:137], v[198:201], v[110:113]
	v_mfma_f32_16x16x32_bf16 v[106:109], v[156:159], v[198:201], v[106:109]
	v_mfma_f32_16x16x32_bf16 v[94:97], v[134:137], v[206:209], v[94:97]
	v_mfma_f32_16x16x32_bf16 v[90:93], v[156:159], v[206:209], v[90:93]
	v_mfma_f32_16x16x32_bf16 v[78:81], v[134:137], v[214:217], v[78:81]
	v_mfma_f32_16x16x32_bf16 v[74:77], v[156:159], v[214:217], v[74:77]
	v_mfma_f32_16x16x32_bf16 v[118:121], v[160:163], v[186:189], v[118:121]
	v_mfma_f32_16x16x32_bf16 v[114:117], v[178:181], v[186:189], v[114:117]
	v_mfma_f32_16x16x32_bf16 v[102:105], v[160:163], v[194:197], v[102:105]
	v_mfma_f32_16x16x32_bf16 v[98:101], v[178:181], v[194:197], v[98:101]
	v_mfma_f32_16x16x32_bf16 v[86:89], v[160:163], v[202:205], v[86:89]
	v_mfma_f32_16x16x32_bf16 v[82:85], v[178:181], v[202:205], v[82:85]
	v_mfma_f32_16x16x32_bf16 v[70:73], v[160:163], v[210:213], v[70:73]
	v_mfma_f32_16x16x32_bf16 v[66:69], v[178:181], v[210:213], v[66:69]
	v_mfma_f32_16x16x32_bf16 v[118:121], v[174:177], v[190:193], v[118:121]
	v_mfma_f32_16x16x32_bf16 v[114:117], v[182:185], v[190:193], v[114:117]
	v_mfma_f32_16x16x32_bf16 v[102:105], v[174:177], v[198:201], v[102:105]
	v_mfma_f32_16x16x32_bf16 v[98:101], v[182:185], v[198:201], v[98:101]
	v_mfma_f32_16x16x32_bf16 v[86:89], v[174:177], v[206:209], v[86:89]
	v_mfma_f32_16x16x32_bf16 v[82:85], v[182:185], v[206:209], v[82:85]
	v_mfma_f32_16x16x32_bf16 v[70:73], v[174:177], v[214:217], v[70:73]
	v_mfma_f32_16x16x32_bf16 v[66:69], v[182:185], v[214:217], v[66:69]
	s_barrier
; #define PG8_STAGEA(bufoff, gbase, voff) PG8_STAGE_X(bufoff, gbase, voff, AUXA)
; #define PG8_STAGEB(bufoff, gbase, voff) PG8_STAGE_X(bufoff, gbase, voff, AUXB)
; #define PG8_LDA(dst, b, h) do { _Pragma("unroll") for (int m = 0; m < 4; ++m) _Pragma("unroll") for (int k = 0; k < 2; ++k) dst[m][k] = *(const PG8_LAS bf16x8*)(lds + PG8_SA(b, h) + aoff + m * 2048 + k * 1024); } while (0)
; #define PG8_WAIT_V(n) asm volatile("s_waitcnt vmcnt(" #n ")" ::: "memory")
; #define PG8_WAIT_L(n) asm volatile("s_waitcnt lgkmcnt(" #n ")" ::: "memory")
;     ...
;         for (int t = t0; t < nt; t += 2) {
;             const bool last = (t == nt - 2);
;             const char* a1 = cA + (size_t)(t + 1) * kstepA;
;             const char* a2 = last ? nA : cA + (size_t)(t + 2) * kstepA; const char* b2 = last ? nB : cB + (size_t)(t + 2) * kstepB;
;             const char* a3 = a2 + kstepA; const char* b3 = b2 + kstepB;
;             if (last && has_next) S.a_ready(nxt);
;             if constexpr (SP2) {
;             PG8_LDB(B0, 0, 0); PG8_LDB(B1, 0, 1); PG8_SCHED; PG8_LDA(At, 0, 0); PG8_STAGEA(PG8_SA(1, 1), a1 + hstepA, voffA);
;     ...
;             const int relax = __builtin_amdgcn_readfirstlane((t == 0 && ui > 0) ? 1 : 0);
;             PG8_WAIT_VR(8, 24, relax); PG8_WAIT_L(0); PG8_BAR; PG8_MMA(0, 0, At, B0); PG8_MMA(0, 1, At, B1); PG8_BAR; PG8_SCHED;
;     ...
;             PG8_WAIT_V(8); PG8_WAIT_L(0); PG8_BAR; PG8_MMA(0, 0, At, B0); PG8_MMA(0, 1, At, B1); PG8_BAR; PG8_SCHED;
;     ...
;             PG8_LDA(At, 0, 1); PG8_STAGEB(PG8_SB(0, 0), b2, voffB); PG8_STAGEB(PG8_SB(0, 1), b2 + hstepB, voffB); PG8_STAGEA(PG8_SA(0, 0), a2, voffA);
;     ...
;             PG8_WAIT_VR(8, 24, relax); PG8_WAIT_L(0); PG8_BAR; PG8_MMA(1, 0, At, B0); PG8_MMA(1, 1, At, B1); PG8_BAR; PG8_SCHED;
;     ...
;             PG8_WAIT_V(8); PG8_WAIT_L(0); PG8_BAR; PG8_MMA(1, 0, At, B0); PG8_MMA(1, 1, At, B1); PG8_BAR; PG8_SCHED;
;     ...
;             PG8_LDB(B0, 1, 0); PG8_LDB(B1, 1, 1); PG8_SCHED; PG8_LDA(At, 1, 0); PG8_STAGEA(PG8_SA(0, 1), a2 + hstepA, voffA);
;             PG8_WAIT_V(8); PG8_WAIT_L(0); PG8_BAR; PG8_MMA(0, 0, At, B0); PG8_MMA(0, 1, At, B1); PG8_BAR; PG8_SCHED;
;             PG8_LDA(At, 1, 1); PG8_STAGEB(PG8_SB(1, 0), b3, voffB); PG8_STAGEB(PG8_SB(1, 1), b3 + hstepB, voffB); PG8_STAGEA(PG8_SA(1, 0), a3, voffA);
;             PG8_WAIT_V(8); PG8_WAIT_L(0); PG8_BAR; PG8_MMA(1, 0, At, B0); PG8_MMA(1, 1, At, B1); PG8_BAR; PG8_SCHED;
	s_add_i32 s14, s18, s42
	v_lshl_add_u64 v[164:165], v[164:165], 0, s[86:87]
	s_mov_b32 m0, s14
	ds_read_b128 v[186:189], v172 offset:49152
	ds_read_b128 v[190:193], v172 offset:50176
	ds_read_b128 v[194:197], v172 offset:51200
	ds_read_b128 v[198:201], v172 offset:52224
	ds_read_b128 v[202:205], v172 offset:53248
	ds_read_b128 v[206:209], v172 offset:54272
	ds_read_b128 v[210:213], v172 offset:55296
	ds_read_b128 v[214:217], v172 offset:56320
	global_load_lds_dwordx4 v[164:165], off
	s_add_i32 m0, s14, 0x2000
	s_add_u32 s10, s10, 0x100080
	v_lshl_add_u64 v[164:165], v[218:219], 0, s[86:87]
	s_addc_u32 s11, s11, 0
	s_add_i32 s14, s19, s42
	global_load_lds_dwordx4 v[164:165], off
	v_lshl_add_u64 v[164:165], s[10:11], 0, v[142:143]
	s_mov_b32 m0, s14
	s_nop 0
	global_load_lds_dwordx4 v[164:165], off
	v_lshl_add_u64 v[164:165], s[10:11], 0, v[138:139]
	s_add_i32 m0, s14, 0x2000
	s_nop 0
	global_load_lds_dwordx4 v[164:165], off
	v_lshl_add_u64 v[164:165], v[220:221], 0, s[86:87]
	s_mov_b32 m0, s73
	s_nop 0
	global_load_lds_dwordx4 v[164:165], off
	v_lshl_add_u64 v[164:165], v[222:223], 0, s[86:87]
	s_mov_b32 m0, s82
	s_nop 0
	global_load_lds_dwordx4 v[164:165], off
	s_waitcnt vmcnt(8)
	s_waitcnt lgkmcnt(0)
	s_nop 0
	s_barrier
	v_mfma_f32_16x16x32_bf16 v[62:65], v[130:133], v[186:189], v[62:65]
	v_mfma_f32_16x16x32_bf16 v[58:61], v[152:155], v[186:189], v[58:61]
	v_mfma_f32_16x16x32_bf16 v[46:49], v[130:133], v[194:197], v[46:49]
	v_mfma_f32_16x16x32_bf16 v[42:45], v[152:155], v[194:197], v[42:45]
	v_mfma_f32_16x16x32_bf16 v[30:33], v[130:133], v[202:205], v[30:33]
	v_mfma_f32_16x16x32_bf16 v[26:29], v[152:155], v[202:205], v[26:29]
	v_mfma_f32_16x16x32_bf16 v[12:15], v[130:133], v[210:213], v[12:15]
	v_mfma_f32_16x16x32_bf16 v[8:11], v[152:155], v[210:213], v[8:11]
	v_mfma_f32_16x16x32_bf16 v[62:65], v[134:137], v[190:193], v[62:65]
	v_mfma_f32_16x16x32_bf16 v[58:61], v[156:159], v[190:193], v[58:61]
	v_mfma_f32_16x16x32_bf16 v[46:49], v[134:137], v[198:201], v[46:49]
	v_mfma_f32_16x16x32_bf16 v[42:45], v[156:159], v[198:201], v[42:45]
	v_mfma_f32_16x16x32_bf16 v[30:33], v[134:137], v[206:209], v[30:33]
	v_mfma_f32_16x16x32_bf16 v[26:29], v[156:159], v[206:209], v[26:29]
	v_mfma_f32_16x16x32_bf16 v[12:15], v[134:137], v[214:217], v[12:15]
	v_mfma_f32_16x16x32_bf16 v[8:11], v[156:159], v[214:217], v[8:11]
	v_mfma_f32_16x16x32_bf16 v[54:57], v[160:163], v[186:189], v[54:57]
	v_mfma_f32_16x16x32_bf16 v[50:53], v[178:181], v[186:189], v[50:53]
	v_mfma_f32_16x16x32_bf16 v[38:41], v[160:163], v[194:197], v[38:41]
	v_mfma_f32_16x16x32_bf16 v[34:37], v[178:181], v[194:197], v[34:37]
	v_mfma_f32_16x16x32_bf16 v[22:25], v[160:163], v[202:205], v[22:25]
	v_mfma_f32_16x16x32_bf16 v[18:21], v[178:181], v[202:205], v[18:21]
	v_mfma_f32_16x16x32_bf16 v[4:7], v[160:163], v[210:213], v[4:7]
	v_mfma_f32_16x16x32_bf16 v[0:3], v[178:181], v[210:213], v[0:3]
	v_mfma_f32_16x16x32_bf16 v[54:57], v[174:177], v[190:193], v[54:57]
	v_mfma_f32_16x16x32_bf16 v[50:53], v[182:185], v[190:193], v[50:53]
	v_mfma_f32_16x16x32_bf16 v[38:41], v[174:177], v[198:201], v[38:41]
	v_mfma_f32_16x16x32_bf16 v[34:37], v[182:185], v[198:201], v[34:37]
	v_mfma_f32_16x16x32_bf16 v[22:25], v[174:177], v[206:209], v[22:25]
	v_mfma_f32_16x16x32_bf16 v[18:21], v[182:185], v[206:209], v[18:21]
	v_mfma_f32_16x16x32_bf16 v[4:7], v[174:177], v[214:217], v[4:7]
	v_mfma_f32_16x16x32_bf16 v[0:3], v[182:185], v[214:217], v[0:3]
	s_barrier
	s_add_i32 s27, s27, 2
	s_add_u32 s8, s8, 0x100
	s_addc_u32 s9, s9, 0
	s_add_u32 s0, s0, 0x100
	s_addc_u32 s1, s1, 0
	v_add_u32_e32 v226, 0x10000, v167
.LBB0_129:
	s_add_u32 s10, s8, 0xfff00080
	s_addc_u32 s11, s9, -1
	s_add_i32 s18, 0, 0x10000
	s_cmp_eq_u32 s27, 60
	s_cselect_b32 s15, s4, s11
	s_cselect_b32 s14, s5, s10
	s_cselect_b32 s11, s16, s1
	s_cselect_b32 s10, s17, s0
	s_add_i32 s20, 0, 0x14000
	s_waitcnt lgkmcnt(0)
	ds_read_b128 v[130:133], v226
	ds_read_b128 v[134:137], v226 offset:1024
	ds_read_b128 v[152:155], v226 offset:2048
	ds_read_b128 v[156:159], v226 offset:3072
	ds_read_b128 v[160:163], v226 offset:16384
	ds_read_b128 v[174:177], v226 offset:17408
	ds_read_b128 v[178:181], v226 offset:18432
	ds_read_b128 v[182:185], v226 offset:19456
	s_add_i32 m0, s51, 0xc000
	ds_read_b128 v[186:189], v172
	ds_read_b128 v[190:193], v172 offset:1024
	ds_read_b128 v[194:197], v172 offset:2048
	ds_read_b128 v[198:201], v172 offset:3072
	ds_read_b128 v[202:205], v172 offset:4096
	ds_read_b128 v[206:209], v172 offset:5120
	ds_read_b128 v[210:213], v172 offset:6144
	ds_read_b128 v[214:217], v172 offset:7168
	global_load_lds_dwordx4 v148, s[8:9]
	s_add_i32 m0, s51, 0xe000
	s_nop 0
	global_load_lds_dwordx4 v150, s[8:9]
	s_waitcnt vmcnt(8)
	s_waitcnt lgkmcnt(0)
	s_nop 0
	s_barrier
; #define PG8_STAGEA(bufoff, gbase, voff) PG8_STAGE_X(bufoff, gbase, voff, AUXA)
; #define PG8_STAGEB(bufoff, gbase, voff) PG8_STAGE_X(bufoff, gbase, voff, AUXB)
; #define PG8_LDA(dst, b, h) do { _Pragma("unroll") for (int m = 0; m < 4; ++m) _Pragma("unroll") for (int k = 0; k < 2; ++k) dst[m][k] = *(const PG8_LAS bf16x8*)(lds + PG8_SA(b, h) + aoff + m * 2048 + k * 1024); } while (0)
; #define PG8_LDB(dst, b, h) do { _Pragma("unroll") for (int n = 0; n < 2; ++n) _Pragma("unroll") for (int k = 0; k < 2; ++k) dst[n][k] = *(const PG8_LAS bf16x8*)(lds + PG8_SB(b, h) + boff + n * 2048 + k * 1024); } while (0)
; #define PG8_MMA(ai, bj, At, Bt) do { if (GEMM_PRIO_MODE == 0) __builtin_amdgcn_s_setprio(1); PG8_MMA_LOOPS \
;         acc[ai][bj][m][n] = __builtin_amdgcn_mfma_f32_16x16x32_bf16(Bt[n][k], At[m][k], acc[ai][bj][m][n], 0, 0, 0); if (GEMM_PRIO_MODE == 0) __builtin_amdgcn_s_setprio(0); } while (0)
; #define PG8_WAIT_V(n) asm volatile("s_waitcnt vmcnt(" #n ")" ::: "memory")
; #define PG8_WAIT_VR(n, nr, flag) asm volatile("s_cmp_eq_u32 %0, 0\n\ts_cbranch_scc1 .Lpg8s%=\n\ts_waitcnt vmcnt(" #nr ")\n\ts_branch .Lpg8d%=\n.Lpg8s%=:\n\ts_waitcnt vmcnt(" #n ")\n.Lpg8d%=:" :: "s"(flag) : "memory", "scc")
; #define PG8_WAIT_L(n) asm volatile("s_waitcnt lgkmcnt(" #n ")" ::: "memory")
; #define PG8_BAR __builtin_amdgcn_s_barrier()
; #define PG8_SCHED __builtin_amdgcn_sched_barrier(0)
;     ...
;             PG8_LDB(B0, 0, 0); PG8_LDB(B1, 0, 1); PG8_SCHED; PG8_LDA(At, 0, 0); PG8_STAGEA(PG8_SA(1, 1), a1 + hstepA, voffA);
;     ...
;             const int relax = __builtin_amdgcn_readfirstlane((t == 0 && ui > 0) ? 1 : 0);
;             PG8_WAIT_VR(8, 24, relax); PG8_WAIT_L(0); PG8_BAR; PG8_MMA(0, 0, At, B0); PG8_MMA(0, 1, At, B1); PG8_BAR; PG8_SCHED;
;     ...
;             PG8_WAIT_V(8); PG8_WAIT_L(0); PG8_BAR; PG8_MMA(0, 0, At, B0); PG8_MMA(0, 1, At, B1); PG8_BAR; PG8_SCHED;
;     ...
;             PG8_LDA(At, 0, 1); PG8_STAGEB(PG8_SB(0, 0), b2, voffB); PG8_STAGEB(PG8_SB(0, 1), b2 + hstepB, voffB); PG8_STAGEA(PG8_SA(0, 0), a2, voffA);
;     ...
;             PG8_WAIT_VR(8, 24, relax); PG8_WAIT_L(0); PG8_BAR; PG8_MMA(1, 0, At, B0); PG8_MMA(1, 1, At, B1); PG8_BAR; PG8_SCHED;
;     ...
;             PG8_WAIT_V(8); PG8_WAIT_L(0); PG8_BAR; PG8_MMA(1, 0, At, B0); PG8_MMA(1, 1, At, B1); PG8_BAR; PG8_SCHED;
	v_mfma_f32_16x16x32_bf16 v[126:129], v[130:133], v[186:189], v[126:129]
	v_mfma_f32_16x16x32_bf16 v[122:125], v[152:155], v[186:189], v[122:125]
	v_mfma_f32_16x16x32_bf16 v[110:113], v[130:133], v[194:197], v[110:113]
	v_mfma_f32_16x16x32_bf16 v[106:109], v[152:155], v[194:197], v[106:109]
	v_mfma_f32_16x16x32_bf16 v[94:97], v[130:133], v[202:205], v[94:97]
	v_mfma_f32_16x16x32_bf16 v[90:93], v[152:155], v[202:205], v[90:93]
	v_mfma_f32_16x16x32_bf16 v[78:81], v[130:133], v[210:213], v[78:81]
	v_mfma_f32_16x16x32_bf16 v[74:77], v[152:155], v[210:213], v[74:77]
	v_mfma_f32_16x16x32_bf16 v[126:129], v[134:137], v[190:193], v[126:129]
	v_mfma_f32_16x16x32_bf16 v[122:125], v[156:159], v[190:193], v[122:125]
	v_mfma_f32_16x16x32_bf16 v[110:113], v[134:137], v[198:201], v[110:113]
	v_mfma_f32_16x16x32_bf16 v[106:109], v[156:159], v[198:201], v[106:109]
	v_mfma_f32_16x16x32_bf16 v[94:97], v[134:137], v[206:209], v[94:97]
	v_mfma_f32_16x16x32_bf16 v[90:93], v[156:159], v[206:209], v[90:93]
	v_mfma_f32_16x16x32_bf16 v[78:81], v[134:137], v[214:217], v[78:81]
	v_mfma_f32_16x16x32_bf16 v[74:77], v[156:159], v[214:217], v[74:77]
	v_mfma_f32_16x16x32_bf16 v[118:121], v[160:163], v[186:189], v[118:121]
	v_mfma_f32_16x16x32_bf16 v[114:117], v[178:181], v[186:189], v[114:117]
	v_mfma_f32_16x16x32_bf16 v[102:105], v[160:163], v[194:197], v[102:105]
	v_mfma_f32_16x16x32_bf16 v[98:101], v[178:181], v[194:197], v[98:101]
	v_mfma_f32_16x16x32_bf16 v[86:89], v[160:163], v[202:205], v[86:89]
	v_mfma_f32_16x16x32_bf16 v[82:85], v[178:181], v[202:205], v[82:85]
	v_mfma_f32_16x16x32_bf16 v[70:73], v[160:163], v[210:213], v[70:73]
	v_mfma_f32_16x16x32_bf16 v[66:69], v[178:181], v[210:213], v[66:69]
	v_mfma_f32_16x16x32_bf16 v[118:121], v[174:177], v[190:193], v[118:121]
	v_mfma_f32_16x16x32_bf16 v[114:117], v[182:185], v[190:193], v[114:117]
	v_mfma_f32_16x16x32_bf16 v[102:105], v[174:177], v[198:201], v[102:105]
	v_mfma_f32_16x16x32_bf16 v[98:101], v[182:185], v[198:201], v[98:101]
	v_mfma_f32_16x16x32_bf16 v[86:89], v[174:177], v[206:209], v[86:89]
	v_mfma_f32_16x16x32_bf16 v[82:85], v[182:185], v[206:209], v[82:85]
	v_mfma_f32_16x16x32_bf16 v[70:73], v[174:177], v[214:217], v[70:73]
	v_mfma_f32_16x16x32_bf16 v[66:69], v[182:185], v[214:217], v[66:69]
	s_barrier
	s_add_i32 s18, s18, s42
	s_mov_b32 m0, s18
	ds_read_b128 v[186:189], v172 offset:16384
	ds_read_b128 v[190:193], v172 offset:17408
	ds_read_b128 v[194:197], v172 offset:18432
	ds_read_b128 v[198:201], v172 offset:19456
	ds_read_b128 v[202:205], v172 offset:20480
	ds_read_b128 v[206:209], v172 offset:21504
	ds_read_b128 v[210:213], v172 offset:22528
	ds_read_b128 v[214:217], v172 offset:23552
	s_add_u32 s100, s14, 0x80
	s_addc_u32 s101, s15, 0
	global_load_lds_dwordx4 v142, s[10:11]
	s_add_i32 m0, s18, 0x2000
	s_add_u32 s18, s10, 0x100000
	s_addc_u32 s19, s11, 0
	s_add_i32 s20, s20, s42
	global_load_lds_dwordx4 v138, s[10:11]
	s_mov_b32 m0, s20
	s_nop 0
	global_load_lds_dwordx4 v142, s[18:19]
	s_add_i32 m0, s20, 0x2000
	s_nop 0
	global_load_lds_dwordx4 v138, s[18:19]
	s_mov_b32 m0, s51
	s_nop 0
	global_load_lds_dwordx4 v144, s[14:15]
	s_mov_b32 m0, s68
	s_nop 0
	global_load_lds_dwordx4 v140, s[14:15]
	s_waitcnt vmcnt(8)
	s_waitcnt lgkmcnt(0)
	s_barrier
	v_mfma_f32_16x16x32_bf16 v[62:65], v[130:133], v[186:189], v[62:65]
	v_mfma_f32_16x16x32_bf16 v[58:61], v[152:155], v[186:189], v[58:61]
	v_mfma_f32_16x16x32_bf16 v[46:49], v[130:133], v[194:197], v[46:49]
	v_mfma_f32_16x16x32_bf16 v[42:45], v[152:155], v[194:197], v[42:45]
	v_mfma_f32_16x16x32_bf16 v[30:33], v[130:133], v[202:205], v[30:33]
	v_mfma_f32_16x16x32_bf16 v[26:29], v[152:155], v[202:205], v[26:29]
	v_mfma_f32_16x16x32_bf16 v[12:15], v[130:133], v[210:213], v[12:15]
	v_mfma_f32_16x16x32_bf16 v[8:11], v[152:155], v[210:213], v[8:11]
	v_mfma_f32_16x16x32_bf16 v[62:65], v[134:137], v[190:193], v[62:65]
	v_mfma_f32_16x16x32_bf16 v[58:61], v[156:159], v[190:193], v[58:61]
	v_mfma_f32_16x16x32_bf16 v[46:49], v[134:137], v[198:201], v[46:49]
	v_mfma_f32_16x16x32_bf16 v[42:45], v[156:159], v[198:201], v[42:45]
	v_mfma_f32_16x16x32_bf16 v[30:33], v[134:137], v[206:209], v[30:33]
	v_mfma_f32_16x16x32_bf16 v[26:29], v[156:159], v[206:209], v[26:29]
	v_mfma_f32_16x16x32_bf16 v[12:15], v[134:137], v[214:217], v[12:15]
	v_mfma_f32_16x16x32_bf16 v[8:11], v[156:159], v[214:217], v[8:11]
	v_mfma_f32_16x16x32_bf16 v[54:57], v[160:163], v[186:189], v[54:57]
	v_mfma_f32_16x16x32_bf16 v[50:53], v[178:181], v[186:189], v[50:53]
	v_mfma_f32_16x16x32_bf16 v[38:41], v[160:163], v[194:197], v[38:41]
	v_mfma_f32_16x16x32_bf16 v[34:37], v[178:181], v[194:197], v[34:37]
	v_mfma_f32_16x16x32_bf16 v[22:25], v[160:163], v[202:205], v[22:25]
	v_mfma_f32_16x16x32_bf16 v[18:21], v[178:181], v[202:205], v[18:21]
	v_mfma_f32_16x16x32_bf16 v[4:7], v[160:163], v[210:213], v[4:7]
	v_mfma_f32_16x16x32_bf16 v[0:3], v[178:181], v[210:213], v[0:3]
	v_mfma_f32_16x16x32_bf16 v[54:57], v[174:177], v[190:193], v[54:57]
	v_mfma_f32_16x16x32_bf16 v[50:53], v[182:185], v[190:193], v[50:53]
	v_mfma_f32_16x16x32_bf16 v[38:41], v[174:177], v[198:201], v[38:41]
	v_mfma_f32_16x16x32_bf16 v[34:37], v[182:185], v[198:201], v[34:37]
	v_mfma_f32_16x16x32_bf16 v[22:25], v[174:177], v[206:209], v[22:25]
	v_mfma_f32_16x16x32_bf16 v[18:21], v[182:185], v[206:209], v[18:21]
	v_mfma_f32_16x16x32_bf16 v[4:7], v[174:177], v[214:217], v[4:7]
	v_mfma_f32_16x16x32_bf16 v[0:3], v[182:185], v[214:217], v[0:3]
	s_barrier
; #define PG8_STAGEA(bufoff, gbase, voff) PG8_STAGE_X(bufoff, gbase, voff, AUXA)
; #define PG8_STAGEB(bufoff, gbase, voff) PG8_STAGE_X(bufoff, gbase, voff, AUXB)
; #define PG8_LDA(dst, b, h) do { _Pragma("unroll") for (int m = 0; m < 4; ++m) _Pragma("unroll") for (int k = 0; k < 2; ++k) dst[m][k] = *(const PG8_LAS bf16x8*)(lds + PG8_SA(b, h) + aoff + m * 2048 + k * 1024); } while (0)
; #define PG8_LDB(dst, b, h) do { _Pragma("unroll") for (int n = 0; n < 2; ++n) _Pragma("unroll") for (int k = 0; k < 2; ++k) dst[n][k] = *(const PG8_LAS bf16x8*)(lds + PG8_SB(b, h) + boff + n * 2048 + k * 1024); } while (0)
; #define PG8_MMA(ai, bj, At, Bt) do { if (GEMM_PRIO_MODE == 0) __builtin_amdgcn_s_setprio(1); PG8_MMA_LOOPS \
;         acc[ai][bj][m][n] = __builtin_amdgcn_mfma_f32_16x16x32_bf16(Bt[n][k], At[m][k], acc[ai][bj][m][n], 0, 0, 0); if (GEMM_PRIO_MODE == 0) __builtin_amdgcn_s_setprio(0); } while (0)
; #define PG8_WAIT_V(n) asm volatile("s_waitcnt vmcnt(" #n ")" ::: "memory")
; #define PG8_WAIT_L(n) asm volatile("s_waitcnt lgkmcnt(" #n ")" ::: "memory")
; #define PG8_BAR __builtin_amdgcn_s_barrier()
; #define PG8_SCHED __builtin_amdgcn_sched_barrier(0)
;     ...
;             PG8_LDB(B0, 1, 0); PG8_LDB(B1, 1, 1); PG8_SCHED; PG8_LDA(At, 1, 0); PG8_STAGEA(PG8_SA(0, 1), a2 + hstepA, voffA);
;             PG8_WAIT_V(8); PG8_WAIT_L(0); PG8_BAR; PG8_MMA(0, 0, At, B0); PG8_MMA(0, 1, At, B1); PG8_BAR; PG8_SCHED;
;             PG8_LDA(At, 1, 1); PG8_STAGEB(PG8_SB(1, 0), b3, voffB); PG8_STAGEB(PG8_SB(1, 1), b3 + hstepB, voffB); PG8_STAGEA(PG8_SA(1, 0), a3, voffA);
;             PG8_WAIT_V(8); PG8_WAIT_L(0); PG8_BAR; PG8_MMA(1, 0, At, B0); PG8_MMA(1, 1, At, B1); PG8_BAR; PG8_SCHED;
	s_add_i32 s18, 0, 0x18000
	s_add_i32 s19, 0, 0x1c000
	ds_read_b128 v[130:133], v226 offset:32768
	ds_read_b128 v[134:137], v226 offset:33792
	ds_read_b128 v[152:155], v226 offset:34816
	ds_read_b128 v[156:159], v226 offset:35840
	ds_read_b128 v[160:163], v226 offset:49152
	ds_read_b128 v[174:177], v226 offset:50176
	ds_read_b128 v[178:181], v226 offset:51200
	ds_read_b128 v[182:185], v226 offset:52224
	s_add_u32 s14, s14, 0x100000
	s_addc_u32 s15, s15, 0
	s_mov_b32 m0, s69
	ds_read_b128 v[186:189], v172 offset:32768
	ds_read_b128 v[190:193], v172 offset:33792
	ds_read_b128 v[194:197], v172 offset:34816
	ds_read_b128 v[198:201], v172 offset:35840
	ds_read_b128 v[202:205], v172 offset:36864
	ds_read_b128 v[206:209], v172 offset:37888
	ds_read_b128 v[210:213], v172 offset:38912
	ds_read_b128 v[214:217], v172 offset:39936
	global_load_lds_dwordx4 v144, s[14:15]
	s_mov_b32 m0, s72
	s_nop 0
	global_load_lds_dwordx4 v140, s[14:15]
	s_waitcnt vmcnt(8)
	s_waitcnt lgkmcnt(0)
	s_barrier
	v_mfma_f32_16x16x32_bf16 v[126:129], v[130:133], v[186:189], v[126:129]
	v_mfma_f32_16x16x32_bf16 v[122:125], v[152:155], v[186:189], v[122:125]
	v_mfma_f32_16x16x32_bf16 v[110:113], v[130:133], v[194:197], v[110:113]
	v_mfma_f32_16x16x32_bf16 v[106:109], v[152:155], v[194:197], v[106:109]
	v_mfma_f32_16x16x32_bf16 v[94:97], v[130:133], v[202:205], v[94:97]
	v_mfma_f32_16x16x32_bf16 v[90:93], v[152:155], v[202:205], v[90:93]
	v_mfma_f32_16x16x32_bf16 v[78:81], v[130:133], v[210:213], v[78:81]
	v_mfma_f32_16x16x32_bf16 v[74:77], v[152:155], v[210:213], v[74:77]
	v_mfma_f32_16x16x32_bf16 v[126:129], v[134:137], v[190:193], v[126:129]
	v_mfma_f32_16x16x32_bf16 v[122:125], v[156:159], v[190:193], v[122:125]
	v_mfma_f32_16x16x32_bf16 v[110:113], v[134:137], v[198:201], v[110:113]
	v_mfma_f32_16x16x32_bf16 v[106:109], v[156:159], v[198:201], v[106:109]
	v_mfma_f32_16x16x32_bf16 v[94:97], v[134:137], v[206:209], v[94:97]
	v_mfma_f32_16x16x32_bf16 v[90:93], v[156:159], v[206:209], v[90:93]
	v_mfma_f32_16x16x32_bf16 v[78:81], v[134:137], v[214:217], v[78:81]
	v_mfma_f32_16x16x32_bf16 v[74:77], v[156:159], v[214:217], v[74:77]
	v_mfma_f32_16x16x32_bf16 v[118:121], v[160:163], v[186:189], v[118:121]
	v_mfma_f32_16x16x32_bf16 v[114:117], v[178:181], v[186:189], v[114:117]
	v_mfma_f32_16x16x32_bf16 v[102:105], v[160:163], v[194:197], v[102:105]
	v_mfma_f32_16x16x32_bf16 v[98:101], v[178:181], v[194:197], v[98:101]
	v_mfma_f32_16x16x32_bf16 v[86:89], v[160:163], v[202:205], v[86:89]
	v_mfma_f32_16x16x32_bf16 v[82:85], v[178:181], v[202:205], v[82:85]
	v_mfma_f32_16x16x32_bf16 v[70:73], v[160:163], v[210:213], v[70:73]
	v_mfma_f32_16x16x32_bf16 v[66:69], v[178:181], v[210:213], v[66:69]
	v_mfma_f32_16x16x32_bf16 v[118:121], v[174:177], v[190:193], v[118:121]
	v_mfma_f32_16x16x32_bf16 v[114:117], v[182:185], v[190:193], v[114:117]
	v_mfma_f32_16x16x32_bf16 v[102:105], v[174:177], v[198:201], v[102:105]
	v_mfma_f32_16x16x32_bf16 v[98:101], v[182:185], v[198:201], v[98:101]
	v_mfma_f32_16x16x32_bf16 v[86:89], v[174:177], v[206:209], v[86:89]
	v_mfma_f32_16x16x32_bf16 v[82:85], v[182:185], v[206:209], v[82:85]
	v_mfma_f32_16x16x32_bf16 v[70:73], v[174:177], v[214:217], v[70:73]
	v_mfma_f32_16x16x32_bf16 v[66:69], v[182:185], v[214:217], v[66:69]
	s_barrier
	s_add_i32 s14, s18, s42
	s_mov_b32 m0, s14
	ds_read_b128 v[186:189], v172 offset:49152
	ds_read_b128 v[190:193], v172 offset:50176
	ds_read_b128 v[194:197], v172 offset:51200
	ds_read_b128 v[198:201], v172 offset:52224
	ds_read_b128 v[202:205], v172 offset:53248
	ds_read_b128 v[206:209], v172 offset:54272
	ds_read_b128 v[210:213], v172 offset:55296
	ds_read_b128 v[214:217], v172 offset:56320
	s_add_u32 vcc_lo, s10, 0x80
	s_addc_u32 vcc_hi, s11, 0
	global_load_lds_dwordx4 v142, vcc
	s_add_i32 m0, s14, 0x2000
	s_add_u32 s10, s10, 0x100080
	s_addc_u32 s11, s11, 0
	s_add_i32 s14, s19, s42
	global_load_lds_dwordx4 v138, vcc
	s_mov_b32 m0, s14
	s_nop 0
	global_load_lds_dwordx4 v142, s[10:11]
	s_add_i32 m0, s14, 0x2000
	s_nop 0
	global_load_lds_dwordx4 v138, s[10:11]
	s_mov_b32 m0, s73
	s_nop 0
	global_load_lds_dwordx4 v144, s[100:101]
	s_mov_b32 m0, s82
	s_nop 0
	global_load_lds_dwordx4 v140, s[100:101]
	s_waitcnt vmcnt(8)
	s_waitcnt lgkmcnt(0)
	s_barrier
	v_mfma_f32_16x16x32_bf16 v[62:65], v[130:133], v[186:189], v[62:65]
	v_mfma_f32_16x16x32_bf16 v[58:61], v[152:155], v[186:189], v[58:61]
	v_mfma_f32_16x16x32_bf16 v[46:49], v[130:133], v[194:197], v[46:49]
	v_mfma_f32_16x16x32_bf16 v[42:45], v[152:155], v[194:197], v[42:45]
	v_mfma_f32_16x16x32_bf16 v[30:33], v[130:133], v[202:205], v[30:33]
	v_mfma_f32_16x16x32_bf16 v[26:29], v[152:155], v[202:205], v[26:29]
	v_mfma_f32_16x16x32_bf16 v[12:15], v[130:133], v[210:213], v[12:15]
	v_mfma_f32_16x16x32_bf16 v[8:11], v[152:155], v[210:213], v[8:11]
	v_mfma_f32_16x16x32_bf16 v[62:65], v[134:137], v[190:193], v[62:65]
	v_mfma_f32_16x16x32_bf16 v[58:61], v[156:159], v[190:193], v[58:61]
	v_mfma_f32_16x16x32_bf16 v[46:49], v[134:137], v[198:201], v[46:49]
	v_mfma_f32_16x16x32_bf16 v[42:45], v[156:159], v[198:201], v[42:45]
	v_mfma_f32_16x16x32_bf16 v[30:33], v[134:137], v[206:209], v[30:33]
	v_mfma_f32_16x16x32_bf16 v[26:29], v[156:159], v[206:209], v[26:29]
	v_mfma_f32_16x16x32_bf16 v[12:15], v[134:137], v[214:217], v[12:15]
	v_mfma_f32_16x16x32_bf16 v[8:11], v[156:159], v[214:217], v[8:11]
	v_mfma_f32_16x16x32_bf16 v[54:57], v[160:163], v[186:189], v[54:57]
	v_mfma_f32_16x16x32_bf16 v[50:53], v[178:181], v[186:189], v[50:53]
	v_mfma_f32_16x16x32_bf16 v[38:41], v[160:163], v[194:197], v[38:41]
	v_mfma_f32_16x16x32_bf16 v[34:37], v[178:181], v[194:197], v[34:37]
	v_mfma_f32_16x16x32_bf16 v[22:25], v[160:163], v[202:205], v[22:25]
	v_mfma_f32_16x16x32_bf16 v[18:21], v[178:181], v[202:205], v[18:21]
	v_mfma_f32_16x16x32_bf16 v[4:7], v[160:163], v[210:213], v[4:7]
	v_mfma_f32_16x16x32_bf16 v[0:3], v[178:181], v[210:213], v[0:3]
	v_mfma_f32_16x16x32_bf16 v[54:57], v[174:177], v[190:193], v[54:57]
	v_mfma_f32_16x16x32_bf16 v[50:53], v[182:185], v[190:193], v[50:53]
	v_mfma_f32_16x16x32_bf16 v[38:41], v[174:177], v[198:201], v[38:41]
	v_mfma_f32_16x16x32_bf16 v[34:37], v[182:185], v[198:201], v[34:37]
	v_mfma_f32_16x16x32_bf16 v[22:25], v[174:177], v[206:209], v[22:25]
	v_mfma_f32_16x16x32_bf16 v[18:21], v[182:185], v[206:209], v[18:21]
	v_mfma_f32_16x16x32_bf16 v[4:7], v[174:177], v[214:217], v[4:7]
	v_mfma_f32_16x16x32_bf16 v[0:3], v[182:185], v[214:217], v[0:3]
	s_barrier
	s_add_i32 s27, s27, 2
	s_add_u32 s8, s8, 0x100
	s_addc_u32 s9, s9, 0
	s_add_u32 s0, s0, 0x100
	s_addc_u32 s1, s1, 0
	s_cmp_gt_u32 s27, 61
	s_cbranch_scc0 .LBB0_129
	s_and_b64 vcc, exec, s[24:25]
	s_cbranch_vccz .LBB0_132
	s_barrier

; #define PG8_STAGEA(bufoff, gbase, voff) PG8_STAGE_X(bufoff, gbase, voff, AUXA)
; #define PG8_STR(x) PG8_STR2(x)
;     ...
;         const bool has_next = S.next(ui + 1, nxt);
;         const char* nA = has_next ? (const char*)g.A + (size_t)nxt.pm * tstepA : cA; const char* nB = has_next ? (const char*)g.Bt + (size_t)nxt.pn * tstepB : cB;
;         int t0 = 0;
;         if constexpr (SP2 && GEMM_RELAX == 1) { if (ui > 0) {
;             const char* a1 = cA + kstepA; const char* a2 = cA + 2 * kstepA; const char* b2 = cB + 2 * kstepB; const char* a3 = a2 + kstepA; const char* b3 = b2 + kstepB;
;             PG8_LDB(B0, 0, 0); PG8_LDB(B1, 0, 1); PG8_SCHED; PG8_LDA(At, 0, 0); PG8_STAGEA(PG8_SA(1, 1), a1 + hstepA, voffA);
;             PG8_WAIT_V(24); PG8_WAIT_L(0); PG8_BAR; PG8_MMA(0, 0, At, B0); PG8_MMA(0, 1, At, B1); PG8_BAR; PG8_SCHED;
;             PG8_LDA(At, 0, 1); PG8_STAGEB(PG8_SB(0, 0), b2, voffB); PG8_STAGEB(PG8_SB(0, 1), b2 + hstepB, voffB); PG8_STAGEA(PG8_SA(0, 0), a2, voffA);
;             PG8_WAIT_V(24); PG8_WAIT_L(0); PG8_BAR; PG8_MMA(1, 0, At, B0); PG8_MMA(1, 1, At, B1); PG8_BAR; PG8_SCHED;
;             PG8_LDB(B0, 1, 0); PG8_LDB(B1, 1, 1); PG8_SCHED; PG8_LDA(At, 1, 0); PG8_STAGEA(PG8_SA(0, 1), a2 + hstepA, voffA);
;             PG8_WAIT_V(8); PG8_WAIT_L(0); PG8_BAR; PG8_MMA(0, 0, At, B0); PG8_MMA(0, 1, At, B1); PG8_BAR; PG8_SCHED;
;             PG8_LDA(At, 1, 1); PG8_STAGEB(PG8_SB(1, 0), b3, voffB); PG8_STAGEB(PG8_SB(1, 1), b3 + hstepB, voffB); PG8_STAGEA(PG8_SA(1, 0), a3, voffA);
;             PG8_WAIT_V(8); PG8_WAIT_L(0); PG8_BAR; PG8_MMA(1, 0, At, B0); PG8_MMA(1, 1, At, B1); PG8_BAR; PG8_SCHED;
;             t0 = 2; } }
;     ...
;         asm volatile(".p2align " PG8_STR(GEMM_LOOP_ALIGN) ::: "memory");
;     ...
;         for (int t = t0; t < nt; t += 2) {
;             const bool last = (t == nt - 2);
;             const char* a1 = cA + (size_t)(t + 1) * kstepA;
;             const char* a2 = last ? nA : cA + (size_t)(t + 2) * kstepA; const char* b2 = last ? nB : cB + (size_t)(t + 2) * kstepB;
;             const char* a3 = a2 + kstepA; const char* b3 = b2 + kstepB;
;             if (last && has_next) S.a_ready(nxt);
;             if constexpr (SP2) {
;             PG8_LDB(B0, 0, 0); PG8_LDB(B1, 0, 1); PG8_SCHED; PG8_LDA(At, 0, 0); PG8_STAGEA(PG8_SA(1, 1), a1 + hstepA, voffA);
;     ...
;             const int relax = __builtin_amdgcn_readfirstlane((t == 0 && ui > 0) ? 1 : 0);
.LBB0_557:
	s_ashr_i32 s21, s20, 31
	s_lshl_b64 s[6:7], s[20:21], 21
	s_add_u32 s24, s60, s6
	s_addc_u32 s25, s61, s7
	s_and_b64 s[6:7], s[26:27], exec
	s_cselect_b32 s21, s25, s1
	s_cselect_b32 s82, s24, s0
	s_ashr_i32 s23, s22, 31
	s_lshl_b64 s[6:7], s[22:23], 21
	s_add_u32 s36, s4, s6
	s_addc_u32 s37, s5, s7
	s_and_b64 s[6:7], s[26:27], exec
	s_cselect_b32 s23, s37, s41
	s_cselect_b32 s83, s36, s40
	s_add_u32 s38, s0, 0x100080
	s_addc_u32 s39, s1, 0
	s_add_u32 s0, s40, 0x100
	s_addc_u32 s1, s41, 0
	s_mov_b32 s90, -2
	s_waitcnt lgkmcnt(0)
	s_waitcnt vmcnt(0)
	s_add_u32 s6, s38, 0xfff00080
	s_addc_u32 s7, s39, -1
	s_add_i32 s91, 0, 0x10000
	s_cmp_eq_u32 s90, 60
	s_cselect_b32 s41, s21, s7
	s_cselect_b32 s40, s82, s6
	s_cselect_b32 s17, s23, s1
	s_cselect_b32 s16, s83, s0
	s_add_i32 s94, 0, 0x14000
	v_add_u32_e32 v152, s91, v157
	v_add_u32_e32 v174, s94, v157
	ds_read_b128 v[130:133], v152
	ds_read_b128 v[134:137], v152 offset:1024
	ds_read_b128 v[148:151], v152 offset:2048
	ds_read_b128 v[152:155], v152 offset:3072
	ds_read_b128 v[162:165], v174
	ds_read_b128 v[166:169], v174 offset:1024
	ds_read_b128 v[170:173], v174 offset:2048
	ds_read_b128 v[174:177], v174 offset:3072
	v_lshl_add_u64 v[210:211], s[38:39], 0, v[144:145]
	s_add_i32 m0, s13, 0xc000
	ds_read_b128 v[178:181], v161
	ds_read_b128 v[182:185], v161 offset:1024
	ds_read_b128 v[186:189], v161 offset:2048
	ds_read_b128 v[190:193], v161 offset:3072
	ds_read_b128 v[194:197], v161 offset:4096
	ds_read_b128 v[198:201], v161 offset:5120
	ds_read_b128 v[202:205], v161 offset:6144
	ds_read_b128 v[206:209], v161 offset:7168
	global_load_lds_dwordx4 v[210:211], off
	v_lshl_add_u64 v[210:211], s[38:39], 0, v[146:147]
	s_add_i32 m0, s13, 0xe000
	s_nop 0
	global_load_lds_dwordx4 v[210:211], off
	s_waitcnt vmcnt(8)
	s_waitcnt lgkmcnt(0)
	s_barrier
	v_mfma_f32_16x16x32_bf16 v[126:129], v[130:133], v[178:181], 0
	v_mfma_f32_16x16x32_bf16 v[122:125], v[148:151], v[178:181], 0
	v_mfma_f32_16x16x32_bf16 v[110:113], v[130:133], v[186:189], 0
	v_mfma_f32_16x16x32_bf16 v[106:109], v[148:151], v[186:189], 0
	v_mfma_f32_16x16x32_bf16 v[94:97], v[130:133], v[194:197], 0
	v_mfma_f32_16x16x32_bf16 v[90:93], v[148:151], v[194:197], 0
	v_mfma_f32_16x16x32_bf16 v[78:81], v[130:133], v[202:205], 0
	v_mfma_f32_16x16x32_bf16 v[74:77], v[148:151], v[202:205], 0
	v_mfma_f32_16x16x32_bf16 v[126:129], v[134:137], v[182:185], v[126:129]
	v_mfma_f32_16x16x32_bf16 v[122:125], v[152:155], v[182:185], v[122:125]
	v_mfma_f32_16x16x32_bf16 v[110:113], v[134:137], v[190:193], v[110:113]
	v_mfma_f32_16x16x32_bf16 v[106:109], v[152:155], v[190:193], v[106:109]
	v_mfma_f32_16x16x32_bf16 v[94:97], v[134:137], v[198:201], v[94:97]
	v_mfma_f32_16x16x32_bf16 v[90:93], v[152:155], v[198:201], v[90:93]
	v_mfma_f32_16x16x32_bf16 v[78:81], v[134:137], v[206:209], v[78:81]
	v_mfma_f32_16x16x32_bf16 v[74:77], v[152:155], v[206:209], v[74:77]
	v_mfma_f32_16x16x32_bf16 v[118:121], v[162:165], v[178:181], 0
	v_mfma_f32_16x16x32_bf16 v[114:117], v[170:173], v[178:181], 0
	v_mfma_f32_16x16x32_bf16 v[102:105], v[162:165], v[186:189], 0
	v_mfma_f32_16x16x32_bf16 v[98:101], v[170:173], v[186:189], 0
	v_mfma_f32_16x16x32_bf16 v[86:89], v[162:165], v[194:197], 0
	v_mfma_f32_16x16x32_bf16 v[82:85], v[170:173], v[194:197], 0
	v_mfma_f32_16x16x32_bf16 v[70:73], v[162:165], v[202:205], 0
	v_mfma_f32_16x16x32_bf16 v[66:69], v[170:173], v[202:205], 0
	v_mfma_f32_16x16x32_bf16 v[118:121], v[166:169], v[182:185], v[118:121]
	v_mfma_f32_16x16x32_bf16 v[114:117], v[174:177], v[182:185], v[114:117]
	v_mfma_f32_16x16x32_bf16 v[102:105], v[166:169], v[190:193], v[102:105]
	v_mfma_f32_16x16x32_bf16 v[98:101], v[174:177], v[190:193], v[98:101]
	v_mfma_f32_16x16x32_bf16 v[86:89], v[166:169], v[198:201], v[86:89]
	v_mfma_f32_16x16x32_bf16 v[82:85], v[174:177], v[198:201], v[82:85]
	v_mfma_f32_16x16x32_bf16 v[70:73], v[166:169], v[206:209], v[70:73]
	v_mfma_f32_16x16x32_bf16 v[66:69], v[174:177], v[206:209], v[66:69]
	s_barrier
	s_add_i32 s6, s91, s12
	v_lshl_add_u64 v[210:211], s[16:17], 0, v[16:17]
	s_mov_b32 m0, s6
	ds_read_b128 v[178:181], v161 offset:16384
	ds_read_b128 v[182:185], v161 offset:17408
	ds_read_b128 v[186:189], v161 offset:18432
	ds_read_b128 v[190:193], v161 offset:19456
	ds_read_b128 v[194:197], v161 offset:20480
	ds_read_b128 v[198:201], v161 offset:21504
	ds_read_b128 v[202:205], v161 offset:22528
	ds_read_b128 v[206:209], v161 offset:23552
	global_load_lds_dwordx4 v[210:211], off
	s_add_i32 m0, s6, 0x2000
	s_add_u32 s6, s16, 0x100000
	v_lshl_add_u64 v[212:213], s[16:17], 0, v[138:139]
	s_addc_u32 s7, s17, 0
	s_add_i32 s91, s94, s12
	global_load_lds_dwordx4 v[212:213], off
	v_lshl_add_u64 v[214:215], s[6:7], 0, v[16:17]
	s_mov_b32 m0, s91
	v_lshl_add_u64 v[216:217], s[40:41], 0, v[140:141]
	global_load_lds_dwordx4 v[214:215], off
	v_lshl_add_u64 v[214:215], s[6:7], 0, v[138:139]
	s_add_i32 m0, s91, 0x2000
	s_nop 0
	global_load_lds_dwordx4 v[214:215], off
	v_lshl_add_u64 v[214:215], s[40:41], 0, v[142:143]
	s_mov_b32 m0, s13
	s_nop 0
	global_load_lds_dwordx4 v[214:215], off
	s_mov_b32 m0, s42
	s_nop 0
	global_load_lds_dwordx4 v[216:217], off
	s_waitcnt vmcnt(8)
	s_waitcnt lgkmcnt(0)
	s_barrier
; #define PG8_STAGEA(bufoff, gbase, voff) PG8_STAGE_X(bufoff, gbase, voff, AUXA)
; #define PG8_LDA(dst, b, h) do { _Pragma("unroll") for (int m = 0; m < 4; ++m) _Pragma("unroll") for (int k = 0; k < 2; ++k) dst[m][k] = *(const PG8_LAS bf16x8*)(lds + PG8_SA(b, h) + aoff + m * 2048 + k * 1024); } while (0)
; #define PG8_LDB(dst, b, h) do { _Pragma("unroll") for (int n = 0; n < 2; ++n) _Pragma("unroll") for (int k = 0; k < 2; ++k) dst[n][k] = *(const PG8_LAS bf16x8*)(lds + PG8_SB(b, h) + boff + n * 2048 + k * 1024); } while (0)
; #define PG8_MMA(ai, bj, At, Bt) do { if (GEMM_PRIO_MODE == 0) __builtin_amdgcn_s_setprio(1); PG8_MMA_LOOPS \
;         acc[ai][bj][m][n] = __builtin_amdgcn_mfma_f32_16x16x32_bf16(Bt[n][k], At[m][k], acc[ai][bj][m][n], 0, 0, 0); if (GEMM_PRIO_MODE == 0) __builtin_amdgcn_s_setprio(0); } while (0)
; #define PG8_WAIT_V(n) asm volatile("s_waitcnt vmcnt(" #n ")" ::: "memory")
; #define PG8_WAIT_VR(n, nr, flag) asm volatile("s_cmp_eq_u32 %0, 0\n\ts_cbranch_scc1 .Lpg8s%=\n\ts_waitcnt vmcnt(" #nr ")\n\ts_branch .Lpg8d%=\n.Lpg8s%=:\n\ts_waitcnt vmcnt(" #n ")\n.Lpg8d%=:" :: "s"(flag) : "memory", "scc")
; #define PG8_WAIT_L(n) asm volatile("s_waitcnt lgkmcnt(" #n ")" ::: "memory")
; #define PG8_BAR __builtin_amdgcn_s_barrier()
; #define PG8_SCHED __builtin_amdgcn_sched_barrier(0)
;     ...
;             PG8_WAIT_VR(8, 24, relax); PG8_WAIT_L(0); PG8_BAR; PG8_MMA(1, 0, At, B0); PG8_MMA(1, 1, At, B1); PG8_BAR; PG8_SCHED;
;     ...
;             PG8_WAIT_V(8); PG8_WAIT_L(0); PG8_BAR; PG8_MMA(1, 0, At, B0); PG8_MMA(1, 1, At, B1); PG8_BAR; PG8_SCHED;
;     ...
;             PG8_LDB(B0, 1, 0); PG8_LDB(B1, 1, 1); PG8_SCHED; PG8_LDA(At, 1, 0); PG8_STAGEA(PG8_SA(0, 1), a2 + hstepA, voffA);
;             PG8_WAIT_V(8); PG8_WAIT_L(0); PG8_BAR; PG8_MMA(0, 0, At, B0); PG8_MMA(0, 1, At, B1); PG8_BAR; PG8_SCHED;
	v_mfma_f32_16x16x32_bf16 v[62:65], v[130:133], v[178:181], 0
	v_mfma_f32_16x16x32_bf16 v[58:61], v[148:151], v[178:181], 0
	v_mfma_f32_16x16x32_bf16 v[46:49], v[130:133], v[186:189], 0
	v_mfma_f32_16x16x32_bf16 v[42:45], v[148:151], v[186:189], 0
	v_mfma_f32_16x16x32_bf16 v[30:33], v[130:133], v[194:197], 0
	v_mfma_f32_16x16x32_bf16 v[26:29], v[148:151], v[194:197], 0
	v_mfma_f32_16x16x32_bf16 v[12:15], v[130:133], v[202:205], 0
	v_mfma_f32_16x16x32_bf16 v[8:11], v[148:151], v[202:205], 0
	v_mfma_f32_16x16x32_bf16 v[62:65], v[134:137], v[182:185], v[62:65]
	v_mfma_f32_16x16x32_bf16 v[58:61], v[152:155], v[182:185], v[58:61]
	v_mfma_f32_16x16x32_bf16 v[46:49], v[134:137], v[190:193], v[46:49]
	v_mfma_f32_16x16x32_bf16 v[42:45], v[152:155], v[190:193], v[42:45]
	v_mfma_f32_16x16x32_bf16 v[30:33], v[134:137], v[198:201], v[30:33]
	v_mfma_f32_16x16x32_bf16 v[26:29], v[152:155], v[198:201], v[26:29]
	v_mfma_f32_16x16x32_bf16 v[12:15], v[134:137], v[206:209], v[12:15]
	v_mfma_f32_16x16x32_bf16 v[8:11], v[152:155], v[206:209], v[8:11]
	v_mfma_f32_16x16x32_bf16 v[54:57], v[162:165], v[178:181], 0
	v_mfma_f32_16x16x32_bf16 v[50:53], v[170:173], v[178:181], 0
	v_mfma_f32_16x16x32_bf16 v[38:41], v[162:165], v[186:189], 0
	v_mfma_f32_16x16x32_bf16 v[34:37], v[170:173], v[186:189], 0
	v_mfma_f32_16x16x32_bf16 v[22:25], v[162:165], v[194:197], 0
	v_mfma_f32_16x16x32_bf16 v[18:21], v[170:173], v[194:197], 0
	v_mfma_f32_16x16x32_bf16 v[4:7], v[162:165], v[202:205], 0
	v_mfma_f32_16x16x32_bf16 v[0:3], v[170:173], v[202:205], 0
	v_mfma_f32_16x16x32_bf16 v[54:57], v[166:169], v[182:185], v[54:57]
	v_mfma_f32_16x16x32_bf16 v[50:53], v[174:177], v[182:185], v[50:53]
	v_mfma_f32_16x16x32_bf16 v[38:41], v[166:169], v[190:193], v[38:41]
	v_mfma_f32_16x16x32_bf16 v[34:37], v[174:177], v[190:193], v[34:37]
	v_mfma_f32_16x16x32_bf16 v[22:25], v[166:169], v[198:201], v[22:25]
	v_mfma_f32_16x16x32_bf16 v[18:21], v[174:177], v[198:201], v[18:21]
	v_mfma_f32_16x16x32_bf16 v[4:7], v[166:169], v[206:209], v[4:7]
	v_mfma_f32_16x16x32_bf16 v[0:3], v[174:177], v[206:209], v[0:3]
	s_barrier
	s_add_i32 s91, 0, 0x18000
	s_add_i32 s94, 0, 0x1c000
	v_add_u32_e32 v152, s91, v157
	v_add_u32_e32 v174, s94, v157
	ds_read_b128 v[130:133], v152
	ds_read_b128 v[134:137], v152 offset:1024
	ds_read_b128 v[148:151], v152 offset:2048
	ds_read_b128 v[152:155], v152 offset:3072
	ds_read_b128 v[162:165], v174
	ds_read_b128 v[166:169], v174 offset:1024
	ds_read_b128 v[170:173], v174 offset:2048
	ds_read_b128 v[174:177], v174 offset:3072
	s_add_u32 s6, s40, 0x100000
	s_addc_u32 s7, s41, 0
	s_mov_b32 m0, s43
	v_lshl_add_u64 v[218:219], s[6:7], 0, v[142:143]
	ds_read_b128 v[178:181], v161 offset:32768
	ds_read_b128 v[182:185], v161 offset:33792
	ds_read_b128 v[186:189], v161 offset:34816
	ds_read_b128 v[190:193], v161 offset:35840
	ds_read_b128 v[194:197], v161 offset:36864
	ds_read_b128 v[198:201], v161 offset:37888
	ds_read_b128 v[202:205], v161 offset:38912
	ds_read_b128 v[206:209], v161 offset:39936
	global_load_lds_dwordx4 v[218:219], off
	v_lshl_add_u64 v[218:219], s[6:7], 0, v[140:141]
	s_mov_b32 m0, s50
	s_nop 0
	global_load_lds_dwordx4 v[218:219], off
	s_waitcnt vmcnt(8)
	s_waitcnt lgkmcnt(0)
	s_barrier
	v_mfma_f32_16x16x32_bf16 v[126:129], v[130:133], v[178:181], v[126:129]
	v_mfma_f32_16x16x32_bf16 v[122:125], v[148:151], v[178:181], v[122:125]
	v_mfma_f32_16x16x32_bf16 v[110:113], v[130:133], v[186:189], v[110:113]
	v_mfma_f32_16x16x32_bf16 v[106:109], v[148:151], v[186:189], v[106:109]
	v_mfma_f32_16x16x32_bf16 v[94:97], v[130:133], v[194:197], v[94:97]
	v_mfma_f32_16x16x32_bf16 v[90:93], v[148:151], v[194:197], v[90:93]
	v_mfma_f32_16x16x32_bf16 v[78:81], v[130:133], v[202:205], v[78:81]
	v_mfma_f32_16x16x32_bf16 v[74:77], v[148:151], v[202:205], v[74:77]
	v_mfma_f32_16x16x32_bf16 v[126:129], v[134:137], v[182:185], v[126:129]
	v_mfma_f32_16x16x32_bf16 v[122:125], v[152:155], v[182:185], v[122:125]
	v_mfma_f32_16x16x32_bf16 v[110:113], v[134:137], v[190:193], v[110:113]
	v_mfma_f32_16x16x32_bf16 v[106:109], v[152:155], v[190:193], v[106:109]
	v_mfma_f32_16x16x32_bf16 v[94:97], v[134:137], v[198:201], v[94:97]
	v_mfma_f32_16x16x32_bf16 v[90:93], v[152:155], v[198:201], v[90:93]
	v_mfma_f32_16x16x32_bf16 v[78:81], v[134:137], v[206:209], v[78:81]
	v_mfma_f32_16x16x32_bf16 v[74:77], v[152:155], v[206:209], v[74:77]
	v_mfma_f32_16x16x32_bf16 v[118:121], v[162:165], v[178:181], v[118:121]
	v_mfma_f32_16x16x32_bf16 v[114:117], v[170:173], v[178:181], v[114:117]
	v_mfma_f32_16x16x32_bf16 v[102:105], v[162:165], v[186:189], v[102:105]
	v_mfma_f32_16x16x32_bf16 v[98:101], v[170:173], v[186:189], v[98:101]
	v_mfma_f32_16x16x32_bf16 v[86:89], v[162:165], v[194:197], v[86:89]
	v_mfma_f32_16x16x32_bf16 v[82:85], v[170:173], v[194:197], v[82:85]
	v_mfma_f32_16x16x32_bf16 v[70:73], v[162:165], v[202:205], v[70:73]
	v_mfma_f32_16x16x32_bf16 v[66:69], v[170:173], v[202:205], v[66:69]
	v_mfma_f32_16x16x32_bf16 v[118:121], v[166:169], v[182:185], v[118:121]
	v_mfma_f32_16x16x32_bf16 v[114:117], v[174:177], v[182:185], v[114:117]
	v_mfma_f32_16x16x32_bf16 v[102:105], v[166:169], v[190:193], v[102:105]
	v_mfma_f32_16x16x32_bf16 v[98:101], v[174:177], v[190:193], v[98:101]
	v_mfma_f32_16x16x32_bf16 v[86:89], v[166:169], v[198:201], v[86:89]
	v_mfma_f32_16x16x32_bf16 v[82:85], v[174:177], v[198:201], v[82:85]
	v_mfma_f32_16x16x32_bf16 v[70:73], v[166:169], v[206:209], v[70:73]
	v_mfma_f32_16x16x32_bf16 v[66:69], v[174:177], v[206:209], v[66:69]
	s_barrier
; #define PG8_STAGEA(bufoff, gbase, voff) PG8_STAGE_X(bufoff, gbase, voff, AUXA)
; #define PG8_STAGEB(bufoff, gbase, voff) PG8_STAGE_X(bufoff, gbase, voff, AUXB)
; #define PG8_LDA(dst, b, h) do { _Pragma("unroll") for (int m = 0; m < 4; ++m) _Pragma("unroll") for (int k = 0; k < 2; ++k) dst[m][k] = *(const PG8_LAS bf16x8*)(lds + PG8_SA(b, h) + aoff + m * 2048 + k * 1024); } while (0)
; #define PG8_LDB(dst, b, h) do { _Pragma("unroll") for (int n = 0; n < 2; ++n) _Pragma("unroll") for (int k = 0; k < 2; ++k) dst[n][k] = *(const PG8_LAS bf16x8*)(lds + PG8_SB(b, h) + boff + n * 2048 + k * 1024); } while (0)
; #define PG8_MMA(ai, bj, At, Bt) do { if (GEMM_PRIO_MODE == 0) __builtin_amdgcn_s_setprio(1); PG8_MMA_LOOPS \
;         acc[ai][bj][m][n] = __builtin_amdgcn_mfma_f32_16x16x32_bf16(Bt[n][k], At[m][k], acc[ai][bj][m][n], 0, 0, 0); if (GEMM_PRIO_MODE == 0) __builtin_amdgcn_s_setprio(0); } while (0)
; #define PG8_WAIT_V(n) asm volatile("s_waitcnt vmcnt(" #n ")" ::: "memory")
; #define PG8_WAIT_L(n) asm volatile("s_waitcnt lgkmcnt(" #n ")" ::: "memory")
; #define PG8_BAR __builtin_amdgcn_s_barrier()
; #define PG8_SCHED __builtin_amdgcn_sched_barrier(0)
;     ...
;         for (int t = t0; t < nt; t += 2) {
;             const bool last = (t == nt - 2);
;             const char* a1 = cA + (size_t)(t + 1) * kstepA;
;             const char* a2 = last ? nA : cA + (size_t)(t + 2) * kstepA; const char* b2 = last ? nB : cB + (size_t)(t + 2) * kstepB;
;             const char* a3 = a2 + kstepA; const char* b3 = b2 + kstepB;
;             if (last && has_next) S.a_ready(nxt);
;             if constexpr (SP2) {
;             PG8_LDB(B0, 0, 0); PG8_LDB(B1, 0, 1); PG8_SCHED; PG8_LDA(At, 0, 0); PG8_STAGEA(PG8_SA(1, 1), a1 + hstepA, voffA);
;     ...
;             PG8_LDA(At, 1, 1); PG8_STAGEB(PG8_SB(1, 0), b3, voffB); PG8_STAGEB(PG8_SB(1, 1), b3 + hstepB, voffB); PG8_STAGEA(PG8_SA(1, 0), a3, voffA);
;             PG8_WAIT_V(8); PG8_WAIT_L(0); PG8_BAR; PG8_MMA(1, 0, At, B0); PG8_MMA(1, 1, At, B1); PG8_BAR; PG8_SCHED;
	s_add_i32 s6, s91, s12
	v_lshl_add_u64 v[210:211], v[210:211], 0, s[86:87]
	s_mov_b32 m0, s6
	ds_read_b128 v[178:181], v161 offset:49152
	ds_read_b128 v[182:185], v161 offset:50176
	ds_read_b128 v[186:189], v161 offset:51200
	ds_read_b128 v[190:193], v161 offset:52224
	ds_read_b128 v[194:197], v161 offset:53248
	ds_read_b128 v[198:201], v161 offset:54272
	ds_read_b128 v[202:205], v161 offset:55296
	ds_read_b128 v[206:209], v161 offset:56320
	global_load_lds_dwordx4 v[210:211], off
	s_add_i32 m0, s6, 0x2000
	s_add_u32 s6, s16, 0x100080
	v_lshl_add_u64 v[210:211], v[212:213], 0, s[86:87]
	s_addc_u32 s7, s17, 0
	s_add_i32 s16, s94, s12
	global_load_lds_dwordx4 v[210:211], off
	v_lshl_add_u64 v[210:211], s[6:7], 0, v[16:17]
	s_mov_b32 m0, s16
	s_nop 0
	global_load_lds_dwordx4 v[210:211], off
	v_lshl_add_u64 v[210:211], s[6:7], 0, v[138:139]
	s_add_i32 m0, s16, 0x2000
	s_nop 0
	global_load_lds_dwordx4 v[210:211], off
	v_lshl_add_u64 v[210:211], v[214:215], 0, s[86:87]
	s_mov_b32 m0, s68
	s_nop 0
	global_load_lds_dwordx4 v[210:211], off
	v_lshl_add_u64 v[210:211], v[216:217], 0, s[86:87]
	s_mov_b32 m0, s69
	s_nop 0
	global_load_lds_dwordx4 v[210:211], off
	s_waitcnt vmcnt(8)
	s_waitcnt lgkmcnt(0)
	s_nop 0
	s_barrier
	v_mfma_f32_16x16x32_bf16 v[62:65], v[130:133], v[178:181], v[62:65]
	v_mfma_f32_16x16x32_bf16 v[58:61], v[148:151], v[178:181], v[58:61]
	v_mfma_f32_16x16x32_bf16 v[46:49], v[130:133], v[186:189], v[46:49]
	v_mfma_f32_16x16x32_bf16 v[42:45], v[148:151], v[186:189], v[42:45]
	v_mfma_f32_16x16x32_bf16 v[30:33], v[130:133], v[194:197], v[30:33]
	v_mfma_f32_16x16x32_bf16 v[26:29], v[148:151], v[194:197], v[26:29]
	v_mfma_f32_16x16x32_bf16 v[12:15], v[130:133], v[202:205], v[12:15]
	v_mfma_f32_16x16x32_bf16 v[8:11], v[148:151], v[202:205], v[8:11]
	v_mfma_f32_16x16x32_bf16 v[62:65], v[134:137], v[182:185], v[62:65]
	v_mfma_f32_16x16x32_bf16 v[58:61], v[152:155], v[182:185], v[58:61]
	v_mfma_f32_16x16x32_bf16 v[46:49], v[134:137], v[190:193], v[46:49]
	v_mfma_f32_16x16x32_bf16 v[42:45], v[152:155], v[190:193], v[42:45]
	v_mfma_f32_16x16x32_bf16 v[30:33], v[134:137], v[198:201], v[30:33]
	v_mfma_f32_16x16x32_bf16 v[26:29], v[152:155], v[198:201], v[26:29]
	v_mfma_f32_16x16x32_bf16 v[12:15], v[134:137], v[206:209], v[12:15]
	v_mfma_f32_16x16x32_bf16 v[8:11], v[152:155], v[206:209], v[8:11]
	v_mfma_f32_16x16x32_bf16 v[54:57], v[162:165], v[178:181], v[54:57]
	v_mfma_f32_16x16x32_bf16 v[50:53], v[170:173], v[178:181], v[50:53]
	v_mfma_f32_16x16x32_bf16 v[38:41], v[162:165], v[186:189], v[38:41]
	v_mfma_f32_16x16x32_bf16 v[34:37], v[170:173], v[186:189], v[34:37]
	v_mfma_f32_16x16x32_bf16 v[22:25], v[162:165], v[194:197], v[22:25]
	v_mfma_f32_16x16x32_bf16 v[18:21], v[170:173], v[194:197], v[18:21]
	v_mfma_f32_16x16x32_bf16 v[4:7], v[162:165], v[202:205], v[4:7]
	v_mfma_f32_16x16x32_bf16 v[0:3], v[170:173], v[202:205], v[0:3]
	v_mfma_f32_16x16x32_bf16 v[54:57], v[166:169], v[182:185], v[54:57]
	v_mfma_f32_16x16x32_bf16 v[50:53], v[174:177], v[182:185], v[50:53]
	v_mfma_f32_16x16x32_bf16 v[38:41], v[166:169], v[190:193], v[38:41]
	v_mfma_f32_16x16x32_bf16 v[34:37], v[174:177], v[190:193], v[34:37]
	v_mfma_f32_16x16x32_bf16 v[22:25], v[166:169], v[198:201], v[22:25]
	v_mfma_f32_16x16x32_bf16 v[18:21], v[174:177], v[198:201], v[18:21]
	v_mfma_f32_16x16x32_bf16 v[4:7], v[166:169], v[206:209], v[4:7]
	v_mfma_f32_16x16x32_bf16 v[0:3], v[174:177], v[206:209], v[0:3]
	s_barrier
	s_add_i32 s90, s90, 2
	s_add_u32 s38, s38, 0x100
	s_addc_u32 s39, s39, 0
	s_add_u32 s0, s0, 0x100
	s_addc_u32 s1, s1, 0
	v_add_u32_e32 v220, 0x10000, v157
.LBB0_558:
	s_add_u32 s6, s38, 0xfff00080
	s_addc_u32 s7, s39, -1
	s_add_i32 s91, 0, 0x10000
	s_cmp_eq_u32 s90, 60
	s_cselect_b32 s41, s21, s7
	s_cselect_b32 s40, s82, s6
	s_cselect_b32 s17, s23, s1
	s_cselect_b32 s16, s83, s0
	s_add_i32 s94, 0, 0x14000
	ds_read_b128 v[130:133], v220
	ds_read_b128 v[134:137], v220 offset:1024
	ds_read_b128 v[148:151], v220 offset:2048
	ds_read_b128 v[152:155], v220 offset:3072
	ds_read_b128 v[162:165], v220 offset:16384
	ds_read_b128 v[166:169], v220 offset:17408
	ds_read_b128 v[170:173], v220 offset:18432
	ds_read_b128 v[174:177], v220 offset:19456
	s_add_i32 m0, s13, 0xc000
	ds_read_b128 v[178:181], v161
	ds_read_b128 v[182:185], v161 offset:1024
	ds_read_b128 v[186:189], v161 offset:2048
	ds_read_b128 v[190:193], v161 offset:3072
	ds_read_b128 v[194:197], v161 offset:4096
	ds_read_b128 v[198:201], v161 offset:5120
	ds_read_b128 v[202:205], v161 offset:6144
	ds_read_b128 v[206:209], v161 offset:7168
	global_load_lds_dwordx4 v144, s[38:39]
	s_add_i32 m0, s13, 0xe000
	s_nop 0
	global_load_lds_dwordx4 v146, s[38:39]
	s_waitcnt vmcnt(8)
	s_waitcnt lgkmcnt(0)
	s_barrier
; #define PG8_STAGEA(bufoff, gbase, voff) PG8_STAGE_X(bufoff, gbase, voff, AUXA)
; #define PG8_STAGEB(bufoff, gbase, voff) PG8_STAGE_X(bufoff, gbase, voff, AUXB)
; #define PG8_LDA(dst, b, h) do { _Pragma("unroll") for (int m = 0; m < 4; ++m) _Pragma("unroll") for (int k = 0; k < 2; ++k) dst[m][k] = *(const PG8_LAS bf16x8*)(lds + PG8_SA(b, h) + aoff + m * 2048 + k * 1024); } while (0)
; #define PG8_LDB(dst, b, h) do { _Pragma("unroll") for (int n = 0; n < 2; ++n) _Pragma("unroll") for (int k = 0; k < 2; ++k) dst[n][k] = *(const PG8_LAS bf16x8*)(lds + PG8_SB(b, h) + boff + n * 2048 + k * 1024); } while (0)
; #define PG8_MMA(ai, bj, At, Bt) do { if (GEMM_PRIO_MODE == 0) __builtin_amdgcn_s_setprio(1); PG8_MMA_LOOPS \
;         acc[ai][bj][m][n] = __builtin_amdgcn_mfma_f32_16x16x32_bf16(Bt[n][k], At[m][k], acc[ai][bj][m][n], 0, 0, 0); if (GEMM_PRIO_MODE == 0) __builtin_amdgcn_s_setprio(0); } while (0)
; #define PG8_WAIT_V(n) asm volatile("s_waitcnt vmcnt(" #n ")" ::: "memory")
; #define PG8_WAIT_VR(n, nr, flag) asm volatile("s_cmp_eq_u32 %0, 0\n\ts_cbranch_scc1 .Lpg8s%=\n\ts_waitcnt vmcnt(" #nr ")\n\ts_branch .Lpg8d%=\n.Lpg8s%=:\n\ts_waitcnt vmcnt(" #n ")\n.Lpg8d%=:" :: "s"(flag) : "memory", "scc")
; #define PG8_WAIT_L(n) asm volatile("s_waitcnt lgkmcnt(" #n ")" ::: "memory")
; #define PG8_BAR __builtin_amdgcn_s_barrier()
; #define PG8_SCHED __builtin_amdgcn_sched_barrier(0)
;     ...
;             PG8_LDB(B0, 0, 0); PG8_LDB(B1, 0, 1); PG8_SCHED; PG8_LDA(At, 0, 0); PG8_STAGEA(PG8_SA(1, 1), a1 + hstepA, voffA);
;     ...
;             const int relax = __builtin_amdgcn_readfirstlane((t == 0 && ui > 0) ? 1 : 0);
;             PG8_WAIT_VR(8, 24, relax); PG8_WAIT_L(0); PG8_BAR; PG8_MMA(0, 0, At, B0); PG8_MMA(0, 1, At, B1); PG8_BAR; PG8_SCHED;
;     ...
;             PG8_WAIT_V(8); PG8_WAIT_L(0); PG8_BAR; PG8_MMA(0, 0, At, B0); PG8_MMA(0, 1, At, B1); PG8_BAR; PG8_SCHED;
;     ...
;             PG8_LDA(At, 0, 1); PG8_STAGEB(PG8_SB(0, 0), b2, voffB); PG8_STAGEB(PG8_SB(0, 1), b2 + hstepB, voffB); PG8_STAGEA(PG8_SA(0, 0), a2, voffA);
;     ...
;             PG8_WAIT_VR(8, 24, relax); PG8_WAIT_L(0); PG8_BAR; PG8_MMA(1, 0, At, B0); PG8_MMA(1, 1, At, B1); PG8_BAR; PG8_SCHED;
;     ...
;             PG8_WAIT_V(8); PG8_WAIT_L(0); PG8_BAR; PG8_MMA(1, 0, At, B0); PG8_MMA(1, 1, At, B1); PG8_BAR; PG8_SCHED;
	v_mfma_f32_16x16x32_bf16 v[126:129], v[130:133], v[178:181], v[126:129]
	v_mfma_f32_16x16x32_bf16 v[122:125], v[148:151], v[178:181], v[122:125]
	v_mfma_f32_16x16x32_bf16 v[110:113], v[130:133], v[186:189], v[110:113]
	v_mfma_f32_16x16x32_bf16 v[106:109], v[148:151], v[186:189], v[106:109]
	v_mfma_f32_16x16x32_bf16 v[94:97], v[130:133], v[194:197], v[94:97]
	v_mfma_f32_16x16x32_bf16 v[90:93], v[148:151], v[194:197], v[90:93]
	v_mfma_f32_16x16x32_bf16 v[78:81], v[130:133], v[202:205], v[78:81]
	v_mfma_f32_16x16x32_bf16 v[74:77], v[148:151], v[202:205], v[74:77]
	v_mfma_f32_16x16x32_bf16 v[126:129], v[134:137], v[182:185], v[126:129]
	v_mfma_f32_16x16x32_bf16 v[122:125], v[152:155], v[182:185], v[122:125]
	v_mfma_f32_16x16x32_bf16 v[110:113], v[134:137], v[190:193], v[110:113]
	v_mfma_f32_16x16x32_bf16 v[106:109], v[152:155], v[190:193], v[106:109]
	v_mfma_f32_16x16x32_bf16 v[94:97], v[134:137], v[198:201], v[94:97]
	v_mfma_f32_16x16x32_bf16 v[90:93], v[152:155], v[198:201], v[90:93]
	v_mfma_f32_16x16x32_bf16 v[78:81], v[134:137], v[206:209], v[78:81]
	v_mfma_f32_16x16x32_bf16 v[74:77], v[152:155], v[206:209], v[74:77]
	v_mfma_f32_16x16x32_bf16 v[118:121], v[162:165], v[178:181], v[118:121]
	v_mfma_f32_16x16x32_bf16 v[114:117], v[170:173], v[178:181], v[114:117]
	v_mfma_f32_16x16x32_bf16 v[102:105], v[162:165], v[186:189], v[102:105]
	v_mfma_f32_16x16x32_bf16 v[98:101], v[170:173], v[186:189], v[98:101]
	v_mfma_f32_16x16x32_bf16 v[86:89], v[162:165], v[194:197], v[86:89]
	v_mfma_f32_16x16x32_bf16 v[82:85], v[170:173], v[194:197], v[82:85]
	v_mfma_f32_16x16x32_bf16 v[70:73], v[162:165], v[202:205], v[70:73]
	v_mfma_f32_16x16x32_bf16 v[66:69], v[170:173], v[202:205], v[66:69]
	v_mfma_f32_16x16x32_bf16 v[118:121], v[166:169], v[182:185], v[118:121]
	v_mfma_f32_16x16x32_bf16 v[114:117], v[174:177], v[182:185], v[114:117]
	v_mfma_f32_16x16x32_bf16 v[102:105], v[166:169], v[190:193], v[102:105]
	v_mfma_f32_16x16x32_bf16 v[98:101], v[174:177], v[190:193], v[98:101]
	v_mfma_f32_16x16x32_bf16 v[86:89], v[166:169], v[198:201], v[86:89]
	v_mfma_f32_16x16x32_bf16 v[82:85], v[174:177], v[198:201], v[82:85]
	v_mfma_f32_16x16x32_bf16 v[70:73], v[166:169], v[206:209], v[70:73]
	v_mfma_f32_16x16x32_bf16 v[66:69], v[174:177], v[206:209], v[66:69]
	s_barrier
	s_add_i32 s6, s91, s12
	s_mov_b32 m0, s6
	ds_read_b128 v[178:181], v161 offset:16384
	ds_read_b128 v[182:185], v161 offset:17408
	ds_read_b128 v[186:189], v161 offset:18432
	ds_read_b128 v[190:193], v161 offset:19456
	ds_read_b128 v[194:197], v161 offset:20480
	ds_read_b128 v[198:201], v161 offset:21504
	ds_read_b128 v[202:205], v161 offset:22528
	ds_read_b128 v[206:209], v161 offset:23552
	global_load_lds_dwordx4 v16, s[16:17]
	s_add_i32 m0, s6, 0x2000
	s_add_u32 s6, s16, 0x100000
	s_addc_u32 s7, s17, 0
	s_add_i32 s91, s94, s12
	global_load_lds_dwordx4 v138, s[16:17]
	s_mov_b32 m0, s91
	s_nop 0
	global_load_lds_dwordx4 v16, s[6:7]
	s_add_i32 m0, s91, 0x2000
	s_nop 0
	global_load_lds_dwordx4 v138, s[6:7]
	s_mov_b32 m0, s13
	s_nop 0
	global_load_lds_dwordx4 v142, s[40:41]
	s_mov_b32 m0, s42
	s_nop 0
	global_load_lds_dwordx4 v140, s[40:41]
	s_waitcnt vmcnt(8)
	s_waitcnt lgkmcnt(0)
	s_nop 0
	s_barrier
	v_mfma_f32_16x16x32_bf16 v[62:65], v[130:133], v[178:181], v[62:65]
	v_mfma_f32_16x16x32_bf16 v[58:61], v[148:151], v[178:181], v[58:61]
	v_mfma_f32_16x16x32_bf16 v[46:49], v[130:133], v[186:189], v[46:49]
	v_mfma_f32_16x16x32_bf16 v[42:45], v[148:151], v[186:189], v[42:45]
	v_mfma_f32_16x16x32_bf16 v[30:33], v[130:133], v[194:197], v[30:33]
	v_mfma_f32_16x16x32_bf16 v[26:29], v[148:151], v[194:197], v[26:29]
	v_mfma_f32_16x16x32_bf16 v[12:15], v[130:133], v[202:205], v[12:15]
	v_mfma_f32_16x16x32_bf16 v[8:11], v[148:151], v[202:205], v[8:11]
	v_mfma_f32_16x16x32_bf16 v[62:65], v[134:137], v[182:185], v[62:65]
	v_mfma_f32_16x16x32_bf16 v[58:61], v[152:155], v[182:185], v[58:61]
	v_mfma_f32_16x16x32_bf16 v[46:49], v[134:137], v[190:193], v[46:49]
	v_mfma_f32_16x16x32_bf16 v[42:45], v[152:155], v[190:193], v[42:45]
	v_mfma_f32_16x16x32_bf16 v[30:33], v[134:137], v[198:201], v[30:33]
	v_mfma_f32_16x16x32_bf16 v[26:29], v[152:155], v[198:201], v[26:29]
	v_mfma_f32_16x16x32_bf16 v[12:15], v[134:137], v[206:209], v[12:15]
	v_mfma_f32_16x16x32_bf16 v[8:11], v[152:155], v[206:209], v[8:11]
	v_mfma_f32_16x16x32_bf16 v[54:57], v[162:165], v[178:181], v[54:57]
	v_mfma_f32_16x16x32_bf16 v[50:53], v[170:173], v[178:181], v[50:53]
	v_mfma_f32_16x16x32_bf16 v[38:41], v[162:165], v[186:189], v[38:41]
	v_mfma_f32_16x16x32_bf16 v[34:37], v[170:173], v[186:189], v[34:37]
	v_mfma_f32_16x16x32_bf16 v[22:25], v[162:165], v[194:197], v[22:25]
	v_mfma_f32_16x16x32_bf16 v[18:21], v[170:173], v[194:197], v[18:21]
	v_mfma_f32_16x16x32_bf16 v[4:7], v[162:165], v[202:205], v[4:7]
	v_mfma_f32_16x16x32_bf16 v[0:3], v[170:173], v[202:205], v[0:3]
	v_mfma_f32_16x16x32_bf16 v[54:57], v[166:169], v[182:185], v[54:57]
	v_mfma_f32_16x16x32_bf16 v[50:53], v[174:177], v[182:185], v[50:53]
	v_mfma_f32_16x16x32_bf16 v[38:41], v[166:169], v[190:193], v[38:41]
	v_mfma_f32_16x16x32_bf16 v[34:37], v[174:177], v[190:193], v[34:37]
	v_mfma_f32_16x16x32_bf16 v[22:25], v[166:169], v[198:201], v[22:25]
	v_mfma_f32_16x16x32_bf16 v[18:21], v[174:177], v[198:201], v[18:21]
	v_mfma_f32_16x16x32_bf16 v[4:7], v[166:169], v[206:209], v[4:7]
	v_mfma_f32_16x16x32_bf16 v[0:3], v[174:177], v[206:209], v[0:3]
	s_barrier
; #define PG8_STAGEA(bufoff, gbase, voff) PG8_STAGE_X(bufoff, gbase, voff, AUXA)
; #define PG8_STAGEB(bufoff, gbase, voff) PG8_STAGE_X(bufoff, gbase, voff, AUXB)
; #define PG8_LDA(dst, b, h) do { _Pragma("unroll") for (int m = 0; m < 4; ++m) _Pragma("unroll") for (int k = 0; k < 2; ++k) dst[m][k] = *(const PG8_LAS bf16x8*)(lds + PG8_SA(b, h) + aoff + m * 2048 + k * 1024); } while (0)
; #define PG8_LDB(dst, b, h) do { _Pragma("unroll") for (int n = 0; n < 2; ++n) _Pragma("unroll") for (int k = 0; k < 2; ++k) dst[n][k] = *(const PG8_LAS bf16x8*)(lds + PG8_SB(b, h) + boff + n * 2048 + k * 1024); } while (0)
; #define PG8_MMA(ai, bj, At, Bt) do { if (GEMM_PRIO_MODE == 0) __builtin_amdgcn_s_setprio(1); PG8_MMA_LOOPS \
;         acc[ai][bj][m][n] = __builtin_amdgcn_mfma_f32_16x16x32_bf16(Bt[n][k], At[m][k], acc[ai][bj][m][n], 0, 0, 0); if (GEMM_PRIO_MODE == 0) __builtin_amdgcn_s_setprio(0); } while (0)
; #define PG8_WAIT_V(n) asm volatile("s_waitcnt vmcnt(" #n ")" ::: "memory")
; #define PG8_WAIT_L(n) asm volatile("s_waitcnt lgkmcnt(" #n ")" ::: "memory")
; #define PG8_BAR __builtin_amdgcn_s_barrier()
; #define PG8_SCHED __builtin_amdgcn_sched_barrier(0)
;     ...
;             PG8_LDB(B0, 1, 0); PG8_LDB(B1, 1, 1); PG8_SCHED; PG8_LDA(At, 1, 0); PG8_STAGEA(PG8_SA(0, 1), a2 + hstepA, voffA);
;             PG8_WAIT_V(8); PG8_WAIT_L(0); PG8_BAR; PG8_MMA(0, 0, At, B0); PG8_MMA(0, 1, At, B1); PG8_BAR; PG8_SCHED;
;             PG8_LDA(At, 1, 1); PG8_STAGEB(PG8_SB(1, 0), b3, voffB); PG8_STAGEB(PG8_SB(1, 1), b3 + hstepB, voffB); PG8_STAGEA(PG8_SA(1, 0), a3, voffA);
;             PG8_WAIT_V(8); PG8_WAIT_L(0); PG8_BAR; PG8_MMA(1, 0, At, B0); PG8_MMA(1, 1, At, B1); PG8_BAR; PG8_SCHED;
	s_add_i32 s91, 0, 0x18000
	s_add_i32 s94, 0, 0x1c000
	ds_read_b128 v[130:133], v220 offset:32768
	ds_read_b128 v[134:137], v220 offset:33792
	ds_read_b128 v[148:151], v220 offset:34816
	ds_read_b128 v[152:155], v220 offset:35840
	ds_read_b128 v[162:165], v220 offset:49152
	ds_read_b128 v[166:169], v220 offset:50176
	ds_read_b128 v[170:173], v220 offset:51200
	ds_read_b128 v[174:177], v220 offset:52224
	s_add_u32 s6, s40, 0x100000
	s_addc_u32 s7, s41, 0
	s_mov_b32 m0, s43
	ds_read_b128 v[178:181], v161 offset:32768
	ds_read_b128 v[182:185], v161 offset:33792
	ds_read_b128 v[186:189], v161 offset:34816
	ds_read_b128 v[190:193], v161 offset:35840
	ds_read_b128 v[194:197], v161 offset:36864
	ds_read_b128 v[198:201], v161 offset:37888
	ds_read_b128 v[202:205], v161 offset:38912
	ds_read_b128 v[206:209], v161 offset:39936
	global_load_lds_dwordx4 v142, s[6:7]
	s_mov_b32 m0, s50
	s_nop 0
	global_load_lds_dwordx4 v140, s[6:7]
	s_waitcnt vmcnt(8)
	s_waitcnt lgkmcnt(0)
	s_barrier
	v_mfma_f32_16x16x32_bf16 v[126:129], v[130:133], v[178:181], v[126:129]
	v_mfma_f32_16x16x32_bf16 v[122:125], v[148:151], v[178:181], v[122:125]
	v_mfma_f32_16x16x32_bf16 v[110:113], v[130:133], v[186:189], v[110:113]
	v_mfma_f32_16x16x32_bf16 v[106:109], v[148:151], v[186:189], v[106:109]
	v_mfma_f32_16x16x32_bf16 v[94:97], v[130:133], v[194:197], v[94:97]
	v_mfma_f32_16x16x32_bf16 v[90:93], v[148:151], v[194:197], v[90:93]
	v_mfma_f32_16x16x32_bf16 v[78:81], v[130:133], v[202:205], v[78:81]
	v_mfma_f32_16x16x32_bf16 v[74:77], v[148:151], v[202:205], v[74:77]
	v_mfma_f32_16x16x32_bf16 v[126:129], v[134:137], v[182:185], v[126:129]
	v_mfma_f32_16x16x32_bf16 v[122:125], v[152:155], v[182:185], v[122:125]
	v_mfma_f32_16x16x32_bf16 v[110:113], v[134:137], v[190:193], v[110:113]
	v_mfma_f32_16x16x32_bf16 v[106:109], v[152:155], v[190:193], v[106:109]
	v_mfma_f32_16x16x32_bf16 v[94:97], v[134:137], v[198:201], v[94:97]
	v_mfma_f32_16x16x32_bf16 v[90:93], v[152:155], v[198:201], v[90:93]
	v_mfma_f32_16x16x32_bf16 v[78:81], v[134:137], v[206:209], v[78:81]
	v_mfma_f32_16x16x32_bf16 v[74:77], v[152:155], v[206:209], v[74:77]
	v_mfma_f32_16x16x32_bf16 v[118:121], v[162:165], v[178:181], v[118:121]
	v_mfma_f32_16x16x32_bf16 v[114:117], v[170:173], v[178:181], v[114:117]
	v_mfma_f32_16x16x32_bf16 v[102:105], v[162:165], v[186:189], v[102:105]
	v_mfma_f32_16x16x32_bf16 v[98:101], v[170:173], v[186:189], v[98:101]
	v_mfma_f32_16x16x32_bf16 v[86:89], v[162:165], v[194:197], v[86:89]
	v_mfma_f32_16x16x32_bf16 v[82:85], v[170:173], v[194:197], v[82:85]
	v_mfma_f32_16x16x32_bf16 v[70:73], v[162:165], v[202:205], v[70:73]
	v_mfma_f32_16x16x32_bf16 v[66:69], v[170:173], v[202:205], v[66:69]
	v_mfma_f32_16x16x32_bf16 v[118:121], v[166:169], v[182:185], v[118:121]
	v_mfma_f32_16x16x32_bf16 v[114:117], v[174:177], v[182:185], v[114:117]
	v_mfma_f32_16x16x32_bf16 v[102:105], v[166:169], v[190:193], v[102:105]
	v_mfma_f32_16x16x32_bf16 v[98:101], v[174:177], v[190:193], v[98:101]
	v_mfma_f32_16x16x32_bf16 v[86:89], v[166:169], v[198:201], v[86:89]
	v_mfma_f32_16x16x32_bf16 v[82:85], v[174:177], v[198:201], v[82:85]
	v_mfma_f32_16x16x32_bf16 v[70:73], v[166:169], v[206:209], v[70:73]
	v_mfma_f32_16x16x32_bf16 v[66:69], v[174:177], v[206:209], v[66:69]
	s_barrier
	s_add_i32 s6, s91, s12
	s_mov_b32 m0, s6
	ds_read_b128 v[178:181], v161 offset:49152
	ds_read_b128 v[182:185], v161 offset:50176
	ds_read_b128 v[186:189], v161 offset:51200
	ds_read_b128 v[190:193], v161 offset:52224
	ds_read_b128 v[194:197], v161 offset:53248
	ds_read_b128 v[198:201], v161 offset:54272
	ds_read_b128 v[202:205], v161 offset:55296
	ds_read_b128 v[206:209], v161 offset:56320
	s_add_u32 s100, s16, 0x80
	s_addc_u32 s101, s17, 0
	global_load_lds_dwordx4 v16, s[100:101]
	s_add_i32 m0, s6, 0x2000
	s_add_u32 s6, s16, 0x100080
	s_addc_u32 s7, s17, 0
	s_add_i32 s16, s94, s12
	global_load_lds_dwordx4 v138, s[100:101]
	s_mov_b32 m0, s16
	s_nop 0
	global_load_lds_dwordx4 v16, s[6:7]
	s_add_i32 m0, s16, 0x2000
	s_nop 0
	global_load_lds_dwordx4 v138, s[6:7]
	s_mov_b32 m0, s68
	s_nop 0
	s_add_u32 vcc_lo, s40, 0x80
	s_addc_u32 vcc_hi, s41, 0
	global_load_lds_dwordx4 v142, vcc
	s_mov_b32 m0, s69
	s_nop 0
	global_load_lds_dwordx4 v140, vcc
	s_waitcnt vmcnt(8)
	s_waitcnt lgkmcnt(0)
	s_nop 0
	s_barrier
	v_mfma_f32_16x16x32_bf16 v[62:65], v[130:133], v[178:181], v[62:65]
	v_mfma_f32_16x16x32_bf16 v[58:61], v[148:151], v[178:181], v[58:61]
	v_mfma_f32_16x16x32_bf16 v[46:49], v[130:133], v[186:189], v[46:49]
	v_mfma_f32_16x16x32_bf16 v[42:45], v[148:151], v[186:189], v[42:45]
	v_mfma_f32_16x16x32_bf16 v[30:33], v[130:133], v[194:197], v[30:33]
	v_mfma_f32_16x16x32_bf16 v[26:29], v[148:151], v[194:197], v[26:29]
	v_mfma_f32_16x16x32_bf16 v[12:15], v[130:133], v[202:205], v[12:15]
	v_mfma_f32_16x16x32_bf16 v[8:11], v[148:151], v[202:205], v[8:11]
	v_mfma_f32_16x16x32_bf16 v[62:65], v[134:137], v[182:185], v[62:65]
	v_mfma_f32_16x16x32_bf16 v[58:61], v[152:155], v[182:185], v[58:61]
	v_mfma_f32_16x16x32_bf16 v[46:49], v[134:137], v[190:193], v[46:49]
	v_mfma_f32_16x16x32_bf16 v[42:45], v[152:155], v[190:193], v[42:45]
	v_mfma_f32_16x16x32_bf16 v[30:33], v[134:137], v[198:201], v[30:33]
	v_mfma_f32_16x16x32_bf16 v[26:29], v[152:155], v[198:201], v[26:29]
	v_mfma_f32_16x16x32_bf16 v[12:15], v[134:137], v[206:209], v[12:15]
	v_mfma_f32_16x16x32_bf16 v[8:11], v[152:155], v[206:209], v[8:11]
	v_mfma_f32_16x16x32_bf16 v[54:57], v[162:165], v[178:181], v[54:57]
	v_mfma_f32_16x16x32_bf16 v[50:53], v[170:173], v[178:181], v[50:53]
	v_mfma_f32_16x16x32_bf16 v[38:41], v[162:165], v[186:189], v[38:41]
	v_mfma_f32_16x16x32_bf16 v[34:37], v[170:173], v[186:189], v[34:37]
	v_mfma_f32_16x16x32_bf16 v[22:25], v[162:165], v[194:197], v[22:25]
	v_mfma_f32_16x16x32_bf16 v[18:21], v[170:173], v[194:197], v[18:21]
	v_mfma_f32_16x16x32_bf16 v[4:7], v[162:165], v[202:205], v[4:7]
	v_mfma_f32_16x16x32_bf16 v[0:3], v[170:173], v[202:205], v[0:3]
	v_mfma_f32_16x16x32_bf16 v[54:57], v[166:169], v[182:185], v[54:57]
	v_mfma_f32_16x16x32_bf16 v[50:53], v[174:177], v[182:185], v[50:53]
	v_mfma_f32_16x16x32_bf16 v[38:41], v[166:169], v[190:193], v[38:41]
	v_mfma_f32_16x16x32_bf16 v[34:37], v[174:177], v[190:193], v[34:37]
	v_mfma_f32_16x16x32_bf16 v[22:25], v[166:169], v[198:201], v[22:25]
	v_mfma_f32_16x16x32_bf16 v[18:21], v[174:177], v[198:201], v[18:21]
	v_mfma_f32_16x16x32_bf16 v[4:7], v[166:169], v[206:209], v[4:7]
	v_mfma_f32_16x16x32_bf16 v[0:3], v[174:177], v[206:209], v[0:3]
	s_barrier
	s_add_i32 s90, s90, 2
	s_add_u32 s38, s38, 0x100
	s_addc_u32 s39, s39, 0
	s_add_u32 s0, s0, 0x100
	s_addc_u32 s1, s1, 0
	s_cmp_gt_u32 s90, 61
	s_cbranch_scc0 .LBB0_558
	s_and_b64 vcc, exec, s[18:19]
	s_cbranch_vccz .LBB0_561
	s_barrier

; #define PG8_STAGEA(bufoff, gbase, voff) PG8_STAGE_X(bufoff, gbase, voff, AUXA)
; #define PG8_STR(x) PG8_STR2(x)
;     ...
;         const bool has_next = S.next(ui + 1, nxt);
;         const char* nA = has_next ? (const char*)g.A + (size_t)nxt.pm * tstepA : cA; const char* nB = has_next ? (const char*)g.Bt + (size_t)nxt.pn * tstepB : cB;
;         int t0 = 0;
;         if constexpr (SP2 && GEMM_RELAX == 1) { if (ui > 0) {
;             const char* a1 = cA + kstepA; const char* a2 = cA + 2 * kstepA; const char* b2 = cB + 2 * kstepB; const char* a3 = a2 + kstepA; const char* b3 = b2 + kstepB;
;             PG8_LDB(B0, 0, 0); PG8_LDB(B1, 0, 1); PG8_SCHED; PG8_LDA(At, 0, 0); PG8_STAGEA(PG8_SA(1, 1), a1 + hstepA, voffA);
;             PG8_WAIT_V(24); PG8_WAIT_L(0); PG8_BAR; PG8_MMA(0, 0, At, B0); PG8_MMA(0, 1, At, B1); PG8_BAR; PG8_SCHED;
;             PG8_LDA(At, 0, 1); PG8_STAGEB(PG8_SB(0, 0), b2, voffB); PG8_STAGEB(PG8_SB(0, 1), b2 + hstepB, voffB); PG8_STAGEA(PG8_SA(0, 0), a2, voffA);
;             PG8_WAIT_V(24); PG8_WAIT_L(0); PG8_BAR; PG8_MMA(1, 0, At, B0); PG8_MMA(1, 1, At, B1); PG8_BAR; PG8_SCHED;
;             PG8_LDB(B0, 1, 0); PG8_LDB(B1, 1, 1); PG8_SCHED; PG8_LDA(At, 1, 0); PG8_STAGEA(PG8_SA(0, 1), a2 + hstepA, voffA);
;             PG8_WAIT_V(8); PG8_WAIT_L(0); PG8_BAR; PG8_MMA(0, 0, At, B0); PG8_MMA(0, 1, At, B1); PG8_BAR; PG8_SCHED;
;             PG8_LDA(At, 1, 1); PG8_STAGEB(PG8_SB(1, 0), b3, voffB); PG8_STAGEB(PG8_SB(1, 1), b3 + hstepB, voffB); PG8_STAGEA(PG8_SA(1, 0), a3, voffA);
;             PG8_WAIT_V(8); PG8_WAIT_L(0); PG8_BAR; PG8_MMA(1, 0, At, B0); PG8_MMA(1, 1, At, B1); PG8_BAR; PG8_SCHED;
;             t0 = 2; } }
;     ...
;         asm volatile(".p2align " PG8_STR(GEMM_LOOP_ALIGN) ::: "memory");
;     ...
;         for (int t = t0; t < nt; t += 2) {
;             const bool last = (t == nt - 2);
;             const char* a1 = cA + (size_t)(t + 1) * kstepA;
;             const char* a2 = last ? nA : cA + (size_t)(t + 2) * kstepA; const char* b2 = last ? nB : cB + (size_t)(t + 2) * kstepB;
;             const char* a3 = a2 + kstepA; const char* b3 = b2 + kstepB;
;             if (last && has_next) S.a_ready(nxt);
;             if constexpr (SP2) {
;             PG8_LDB(B0, 0, 0); PG8_LDB(B1, 0, 1); PG8_SCHED; PG8_LDA(At, 0, 0); PG8_STAGEA(PG8_SA(1, 1), a1 + hstepA, voffA);
;     ...
;             const int relax = __builtin_amdgcn_readfirstlane((t == 0 && ui > 0) ? 1 : 0);
.LBB0_711:
	s_ashr_i32 s25, s24, 31
	s_lshl_b64 s[0:1], s[24:25], 21
	s_add_u32 s26, s56, s0
	s_addc_u32 s27, s57, s1
	s_and_b64 s[0:1], s[10:11], exec
	s_cselect_b32 s0, s27, s13
	s_cselect_b32 s1, s26, s12
	s_ashr_i32 s23, s22, 31
	s_lshl_b64 s[6:7], s[22:23], 21
	s_add_u32 s36, s51, s6
	s_addc_u32 s37, s68, s7
	s_and_b64 s[6:7], s[10:11], exec
	s_cselect_b32 s23, s37, s43
	s_cselect_b32 s25, s36, s42
	s_add_u32 s40, s12, 0x100080
	s_addc_u32 s41, s13, 0
	s_add_u32 s12, s42, 0x100
	s_addc_u32 s13, s43, 0
	s_mov_b32 s39, -2
	s_add_u32 s6, s40, 0xfff00080
	s_addc_u32 s7, s41, -1
	s_add_i32 s95, 0, 0x10000
	s_cmp_eq_u32 s39, 60
	s_cselect_b32 s43, s0, s7
	s_cselect_b32 s42, s1, s6
	v_add_u32_e32 v144, s95, v146
	s_cselect_b32 s17, s23, s13
	s_cselect_b32 s16, s25, s12
	s_add_i32 vcc_lo, 0, 0x14000
	ds_read_b128 v[150:153], v144
	ds_read_b128 v[154:157], v144 offset:1024
	ds_read_b128 v[158:161], v144 offset:2048
	ds_read_b128 v[162:165], v144 offset:3072
	v_add_u32_e32 v144, vcc_lo, v146
	ds_read_b128 v[166:169], v144
	ds_read_b128 v[170:173], v144 offset:1024
	ds_read_b128 v[174:177], v144 offset:2048
	ds_read_b128 v[178:181], v144 offset:3072
	v_lshl_add_u64 v[144:145], s[40:41], 0, v[140:141]
	s_add_i32 m0, s69, 0xc000
	ds_read_b128 v[182:185], v148
	ds_read_b128 v[186:189], v148 offset:1024
	ds_read_b128 v[190:193], v148 offset:2048
	ds_read_b128 v[194:197], v148 offset:3072
	ds_read_b128 v[198:201], v148 offset:4096
	ds_read_b128 v[202:205], v148 offset:5120
	ds_read_b128 v[206:209], v148 offset:6144
	ds_read_b128 v[210:213], v148 offset:7168
	global_load_lds_dwordx4 v[144:145], off
	v_lshl_add_u64 v[144:145], s[40:41], 0, v[142:143]
	s_add_i32 m0, s69, 0xe000
	s_nop 0
	global_load_lds_dwordx4 v[144:145], off
	s_waitcnt vmcnt(8)
	s_waitcnt lgkmcnt(0)
	s_nop 0
	s_barrier
	v_mfma_f32_16x16x32_bf16 v[126:129], v[150:153], v[182:185], 0
	v_mfma_f32_16x16x32_bf16 v[122:125], v[158:161], v[182:185], 0
	v_mfma_f32_16x16x32_bf16 v[110:113], v[150:153], v[190:193], 0
	v_mfma_f32_16x16x32_bf16 v[106:109], v[158:161], v[190:193], 0
	v_mfma_f32_16x16x32_bf16 v[94:97], v[150:153], v[198:201], 0
	v_mfma_f32_16x16x32_bf16 v[90:93], v[158:161], v[198:201], 0
	v_mfma_f32_16x16x32_bf16 v[78:81], v[150:153], v[206:209], 0
	v_mfma_f32_16x16x32_bf16 v[74:77], v[158:161], v[206:209], 0
	v_mfma_f32_16x16x32_bf16 v[126:129], v[154:157], v[186:189], v[126:129]
	v_mfma_f32_16x16x32_bf16 v[122:125], v[162:165], v[186:189], v[122:125]
	v_mfma_f32_16x16x32_bf16 v[110:113], v[154:157], v[194:197], v[110:113]
	v_mfma_f32_16x16x32_bf16 v[106:109], v[162:165], v[194:197], v[106:109]
	v_mfma_f32_16x16x32_bf16 v[94:97], v[154:157], v[202:205], v[94:97]
	v_mfma_f32_16x16x32_bf16 v[90:93], v[162:165], v[202:205], v[90:93]
	v_mfma_f32_16x16x32_bf16 v[78:81], v[154:157], v[210:213], v[78:81]
	v_mfma_f32_16x16x32_bf16 v[74:77], v[162:165], v[210:213], v[74:77]
	v_mfma_f32_16x16x32_bf16 v[118:121], v[166:169], v[182:185], 0
	v_mfma_f32_16x16x32_bf16 v[114:117], v[174:177], v[182:185], 0
	v_mfma_f32_16x16x32_bf16 v[102:105], v[166:169], v[190:193], 0
	v_mfma_f32_16x16x32_bf16 v[98:101], v[174:177], v[190:193], 0
	v_mfma_f32_16x16x32_bf16 v[86:89], v[166:169], v[198:201], 0
	v_mfma_f32_16x16x32_bf16 v[82:85], v[174:177], v[198:201], 0
	v_mfma_f32_16x16x32_bf16 v[70:73], v[166:169], v[206:209], 0
	v_mfma_f32_16x16x32_bf16 v[66:69], v[174:177], v[206:209], 0
	v_mfma_f32_16x16x32_bf16 v[118:121], v[170:173], v[186:189], v[118:121]
	v_mfma_f32_16x16x32_bf16 v[114:117], v[178:181], v[186:189], v[114:117]
	v_mfma_f32_16x16x32_bf16 v[102:105], v[170:173], v[194:197], v[102:105]
	v_mfma_f32_16x16x32_bf16 v[98:101], v[178:181], v[194:197], v[98:101]
	v_mfma_f32_16x16x32_bf16 v[86:89], v[170:173], v[202:205], v[86:89]
	v_mfma_f32_16x16x32_bf16 v[82:85], v[178:181], v[202:205], v[82:85]
	v_mfma_f32_16x16x32_bf16 v[70:73], v[170:173], v[210:213], v[70:73]
	v_mfma_f32_16x16x32_bf16 v[66:69], v[178:181], v[210:213], v[66:69]
	s_barrier
	s_add_i32 s6, s95, s50
	v_lshl_add_u64 v[144:145], s[16:17], 0, v[134:135]
	s_mov_b32 m0, s6
	ds_read_b128 v[182:185], v148 offset:16384
	ds_read_b128 v[186:189], v148 offset:17408
	ds_read_b128 v[190:193], v148 offset:18432
	ds_read_b128 v[194:197], v148 offset:19456
	ds_read_b128 v[198:201], v148 offset:20480
	ds_read_b128 v[202:205], v148 offset:21504
	ds_read_b128 v[206:209], v148 offset:22528
	ds_read_b128 v[210:213], v148 offset:23552
	global_load_lds_dwordx4 v[144:145], off
	s_add_i32 m0, s6, 0x2000
	s_add_u32 s6, s16, 0x100000
	v_lshl_add_u64 v[214:215], s[16:17], 0, v[130:131]
	s_addc_u32 s7, s17, 0
	s_add_i32 s95, vcc_lo, s50
	global_load_lds_dwordx4 v[214:215], off
	v_lshl_add_u64 v[216:217], s[6:7], 0, v[134:135]
	s_mov_b32 m0, s95
	v_lshl_add_u64 v[218:219], s[42:43], 0, v[132:133]
	global_load_lds_dwordx4 v[216:217], off
	v_lshl_add_u64 v[216:217], s[6:7], 0, v[130:131]
	s_add_i32 m0, s95, 0x2000
	s_nop 0
	global_load_lds_dwordx4 v[216:217], off
	v_lshl_add_u64 v[216:217], s[42:43], 0, v[136:137]
	s_mov_b32 m0, s69
	s_nop 0
	global_load_lds_dwordx4 v[216:217], off
	s_mov_b32 m0, s72
	s_nop 0
	global_load_lds_dwordx4 v[218:219], off
	s_waitcnt vmcnt(8)
	s_waitcnt lgkmcnt(0)
	s_barrier
; #define PG8_STAGEA(bufoff, gbase, voff) PG8_STAGE_X(bufoff, gbase, voff, AUXA)
; #define PG8_LDA(dst, b, h) do { _Pragma("unroll") for (int m = 0; m < 4; ++m) _Pragma("unroll") for (int k = 0; k < 2; ++k) dst[m][k] = *(const PG8_LAS bf16x8*)(lds + PG8_SA(b, h) + aoff + m * 2048 + k * 1024); } while (0)
; #define PG8_LDB(dst, b, h) do { _Pragma("unroll") for (int n = 0; n < 2; ++n) _Pragma("unroll") for (int k = 0; k < 2; ++k) dst[n][k] = *(const PG8_LAS bf16x8*)(lds + PG8_SB(b, h) + boff + n * 2048 + k * 1024); } while (0)
; #define PG8_MMA(ai, bj, At, Bt) do { if (GEMM_PRIO_MODE == 0) __builtin_amdgcn_s_setprio(1); PG8_MMA_LOOPS \
;         acc[ai][bj][m][n] = __builtin_amdgcn_mfma_f32_16x16x32_bf16(Bt[n][k], At[m][k], acc[ai][bj][m][n], 0, 0, 0); if (GEMM_PRIO_MODE == 0) __builtin_amdgcn_s_setprio(0); } while (0)
; #define PG8_WAIT_V(n) asm volatile("s_waitcnt vmcnt(" #n ")" ::: "memory")
; #define PG8_WAIT_VR(n, nr, flag) asm volatile("s_cmp_eq_u32 %0, 0\n\ts_cbranch_scc1 .Lpg8s%=\n\ts_waitcnt vmcnt(" #nr ")\n\ts_branch .Lpg8d%=\n.Lpg8s%=:\n\ts_waitcnt vmcnt(" #n ")\n.Lpg8d%=:" :: "s"(flag) : "memory", "scc")
; #define PG8_WAIT_L(n) asm volatile("s_waitcnt lgkmcnt(" #n ")" ::: "memory")
; #define PG8_BAR __builtin_amdgcn_s_barrier()
; #define PG8_SCHED __builtin_amdgcn_sched_barrier(0)
;     ...
;             PG8_WAIT_VR(8, 24, relax); PG8_WAIT_L(0); PG8_BAR; PG8_MMA(1, 0, At, B0); PG8_MMA(1, 1, At, B1); PG8_BAR; PG8_SCHED;
;     ...
;             PG8_WAIT_V(8); PG8_WAIT_L(0); PG8_BAR; PG8_MMA(1, 0, At, B0); PG8_MMA(1, 1, At, B1); PG8_BAR; PG8_SCHED;
;     ...
;             PG8_LDB(B0, 1, 0); PG8_LDB(B1, 1, 1); PG8_SCHED; PG8_LDA(At, 1, 0); PG8_STAGEA(PG8_SA(0, 1), a2 + hstepA, voffA);
;             PG8_WAIT_V(8); PG8_WAIT_L(0); PG8_BAR; PG8_MMA(0, 0, At, B0); PG8_MMA(0, 1, At, B1); PG8_BAR; PG8_SCHED;
	v_mfma_f32_16x16x32_bf16 v[62:65], v[150:153], v[182:185], 0
	v_mfma_f32_16x16x32_bf16 v[58:61], v[158:161], v[182:185], 0
	v_mfma_f32_16x16x32_bf16 v[46:49], v[150:153], v[190:193], 0
	v_mfma_f32_16x16x32_bf16 v[42:45], v[158:161], v[190:193], 0
	v_mfma_f32_16x16x32_bf16 v[30:33], v[150:153], v[198:201], 0
	v_mfma_f32_16x16x32_bf16 v[26:29], v[158:161], v[198:201], 0
	v_mfma_f32_16x16x32_bf16 v[12:15], v[150:153], v[206:209], 0
	v_mfma_f32_16x16x32_bf16 v[8:11], v[158:161], v[206:209], 0
	v_mfma_f32_16x16x32_bf16 v[62:65], v[154:157], v[186:189], v[62:65]
	v_mfma_f32_16x16x32_bf16 v[58:61], v[162:165], v[186:189], v[58:61]
	v_mfma_f32_16x16x32_bf16 v[46:49], v[154:157], v[194:197], v[46:49]
	v_mfma_f32_16x16x32_bf16 v[42:45], v[162:165], v[194:197], v[42:45]
	v_mfma_f32_16x16x32_bf16 v[30:33], v[154:157], v[202:205], v[30:33]
	v_mfma_f32_16x16x32_bf16 v[26:29], v[162:165], v[202:205], v[26:29]
	v_mfma_f32_16x16x32_bf16 v[12:15], v[154:157], v[210:213], v[12:15]
	v_mfma_f32_16x16x32_bf16 v[8:11], v[162:165], v[210:213], v[8:11]
	v_mfma_f32_16x16x32_bf16 v[54:57], v[166:169], v[182:185], 0
	v_mfma_f32_16x16x32_bf16 v[50:53], v[174:177], v[182:185], 0
	v_mfma_f32_16x16x32_bf16 v[38:41], v[166:169], v[190:193], 0
	v_mfma_f32_16x16x32_bf16 v[34:37], v[174:177], v[190:193], 0
	v_mfma_f32_16x16x32_bf16 v[22:25], v[166:169], v[198:201], 0
	v_mfma_f32_16x16x32_bf16 v[18:21], v[174:177], v[198:201], 0
	v_mfma_f32_16x16x32_bf16 v[4:7], v[166:169], v[206:209], 0
	v_mfma_f32_16x16x32_bf16 v[0:3], v[174:177], v[206:209], 0
	v_mfma_f32_16x16x32_bf16 v[54:57], v[170:173], v[186:189], v[54:57]
	v_mfma_f32_16x16x32_bf16 v[50:53], v[178:181], v[186:189], v[50:53]
	v_mfma_f32_16x16x32_bf16 v[38:41], v[170:173], v[194:197], v[38:41]
	v_mfma_f32_16x16x32_bf16 v[34:37], v[178:181], v[194:197], v[34:37]
	v_mfma_f32_16x16x32_bf16 v[22:25], v[170:173], v[202:205], v[22:25]
	v_mfma_f32_16x16x32_bf16 v[18:21], v[178:181], v[202:205], v[18:21]
	v_mfma_f32_16x16x32_bf16 v[4:7], v[170:173], v[210:213], v[4:7]
	v_mfma_f32_16x16x32_bf16 v[0:3], v[178:181], v[210:213], v[0:3]
	s_barrier
	s_add_i32 s95, 0, 0x18000
	v_add_u32_e32 v149, s95, v146
	s_add_i32 vcc_lo, 0, 0x1c000
	ds_read_b128 v[150:153], v149
	ds_read_b128 v[154:157], v149 offset:1024
	ds_read_b128 v[158:161], v149 offset:2048
	ds_read_b128 v[162:165], v149 offset:3072
	v_add_u32_e32 v149, vcc_lo, v146
	ds_read_b128 v[166:169], v149
	ds_read_b128 v[170:173], v149 offset:1024
	ds_read_b128 v[174:177], v149 offset:2048
	ds_read_b128 v[178:181], v149 offset:3072
	s_add_u32 s6, s42, 0x100000
	s_addc_u32 s7, s43, 0
	s_mov_b32 m0, s73
	v_lshl_add_u64 v[220:221], s[6:7], 0, v[136:137]
	ds_read_b128 v[182:185], v148 offset:32768
	ds_read_b128 v[186:189], v148 offset:33792
	ds_read_b128 v[190:193], v148 offset:34816
	ds_read_b128 v[194:197], v148 offset:35840
	ds_read_b128 v[198:201], v148 offset:36864
	ds_read_b128 v[202:205], v148 offset:37888
	ds_read_b128 v[206:209], v148 offset:38912
	ds_read_b128 v[210:213], v148 offset:39936
	global_load_lds_dwordx4 v[220:221], off
	v_lshl_add_u64 v[220:221], s[6:7], 0, v[132:133]
	s_mov_b32 m0, s82
	s_nop 0
	global_load_lds_dwordx4 v[220:221], off
	s_waitcnt vmcnt(8)
	s_waitcnt lgkmcnt(0)
	s_nop 0
	s_nop 0
	s_barrier
	v_mfma_f32_16x16x32_bf16 v[126:129], v[150:153], v[182:185], v[126:129]
	v_mfma_f32_16x16x32_bf16 v[122:125], v[158:161], v[182:185], v[122:125]
	v_mfma_f32_16x16x32_bf16 v[110:113], v[150:153], v[190:193], v[110:113]
	v_mfma_f32_16x16x32_bf16 v[106:109], v[158:161], v[190:193], v[106:109]
	v_mfma_f32_16x16x32_bf16 v[94:97], v[150:153], v[198:201], v[94:97]
	v_mfma_f32_16x16x32_bf16 v[90:93], v[158:161], v[198:201], v[90:93]
	v_mfma_f32_16x16x32_bf16 v[78:81], v[150:153], v[206:209], v[78:81]
	v_mfma_f32_16x16x32_bf16 v[74:77], v[158:161], v[206:209], v[74:77]
	v_mfma_f32_16x16x32_bf16 v[126:129], v[154:157], v[186:189], v[126:129]
	v_mfma_f32_16x16x32_bf16 v[122:125], v[162:165], v[186:189], v[122:125]
	v_mfma_f32_16x16x32_bf16 v[110:113], v[154:157], v[194:197], v[110:113]
	v_mfma_f32_16x16x32_bf16 v[106:109], v[162:165], v[194:197], v[106:109]
	v_mfma_f32_16x16x32_bf16 v[94:97], v[154:157], v[202:205], v[94:97]
	v_mfma_f32_16x16x32_bf16 v[90:93], v[162:165], v[202:205], v[90:93]
	v_mfma_f32_16x16x32_bf16 v[78:81], v[154:157], v[210:213], v[78:81]
	v_mfma_f32_16x16x32_bf16 v[74:77], v[162:165], v[210:213], v[74:77]
	v_mfma_f32_16x16x32_bf16 v[118:121], v[166:169], v[182:185], v[118:121]
	v_mfma_f32_16x16x32_bf16 v[114:117], v[174:177], v[182:185], v[114:117]
	v_mfma_f32_16x16x32_bf16 v[102:105], v[166:169], v[190:193], v[102:105]
	v_mfma_f32_16x16x32_bf16 v[98:101], v[174:177], v[190:193], v[98:101]
	v_mfma_f32_16x16x32_bf16 v[86:89], v[166:169], v[198:201], v[86:89]
	v_mfma_f32_16x16x32_bf16 v[82:85], v[174:177], v[198:201], v[82:85]
	v_mfma_f32_16x16x32_bf16 v[70:73], v[166:169], v[206:209], v[70:73]
	v_mfma_f32_16x16x32_bf16 v[66:69], v[174:177], v[206:209], v[66:69]
	v_mfma_f32_16x16x32_bf16 v[118:121], v[170:173], v[186:189], v[118:121]
	v_mfma_f32_16x16x32_bf16 v[114:117], v[178:181], v[186:189], v[114:117]
	v_mfma_f32_16x16x32_bf16 v[102:105], v[170:173], v[194:197], v[102:105]
	v_mfma_f32_16x16x32_bf16 v[98:101], v[178:181], v[194:197], v[98:101]
	v_mfma_f32_16x16x32_bf16 v[86:89], v[170:173], v[202:205], v[86:89]
	v_mfma_f32_16x16x32_bf16 v[82:85], v[178:181], v[202:205], v[82:85]
	v_mfma_f32_16x16x32_bf16 v[70:73], v[170:173], v[210:213], v[70:73]
	v_mfma_f32_16x16x32_bf16 v[66:69], v[178:181], v[210:213], v[66:69]
	s_barrier
; #define PG8_STAGEA(bufoff, gbase, voff) PG8_STAGE_X(bufoff, gbase, voff, AUXA)
; #define PG8_STAGEB(bufoff, gbase, voff) PG8_STAGE_X(bufoff, gbase, voff, AUXB)
; #define PG8_LDA(dst, b, h) do { _Pragma("unroll") for (int m = 0; m < 4; ++m) _Pragma("unroll") for (int k = 0; k < 2; ++k) dst[m][k] = *(const PG8_LAS bf16x8*)(lds + PG8_SA(b, h) + aoff + m * 2048 + k * 1024); } while (0)
; #define PG8_LDB(dst, b, h) do { _Pragma("unroll") for (int n = 0; n < 2; ++n) _Pragma("unroll") for (int k = 0; k < 2; ++k) dst[n][k] = *(const PG8_LAS bf16x8*)(lds + PG8_SB(b, h) + boff + n * 2048 + k * 1024); } while (0)
; #define PG8_MMA(ai, bj, At, Bt) do { if (GEMM_PRIO_MODE == 0) __builtin_amdgcn_s_setprio(1); PG8_MMA_LOOPS \
;         acc[ai][bj][m][n] = __builtin_amdgcn_mfma_f32_16x16x32_bf16(Bt[n][k], At[m][k], acc[ai][bj][m][n], 0, 0, 0); if (GEMM_PRIO_MODE == 0) __builtin_amdgcn_s_setprio(0); } while (0)
; #define PG8_WAIT_V(n) asm volatile("s_waitcnt vmcnt(" #n ")" ::: "memory")
; #define PG8_WAIT_L(n) asm volatile("s_waitcnt lgkmcnt(" #n ")" ::: "memory")
; #define PG8_BAR __builtin_amdgcn_s_barrier()
; #define PG8_SCHED __builtin_amdgcn_sched_barrier(0)
;     ...
;         for (int t = t0; t < nt; t += 2) {
;             const bool last = (t == nt - 2);
;             const char* a1 = cA + (size_t)(t + 1) * kstepA;
;             const char* a2 = last ? nA : cA + (size_t)(t + 2) * kstepA; const char* b2 = last ? nB : cB + (size_t)(t + 2) * kstepB;
;             const char* a3 = a2 + kstepA; const char* b3 = b2 + kstepB;
;             if (last && has_next) S.a_ready(nxt);
;             if constexpr (SP2) {
;             PG8_LDB(B0, 0, 0); PG8_LDB(B1, 0, 1); PG8_SCHED; PG8_LDA(At, 0, 0); PG8_STAGEA(PG8_SA(1, 1), a1 + hstepA, voffA);
;     ...
;             PG8_LDA(At, 1, 1); PG8_STAGEB(PG8_SB(1, 0), b3, voffB); PG8_STAGEB(PG8_SB(1, 1), b3 + hstepB, voffB); PG8_STAGEA(PG8_SA(1, 0), a3, voffA);
;             PG8_WAIT_V(8); PG8_WAIT_L(0); PG8_BAR; PG8_MMA(1, 0, At, B0); PG8_MMA(1, 1, At, B1); PG8_BAR; PG8_SCHED;
	s_add_i32 s6, s95, s50
	v_lshl_add_u64 v[144:145], v[144:145], 0, s[86:87]
	s_mov_b32 m0, s6
	ds_read_b128 v[182:185], v148 offset:49152
	ds_read_b128 v[186:189], v148 offset:50176
	ds_read_b128 v[190:193], v148 offset:51200
	ds_read_b128 v[194:197], v148 offset:52224
	ds_read_b128 v[198:201], v148 offset:53248
	ds_read_b128 v[202:205], v148 offset:54272
	ds_read_b128 v[206:209], v148 offset:55296
	ds_read_b128 v[210:213], v148 offset:56320
	global_load_lds_dwordx4 v[144:145], off
	s_add_i32 m0, s6, 0x2000
	s_add_u32 s6, s16, 0x100080
	v_lshl_add_u64 v[144:145], v[214:215], 0, s[86:87]
	s_addc_u32 s7, s17, 0
	s_add_i32 s16, vcc_lo, s50
	global_load_lds_dwordx4 v[144:145], off
	v_lshl_add_u64 v[144:145], s[6:7], 0, v[134:135]
	s_mov_b32 m0, s16
	s_nop 0
	global_load_lds_dwordx4 v[144:145], off
	v_lshl_add_u64 v[144:145], s[6:7], 0, v[130:131]
	s_add_i32 m0, s16, 0x2000
	s_nop 0
	global_load_lds_dwordx4 v[144:145], off
	v_lshl_add_u64 v[144:145], v[216:217], 0, s[86:87]
	s_mov_b32 m0, s83
	s_nop 0
	global_load_lds_dwordx4 v[144:145], off
	v_lshl_add_u64 v[144:145], v[218:219], 0, s[86:87]
	s_mov_b32 m0, s90
	s_nop 0
	global_load_lds_dwordx4 v[144:145], off
	s_waitcnt vmcnt(8)
	s_waitcnt lgkmcnt(0)
	s_nop 0
	s_nop 0
	s_nop 0
	s_barrier
	v_mfma_f32_16x16x32_bf16 v[62:65], v[150:153], v[182:185], v[62:65]
	v_mfma_f32_16x16x32_bf16 v[58:61], v[158:161], v[182:185], v[58:61]
	v_mfma_f32_16x16x32_bf16 v[46:49], v[150:153], v[190:193], v[46:49]
	v_mfma_f32_16x16x32_bf16 v[42:45], v[158:161], v[190:193], v[42:45]
	v_mfma_f32_16x16x32_bf16 v[30:33], v[150:153], v[198:201], v[30:33]
	v_mfma_f32_16x16x32_bf16 v[26:29], v[158:161], v[198:201], v[26:29]
	v_mfma_f32_16x16x32_bf16 v[12:15], v[150:153], v[206:209], v[12:15]
	v_mfma_f32_16x16x32_bf16 v[8:11], v[158:161], v[206:209], v[8:11]
	v_mfma_f32_16x16x32_bf16 v[62:65], v[154:157], v[186:189], v[62:65]
	v_mfma_f32_16x16x32_bf16 v[58:61], v[162:165], v[186:189], v[58:61]
	v_mfma_f32_16x16x32_bf16 v[46:49], v[154:157], v[194:197], v[46:49]
	v_mfma_f32_16x16x32_bf16 v[42:45], v[162:165], v[194:197], v[42:45]
	v_mfma_f32_16x16x32_bf16 v[30:33], v[154:157], v[202:205], v[30:33]
	v_mfma_f32_16x16x32_bf16 v[26:29], v[162:165], v[202:205], v[26:29]
	v_mfma_f32_16x16x32_bf16 v[12:15], v[154:157], v[210:213], v[12:15]
	v_mfma_f32_16x16x32_bf16 v[8:11], v[162:165], v[210:213], v[8:11]
	v_mfma_f32_16x16x32_bf16 v[54:57], v[166:169], v[182:185], v[54:57]
	v_mfma_f32_16x16x32_bf16 v[50:53], v[174:177], v[182:185], v[50:53]
	v_mfma_f32_16x16x32_bf16 v[38:41], v[166:169], v[190:193], v[38:41]
	v_mfma_f32_16x16x32_bf16 v[34:37], v[174:177], v[190:193], v[34:37]
	v_mfma_f32_16x16x32_bf16 v[22:25], v[166:169], v[198:201], v[22:25]
	v_mfma_f32_16x16x32_bf16 v[18:21], v[174:177], v[198:201], v[18:21]
	v_mfma_f32_16x16x32_bf16 v[4:7], v[166:169], v[206:209], v[4:7]
	v_mfma_f32_16x16x32_bf16 v[0:3], v[174:177], v[206:209], v[0:3]
	v_mfma_f32_16x16x32_bf16 v[54:57], v[170:173], v[186:189], v[54:57]
	v_mfma_f32_16x16x32_bf16 v[50:53], v[178:181], v[186:189], v[50:53]
	v_mfma_f32_16x16x32_bf16 v[38:41], v[170:173], v[194:197], v[38:41]
	v_mfma_f32_16x16x32_bf16 v[34:37], v[178:181], v[194:197], v[34:37]
	v_mfma_f32_16x16x32_bf16 v[22:25], v[170:173], v[202:205], v[22:25]
	v_mfma_f32_16x16x32_bf16 v[18:21], v[178:181], v[202:205], v[18:21]
	v_mfma_f32_16x16x32_bf16 v[4:7], v[170:173], v[210:213], v[4:7]
	v_mfma_f32_16x16x32_bf16 v[0:3], v[178:181], v[210:213], v[0:3]
	s_barrier
	s_add_i32 s39, s39, 2
	s_add_u32 s40, s40, 0x100
	s_addc_u32 s41, s41, 0
	s_add_u32 s12, s12, 0x100
	s_addc_u32 s13, s13, 0
	v_add_u32_e32 v222, 0x10000, v146
.LBB0_712:
	s_add_u32 s6, s40, 0xfff00080
	s_addc_u32 s7, s41, -1
	s_add_i32 s95, 0, 0x10000
	s_cmp_eq_u32 s39, 60
	s_cselect_b32 s43, s0, s7
	s_cselect_b32 s42, s1, s6
	s_cselect_b32 s17, s23, s13
	s_cselect_b32 s16, s25, s12
	s_add_i32 vcc_lo, 0, 0x14000
	ds_read_b128 v[150:153], v222
	ds_read_b128 v[154:157], v222 offset:1024
	ds_read_b128 v[158:161], v222 offset:2048
	ds_read_b128 v[162:165], v222 offset:3072
	ds_read_b128 v[166:169], v222 offset:16384
	ds_read_b128 v[170:173], v222 offset:17408
	ds_read_b128 v[174:177], v222 offset:18432
	ds_read_b128 v[178:181], v222 offset:19456
	s_add_i32 m0, s69, 0xc000
	ds_read_b128 v[182:185], v148
	ds_read_b128 v[186:189], v148 offset:1024
	ds_read_b128 v[190:193], v148 offset:2048
	ds_read_b128 v[194:197], v148 offset:3072
	ds_read_b128 v[198:201], v148 offset:4096
	ds_read_b128 v[202:205], v148 offset:5120
	ds_read_b128 v[206:209], v148 offset:6144
	ds_read_b128 v[210:213], v148 offset:7168
	global_load_lds_dwordx4 v140, s[40:41]
	s_add_i32 m0, s69, 0xe000
	s_nop 0
	global_load_lds_dwordx4 v142, s[40:41]
	s_waitcnt vmcnt(8)
	s_waitcnt lgkmcnt(0)
	s_barrier
; #define PG8_STAGEA(bufoff, gbase, voff) PG8_STAGE_X(bufoff, gbase, voff, AUXA)
; #define PG8_STAGEB(bufoff, gbase, voff) PG8_STAGE_X(bufoff, gbase, voff, AUXB)
; #define PG8_LDA(dst, b, h) do { _Pragma("unroll") for (int m = 0; m < 4; ++m) _Pragma("unroll") for (int k = 0; k < 2; ++k) dst[m][k] = *(const PG8_LAS bf16x8*)(lds + PG8_SA(b, h) + aoff + m * 2048 + k * 1024); } while (0)
; #define PG8_LDB(dst, b, h) do { _Pragma("unroll") for (int n = 0; n < 2; ++n) _Pragma("unroll") for (int k = 0; k < 2; ++k) dst[n][k] = *(const PG8_LAS bf16x8*)(lds + PG8_SB(b, h) + boff + n * 2048 + k * 1024); } while (0)
; #define PG8_MMA(ai, bj, At, Bt) do { if (GEMM_PRIO_MODE == 0) __builtin_amdgcn_s_setprio(1); PG8_MMA_LOOPS \
;         acc[ai][bj][m][n] = __builtin_amdgcn_mfma_f32_16x16x32_bf16(Bt[n][k], At[m][k], acc[ai][bj][m][n], 0, 0, 0); if (GEMM_PRIO_MODE == 0) __builtin_amdgcn_s_setprio(0); } while (0)
; #define PG8_WAIT_V(n) asm volatile("s_waitcnt vmcnt(" #n ")" ::: "memory")
; #define PG8_WAIT_VR(n, nr, flag) asm volatile("s_cmp_eq_u32 %0, 0\n\ts_cbranch_scc1 .Lpg8s%=\n\ts_waitcnt vmcnt(" #nr ")\n\ts_branch .Lpg8d%=\n.Lpg8s%=:\n\ts_waitcnt vmcnt(" #n ")\n.Lpg8d%=:" :: "s"(flag) : "memory", "scc")
; #define PG8_WAIT_L(n) asm volatile("s_waitcnt lgkmcnt(" #n ")" ::: "memory")
; #define PG8_BAR __builtin_amdgcn_s_barrier()
; #define PG8_SCHED __builtin_amdgcn_sched_barrier(0)
;     ...
;             PG8_LDB(B0, 0, 0); PG8_LDB(B1, 0, 1); PG8_SCHED; PG8_LDA(At, 0, 0); PG8_STAGEA(PG8_SA(1, 1), a1 + hstepA, voffA);
;     ...
;             const int relax = __builtin_amdgcn_readfirstlane((t == 0 && ui > 0) ? 1 : 0);
;             PG8_WAIT_VR(8, 24, relax); PG8_WAIT_L(0); PG8_BAR; PG8_MMA(0, 0, At, B0); PG8_MMA(0, 1, At, B1); PG8_BAR; PG8_SCHED;
;     ...
;             PG8_WAIT_V(8); PG8_WAIT_L(0); PG8_BAR; PG8_MMA(0, 0, At, B0); PG8_MMA(0, 1, At, B1); PG8_BAR; PG8_SCHED;
;     ...
;             PG8_LDA(At, 0, 1); PG8_STAGEB(PG8_SB(0, 0), b2, voffB); PG8_STAGEB(PG8_SB(0, 1), b2 + hstepB, voffB); PG8_STAGEA(PG8_SA(0, 0), a2, voffA);
;     ...
;             PG8_WAIT_VR(8, 24, relax); PG8_WAIT_L(0); PG8_BAR; PG8_MMA(1, 0, At, B0); PG8_MMA(1, 1, At, B1); PG8_BAR; PG8_SCHED;
;     ...
;             PG8_WAIT_V(8); PG8_WAIT_L(0); PG8_BAR; PG8_MMA(1, 0, At, B0); PG8_MMA(1, 1, At, B1); PG8_BAR; PG8_SCHED;
	v_mfma_f32_16x16x32_bf16 v[126:129], v[150:153], v[182:185], v[126:129]
	v_mfma_f32_16x16x32_bf16 v[122:125], v[158:161], v[182:185], v[122:125]
	v_mfma_f32_16x16x32_bf16 v[110:113], v[150:153], v[190:193], v[110:113]
	v_mfma_f32_16x16x32_bf16 v[106:109], v[158:161], v[190:193], v[106:109]
	v_mfma_f32_16x16x32_bf16 v[94:97], v[150:153], v[198:201], v[94:97]
	v_mfma_f32_16x16x32_bf16 v[90:93], v[158:161], v[198:201], v[90:93]
	v_mfma_f32_16x16x32_bf16 v[78:81], v[150:153], v[206:209], v[78:81]
	v_mfma_f32_16x16x32_bf16 v[74:77], v[158:161], v[206:209], v[74:77]
	v_mfma_f32_16x16x32_bf16 v[126:129], v[154:157], v[186:189], v[126:129]
	v_mfma_f32_16x16x32_bf16 v[122:125], v[162:165], v[186:189], v[122:125]
	v_mfma_f32_16x16x32_bf16 v[110:113], v[154:157], v[194:197], v[110:113]
	v_mfma_f32_16x16x32_bf16 v[106:109], v[162:165], v[194:197], v[106:109]
	v_mfma_f32_16x16x32_bf16 v[94:97], v[154:157], v[202:205], v[94:97]
	v_mfma_f32_16x16x32_bf16 v[90:93], v[162:165], v[202:205], v[90:93]
	v_mfma_f32_16x16x32_bf16 v[78:81], v[154:157], v[210:213], v[78:81]
	v_mfma_f32_16x16x32_bf16 v[74:77], v[162:165], v[210:213], v[74:77]
	v_mfma_f32_16x16x32_bf16 v[118:121], v[166:169], v[182:185], v[118:121]
	v_mfma_f32_16x16x32_bf16 v[114:117], v[174:177], v[182:185], v[114:117]
	v_mfma_f32_16x16x32_bf16 v[102:105], v[166:169], v[190:193], v[102:105]
	v_mfma_f32_16x16x32_bf16 v[98:101], v[174:177], v[190:193], v[98:101]
	v_mfma_f32_16x16x32_bf16 v[86:89], v[166:169], v[198:201], v[86:89]
	v_mfma_f32_16x16x32_bf16 v[82:85], v[174:177], v[198:201], v[82:85]
	v_mfma_f32_16x16x32_bf16 v[70:73], v[166:169], v[206:209], v[70:73]
	v_mfma_f32_16x16x32_bf16 v[66:69], v[174:177], v[206:209], v[66:69]
	v_mfma_f32_16x16x32_bf16 v[118:121], v[170:173], v[186:189], v[118:121]
	v_mfma_f32_16x16x32_bf16 v[114:117], v[178:181], v[186:189], v[114:117]
	v_mfma_f32_16x16x32_bf16 v[102:105], v[170:173], v[194:197], v[102:105]
	v_mfma_f32_16x16x32_bf16 v[98:101], v[178:181], v[194:197], v[98:101]
	v_mfma_f32_16x16x32_bf16 v[86:89], v[170:173], v[202:205], v[86:89]
	v_mfma_f32_16x16x32_bf16 v[82:85], v[178:181], v[202:205], v[82:85]
	v_mfma_f32_16x16x32_bf16 v[70:73], v[170:173], v[210:213], v[70:73]
	v_mfma_f32_16x16x32_bf16 v[66:69], v[178:181], v[210:213], v[66:69]
	s_barrier
	s_add_i32 s6, s95, s50
	s_mov_b32 m0, s6
	ds_read_b128 v[182:185], v148 offset:16384
	ds_read_b128 v[186:189], v148 offset:17408
	ds_read_b128 v[190:193], v148 offset:18432
	ds_read_b128 v[194:197], v148 offset:19456
	ds_read_b128 v[198:201], v148 offset:20480
	ds_read_b128 v[202:205], v148 offset:21504
	ds_read_b128 v[206:209], v148 offset:22528
	ds_read_b128 v[210:213], v148 offset:23552
	global_load_lds_dwordx4 v134, s[16:17]
	s_add_i32 m0, s6, 0x2000
	s_add_u32 s6, s16, 0x100000
	s_addc_u32 s7, s17, 0
	s_add_i32 s95, vcc_lo, s50
	global_load_lds_dwordx4 v130, s[16:17]
	s_mov_b32 m0, s95
	s_nop 0
	global_load_lds_dwordx4 v134, s[6:7]
	s_add_i32 m0, s95, 0x2000
	s_nop 0
	global_load_lds_dwordx4 v130, s[6:7]
	s_mov_b32 m0, s69
	s_nop 0
	global_load_lds_dwordx4 v136, s[42:43]
	s_mov_b32 m0, s72
	s_nop 0
	global_load_lds_dwordx4 v132, s[42:43]
	s_waitcnt vmcnt(8)
	s_waitcnt lgkmcnt(0)
	s_nop 0
	s_barrier
	v_mfma_f32_16x16x32_bf16 v[62:65], v[150:153], v[182:185], v[62:65]
	v_mfma_f32_16x16x32_bf16 v[58:61], v[158:161], v[182:185], v[58:61]
	v_mfma_f32_16x16x32_bf16 v[46:49], v[150:153], v[190:193], v[46:49]
	v_mfma_f32_16x16x32_bf16 v[42:45], v[158:161], v[190:193], v[42:45]
	v_mfma_f32_16x16x32_bf16 v[30:33], v[150:153], v[198:201], v[30:33]
	v_mfma_f32_16x16x32_bf16 v[26:29], v[158:161], v[198:201], v[26:29]
	v_mfma_f32_16x16x32_bf16 v[12:15], v[150:153], v[206:209], v[12:15]
	v_mfma_f32_16x16x32_bf16 v[8:11], v[158:161], v[206:209], v[8:11]
	v_mfma_f32_16x16x32_bf16 v[62:65], v[154:157], v[186:189], v[62:65]
	v_mfma_f32_16x16x32_bf16 v[58:61], v[162:165], v[186:189], v[58:61]
	v_mfma_f32_16x16x32_bf16 v[46:49], v[154:157], v[194:197], v[46:49]
	v_mfma_f32_16x16x32_bf16 v[42:45], v[162:165], v[194:197], v[42:45]
	v_mfma_f32_16x16x32_bf16 v[30:33], v[154:157], v[202:205], v[30:33]
	v_mfma_f32_16x16x32_bf16 v[26:29], v[162:165], v[202:205], v[26:29]
	v_mfma_f32_16x16x32_bf16 v[12:15], v[154:157], v[210:213], v[12:15]
	v_mfma_f32_16x16x32_bf16 v[8:11], v[162:165], v[210:213], v[8:11]
	v_mfma_f32_16x16x32_bf16 v[54:57], v[166:169], v[182:185], v[54:57]
	v_mfma_f32_16x16x32_bf16 v[50:53], v[174:177], v[182:185], v[50:53]
	v_mfma_f32_16x16x32_bf16 v[38:41], v[166:169], v[190:193], v[38:41]
	v_mfma_f32_16x16x32_bf16 v[34:37], v[174:177], v[190:193], v[34:37]
	v_mfma_f32_16x16x32_bf16 v[22:25], v[166:169], v[198:201], v[22:25]
	v_mfma_f32_16x16x32_bf16 v[18:21], v[174:177], v[198:201], v[18:21]
	v_mfma_f32_16x16x32_bf16 v[4:7], v[166:169], v[206:209], v[4:7]
	v_mfma_f32_16x16x32_bf16 v[0:3], v[174:177], v[206:209], v[0:3]
	v_mfma_f32_16x16x32_bf16 v[54:57], v[170:173], v[186:189], v[54:57]
	v_mfma_f32_16x16x32_bf16 v[50:53], v[178:181], v[186:189], v[50:53]
	v_mfma_f32_16x16x32_bf16 v[38:41], v[170:173], v[194:197], v[38:41]
	v_mfma_f32_16x16x32_bf16 v[34:37], v[178:181], v[194:197], v[34:37]
	v_mfma_f32_16x16x32_bf16 v[22:25], v[170:173], v[202:205], v[22:25]
	v_mfma_f32_16x16x32_bf16 v[18:21], v[178:181], v[202:205], v[18:21]
	v_mfma_f32_16x16x32_bf16 v[4:7], v[170:173], v[210:213], v[4:7]
	v_mfma_f32_16x16x32_bf16 v[0:3], v[178:181], v[210:213], v[0:3]
	s_barrier
; #define PG8_STAGEA(bufoff, gbase, voff) PG8_STAGE_X(bufoff, gbase, voff, AUXA)
; #define PG8_STAGEB(bufoff, gbase, voff) PG8_STAGE_X(bufoff, gbase, voff, AUXB)
; #define PG8_LDA(dst, b, h) do { _Pragma("unroll") for (int m = 0; m < 4; ++m) _Pragma("unroll") for (int k = 0; k < 2; ++k) dst[m][k] = *(const PG8_LAS bf16x8*)(lds + PG8_SA(b, h) + aoff + m * 2048 + k * 1024); } while (0)
; #define PG8_LDB(dst, b, h) do { _Pragma("unroll") for (int n = 0; n < 2; ++n) _Pragma("unroll") for (int k = 0; k < 2; ++k) dst[n][k] = *(const PG8_LAS bf16x8*)(lds + PG8_SB(b, h) + boff + n * 2048 + k * 1024); } while (0)
; #define PG8_MMA(ai, bj, At, Bt) do { if (GEMM_PRIO_MODE == 0) __builtin_amdgcn_s_setprio(1); PG8_MMA_LOOPS \
;         acc[ai][bj][m][n] = __builtin_amdgcn_mfma_f32_16x16x32_bf16(Bt[n][k], At[m][k], acc[ai][bj][m][n], 0, 0, 0); if (GEMM_PRIO_MODE == 0) __builtin_amdgcn_s_setprio(0); } while (0)
; #define PG8_WAIT_V(n) asm volatile("s_waitcnt vmcnt(" #n ")" ::: "memory")
; #define PG8_WAIT_L(n) asm volatile("s_waitcnt lgkmcnt(" #n ")" ::: "memory")
; #define PG8_BAR __builtin_amdgcn_s_barrier()
; #define PG8_SCHED __builtin_amdgcn_sched_barrier(0)
;     ...
;             PG8_LDB(B0, 1, 0); PG8_LDB(B1, 1, 1); PG8_SCHED; PG8_LDA(At, 1, 0); PG8_STAGEA(PG8_SA(0, 1), a2 + hstepA, voffA);
;             PG8_WAIT_V(8); PG8_WAIT_L(0); PG8_BAR; PG8_MMA(0, 0, At, B0); PG8_MMA(0, 1, At, B1); PG8_BAR; PG8_SCHED;
;             PG8_LDA(At, 1, 1); PG8_STAGEB(PG8_SB(1, 0), b3, voffB); PG8_STAGEB(PG8_SB(1, 1), b3 + hstepB, voffB); PG8_STAGEA(PG8_SA(1, 0), a3, voffA);
;             PG8_WAIT_V(8); PG8_WAIT_L(0); PG8_BAR; PG8_MMA(1, 0, At, B0); PG8_MMA(1, 1, At, B1); PG8_BAR; PG8_SCHED;
	s_add_i32 s95, 0, 0x18000
	s_add_i32 vcc_lo, 0, 0x1c000
	ds_read_b128 v[150:153], v222 offset:32768
	ds_read_b128 v[154:157], v222 offset:33792
	ds_read_b128 v[158:161], v222 offset:34816
	ds_read_b128 v[162:165], v222 offset:35840
	ds_read_b128 v[166:169], v222 offset:49152
	ds_read_b128 v[170:173], v222 offset:50176
	ds_read_b128 v[174:177], v222 offset:51200
	ds_read_b128 v[178:181], v222 offset:52224
	s_add_u32 s6, s42, 0x100000
	s_addc_u32 s7, s43, 0
	s_mov_b32 m0, s73
	ds_read_b128 v[182:185], v148 offset:32768
	ds_read_b128 v[186:189], v148 offset:33792
	ds_read_b128 v[190:193], v148 offset:34816
	ds_read_b128 v[194:197], v148 offset:35840
	ds_read_b128 v[198:201], v148 offset:36864
	ds_read_b128 v[202:205], v148 offset:37888
	ds_read_b128 v[206:209], v148 offset:38912
	ds_read_b128 v[210:213], v148 offset:39936
	global_load_lds_dwordx4 v136, s[6:7]
	s_mov_b32 m0, s82
	s_nop 0
	global_load_lds_dwordx4 v132, s[6:7]
	s_waitcnt vmcnt(8)
	s_waitcnt lgkmcnt(0)
	s_barrier
	v_mfma_f32_16x16x32_bf16 v[126:129], v[150:153], v[182:185], v[126:129]
	v_mfma_f32_16x16x32_bf16 v[122:125], v[158:161], v[182:185], v[122:125]
	v_mfma_f32_16x16x32_bf16 v[110:113], v[150:153], v[190:193], v[110:113]
	v_mfma_f32_16x16x32_bf16 v[106:109], v[158:161], v[190:193], v[106:109]
	v_mfma_f32_16x16x32_bf16 v[94:97], v[150:153], v[198:201], v[94:97]
	v_mfma_f32_16x16x32_bf16 v[90:93], v[158:161], v[198:201], v[90:93]
	v_mfma_f32_16x16x32_bf16 v[78:81], v[150:153], v[206:209], v[78:81]
	v_mfma_f32_16x16x32_bf16 v[74:77], v[158:161], v[206:209], v[74:77]
	v_mfma_f32_16x16x32_bf16 v[126:129], v[154:157], v[186:189], v[126:129]
	v_mfma_f32_16x16x32_bf16 v[122:125], v[162:165], v[186:189], v[122:125]
	v_mfma_f32_16x16x32_bf16 v[110:113], v[154:157], v[194:197], v[110:113]
	v_mfma_f32_16x16x32_bf16 v[106:109], v[162:165], v[194:197], v[106:109]
	v_mfma_f32_16x16x32_bf16 v[94:97], v[154:157], v[202:205], v[94:97]
	v_mfma_f32_16x16x32_bf16 v[90:93], v[162:165], v[202:205], v[90:93]
	v_mfma_f32_16x16x32_bf16 v[78:81], v[154:157], v[210:213], v[78:81]
	v_mfma_f32_16x16x32_bf16 v[74:77], v[162:165], v[210:213], v[74:77]
	v_mfma_f32_16x16x32_bf16 v[118:121], v[166:169], v[182:185], v[118:121]
	v_mfma_f32_16x16x32_bf16 v[114:117], v[174:177], v[182:185], v[114:117]
	v_mfma_f32_16x16x32_bf16 v[102:105], v[166:169], v[190:193], v[102:105]
	v_mfma_f32_16x16x32_bf16 v[98:101], v[174:177], v[190:193], v[98:101]
	v_mfma_f32_16x16x32_bf16 v[86:89], v[166:169], v[198:201], v[86:89]
	v_mfma_f32_16x16x32_bf16 v[82:85], v[174:177], v[198:201], v[82:85]
	v_mfma_f32_16x16x32_bf16 v[70:73], v[166:169], v[206:209], v[70:73]
	v_mfma_f32_16x16x32_bf16 v[66:69], v[174:177], v[206:209], v[66:69]
	v_mfma_f32_16x16x32_bf16 v[118:121], v[170:173], v[186:189], v[118:121]
	v_mfma_f32_16x16x32_bf16 v[114:117], v[178:181], v[186:189], v[114:117]
	v_mfma_f32_16x16x32_bf16 v[102:105], v[170:173], v[194:197], v[102:105]
	v_mfma_f32_16x16x32_bf16 v[98:101], v[178:181], v[194:197], v[98:101]
	v_mfma_f32_16x16x32_bf16 v[86:89], v[170:173], v[202:205], v[86:89]
	v_mfma_f32_16x16x32_bf16 v[82:85], v[178:181], v[202:205], v[82:85]
	v_mfma_f32_16x16x32_bf16 v[70:73], v[170:173], v[210:213], v[70:73]
	v_mfma_f32_16x16x32_bf16 v[66:69], v[178:181], v[210:213], v[66:69]
	s_barrier
	s_add_i32 s6, s95, s50
	s_mov_b32 m0, s6
	ds_read_b128 v[182:185], v148 offset:49152
	ds_read_b128 v[186:189], v148 offset:50176
	ds_read_b128 v[190:193], v148 offset:51200
	ds_read_b128 v[194:197], v148 offset:52224
	ds_read_b128 v[198:201], v148 offset:53248
	ds_read_b128 v[202:205], v148 offset:54272
	ds_read_b128 v[206:209], v148 offset:55296
	ds_read_b128 v[210:213], v148 offset:56320
	s_add_u32 s100, s16, 0x80
	s_addc_u32 s101, s17, 0
	global_load_lds_dwordx4 v134, s[100:101]
	s_add_i32 m0, s6, 0x2000
	s_add_u32 s6, s16, 0x100080
	s_addc_u32 s7, s17, 0
	s_add_i32 s16, vcc_lo, s50
	global_load_lds_dwordx4 v130, s[100:101]
	s_mov_b32 m0, s16
	s_nop 0
	global_load_lds_dwordx4 v134, s[6:7]
	s_add_i32 m0, s16, 0x2000
	s_nop 0
	global_load_lds_dwordx4 v130, s[6:7]
	s_mov_b32 m0, s83
	s_nop 0
	s_add_u32 s100, s42, 0x80
	s_addc_u32 s101, s43, 0
	global_load_lds_dwordx4 v136, s[100:101]
	s_mov_b32 m0, s90
	s_nop 0
	global_load_lds_dwordx4 v132, s[100:101]
	s_waitcnt vmcnt(8)
	s_waitcnt lgkmcnt(0)
	s_nop 0
	s_nop 0
	s_nop 0
	s_barrier
	v_mfma_f32_16x16x32_bf16 v[62:65], v[150:153], v[182:185], v[62:65]
	v_mfma_f32_16x16x32_bf16 v[58:61], v[158:161], v[182:185], v[58:61]
	v_mfma_f32_16x16x32_bf16 v[46:49], v[150:153], v[190:193], v[46:49]
	v_mfma_f32_16x16x32_bf16 v[42:45], v[158:161], v[190:193], v[42:45]
	v_mfma_f32_16x16x32_bf16 v[30:33], v[150:153], v[198:201], v[30:33]
	v_mfma_f32_16x16x32_bf16 v[26:29], v[158:161], v[198:201], v[26:29]
	v_mfma_f32_16x16x32_bf16 v[12:15], v[150:153], v[206:209], v[12:15]
	v_mfma_f32_16x16x32_bf16 v[8:11], v[158:161], v[206:209], v[8:11]
	v_mfma_f32_16x16x32_bf16 v[62:65], v[154:157], v[186:189], v[62:65]
	v_mfma_f32_16x16x32_bf16 v[58:61], v[162:165], v[186:189], v[58:61]
	v_mfma_f32_16x16x32_bf16 v[46:49], v[154:157], v[194:197], v[46:49]
	v_mfma_f32_16x16x32_bf16 v[42:45], v[162:165], v[194:197], v[42:45]
	v_mfma_f32_16x16x32_bf16 v[30:33], v[154:157], v[202:205], v[30:33]
	v_mfma_f32_16x16x32_bf16 v[26:29], v[162:165], v[202:205], v[26:29]
	v_mfma_f32_16x16x32_bf16 v[12:15], v[154:157], v[210:213], v[12:15]
	v_mfma_f32_16x16x32_bf16 v[8:11], v[162:165], v[210:213], v[8:11]
	v_mfma_f32_16x16x32_bf16 v[54:57], v[166:169], v[182:185], v[54:57]
	v_mfma_f32_16x16x32_bf16 v[50:53], v[174:177], v[182:185], v[50:53]
	v_mfma_f32_16x16x32_bf16 v[38:41], v[166:169], v[190:193], v[38:41]
	v_mfma_f32_16x16x32_bf16 v[34:37], v[174:177], v[190:193], v[34:37]
	v_mfma_f32_16x16x32_bf16 v[22:25], v[166:169], v[198:201], v[22:25]
	v_mfma_f32_16x16x32_bf16 v[18:21], v[174:177], v[198:201], v[18:21]
	v_mfma_f32_16x16x32_bf16 v[4:7], v[166:169], v[206:209], v[4:7]
	v_mfma_f32_16x16x32_bf16 v[0:3], v[174:177], v[206:209], v[0:3]
	v_mfma_f32_16x16x32_bf16 v[54:57], v[170:173], v[186:189], v[54:57]
	v_mfma_f32_16x16x32_bf16 v[50:53], v[178:181], v[186:189], v[50:53]
	v_mfma_f32_16x16x32_bf16 v[38:41], v[170:173], v[194:197], v[38:41]
	v_mfma_f32_16x16x32_bf16 v[34:37], v[178:181], v[194:197], v[34:37]
	v_mfma_f32_16x16x32_bf16 v[22:25], v[170:173], v[202:205], v[22:25]
	v_mfma_f32_16x16x32_bf16 v[18:21], v[178:181], v[202:205], v[18:21]
	v_mfma_f32_16x16x32_bf16 v[4:7], v[170:173], v[210:213], v[4:7]
	v_mfma_f32_16x16x32_bf16 v[0:3], v[178:181], v[210:213], v[0:3]
	s_barrier
	s_add_i32 s39, s39, 2
	s_add_u32 s40, s40, 0x100
	s_addc_u32 s41, s41, 0
	s_add_u32 s12, s12, 0x100
	s_addc_u32 s13, s13, 0
	s_cmp_gt_u32 s39, 61
	s_cbranch_scc0 .LBB0_712
	s_and_b64 vcc, exec, s[18:19]
	s_cbranch_vccz .LBB0_715
	s_barrier

; #define PG8_STAGEA(bufoff, gbase, voff) PG8_STAGE_X(bufoff, gbase, voff, AUXA)
; #define PG8_STR(x) PG8_STR2(x)
;     ...
;         const bool has_next = S.next(ui + 1, nxt);
;         const char* nA = has_next ? (const char*)g.A + (size_t)nxt.pm * tstepA : cA; const char* nB = has_next ? (const char*)g.Bt + (size_t)nxt.pn * tstepB : cB;
;         int t0 = 0;
;         if constexpr (SP2 && GEMM_RELAX == 1) { if (ui > 0) {
;             const char* a1 = cA + kstepA; const char* a2 = cA + 2 * kstepA; const char* b2 = cB + 2 * kstepB; const char* a3 = a2 + kstepA; const char* b3 = b2 + kstepB;
;             PG8_LDB(B0, 0, 0); PG8_LDB(B1, 0, 1); PG8_SCHED; PG8_LDA(At, 0, 0); PG8_STAGEA(PG8_SA(1, 1), a1 + hstepA, voffA);
;             PG8_WAIT_V(24); PG8_WAIT_L(0); PG8_BAR; PG8_MMA(0, 0, At, B0); PG8_MMA(0, 1, At, B1); PG8_BAR; PG8_SCHED;
;             PG8_LDA(At, 0, 1); PG8_STAGEB(PG8_SB(0, 0), b2, voffB); PG8_STAGEB(PG8_SB(0, 1), b2 + hstepB, voffB); PG8_STAGEA(PG8_SA(0, 0), a2, voffA);
;             PG8_WAIT_V(24); PG8_WAIT_L(0); PG8_BAR; PG8_MMA(1, 0, At, B0); PG8_MMA(1, 1, At, B1); PG8_BAR; PG8_SCHED;
;             PG8_LDB(B0, 1, 0); PG8_LDB(B1, 1, 1); PG8_SCHED; PG8_LDA(At, 1, 0); PG8_STAGEA(PG8_SA(0, 1), a2 + hstepA, voffA);
;             PG8_WAIT_V(8); PG8_WAIT_L(0); PG8_BAR; PG8_MMA(0, 0, At, B0); PG8_MMA(0, 1, At, B1); PG8_BAR; PG8_SCHED;
;             PG8_LDA(At, 1, 1); PG8_STAGEB(PG8_SB(1, 0), b3, voffB); PG8_STAGEB(PG8_SB(1, 1), b3 + hstepB, voffB); PG8_STAGEA(PG8_SA(1, 0), a3, voffA);
;             PG8_WAIT_V(8); PG8_WAIT_L(0); PG8_BAR; PG8_MMA(1, 0, At, B0); PG8_MMA(1, 1, At, B1); PG8_BAR; PG8_SCHED;
;             t0 = 2; } }
;     ...
;         asm volatile(".p2align " PG8_STR(GEMM_LOOP_ALIGN) ::: "memory");
;     ...
;         for (int t = t0; t < nt; t += 2) {
;             const bool last = (t == nt - 2);
;             const char* a1 = cA + (size_t)(t + 1) * kstepA;
;             const char* a2 = last ? nA : cA + (size_t)(t + 2) * kstepA; const char* b2 = last ? nB : cB + (size_t)(t + 2) * kstepB;
;             const char* a3 = a2 + kstepA; const char* b3 = b2 + kstepB;
;             if (last && has_next) S.a_ready(nxt);
;             if constexpr (SP2) {
;             PG8_LDB(B0, 0, 0); PG8_LDB(B1, 0, 1); PG8_SCHED; PG8_LDA(At, 0, 0); PG8_STAGEA(PG8_SA(1, 1), a1 + hstepA, voffA);
;     ...
;             const int relax = __builtin_amdgcn_readfirstlane((t == 0 && ui > 0) ? 1 : 0);
.LBB0_847:
	s_ashr_i32 s11, s10, 31
	s_lshl_b64 s[18:19], s[10:11], 23
	s_add_u32 s18, s62, s18
	s_addc_u32 s19, s63, s19
	s_and_b64 s[22:23], s[20:21], exec
	s_cselect_b32 s11, s19, s1
	s_cselect_b32 s73, s18, s0
	s_ashr_i32 s15, s14, 31
	s_lshl_b64 s[22:23], s[14:15], 23
	s_add_u32 s22, s12, s22
	s_addc_u32 s23, s13, s23
	s_and_b64 s[24:25], s[20:21], exec
	s_cselect_b32 s15, s23, s17
	s_cselect_b32 s78, s22, s16
	s_add_u32 s24, s0, 0xc000
	s_addc_u32 s25, s1, 0
	s_add_u32 s0, s16, 0x10000
	s_addc_u32 s1, s17, 0
	s_mov_b32 s82, -2
	s_waitcnt lgkmcnt(0)
	s_add_u32 s16, s24, 0x4000
	s_addc_u32 s17, s25, 0
	s_cmpk_eq_i32 s82, 0xfc
	s_cselect_b32 s36, s73, s16
	s_cselect_b32 s37, s11, s17
	s_cselect_b32 s16, s78, s0
	s_cselect_b32 s17, s15, s1
	s_add_u32 s26, s36, 0x8000
	s_addc_u32 s27, s37, 0
	s_add_i32 s83, 0, 0x10000
	s_add_i32 s94, 0, 0x14000
	v_add_u32_e32 v152, s83, v157
	v_add_u32_e32 v174, s94, v157
	ds_read_b128 v[130:133], v152
	ds_read_b128 v[134:137], v152 offset:1024
	ds_read_b128 v[148:151], v152 offset:2048
	ds_read_b128 v[152:155], v152 offset:3072
	ds_read_b128 v[162:165], v174
	ds_read_b128 v[166:169], v174 offset:1024
	ds_read_b128 v[170:173], v174 offset:2048
	ds_read_b128 v[174:177], v174 offset:3072
	v_lshl_add_u64 v[210:211], s[24:25], 0, v[144:145]
	s_add_i32 m0, s39, 0xc000
	ds_read_b128 v[178:181], v161
	ds_read_b128 v[182:185], v161 offset:1024
	ds_read_b128 v[186:189], v161 offset:2048
	ds_read_b128 v[190:193], v161 offset:3072
	ds_read_b128 v[194:197], v161 offset:4096
	ds_read_b128 v[198:201], v161 offset:5120
	ds_read_b128 v[202:205], v161 offset:6144
	ds_read_b128 v[206:209], v161 offset:7168
	global_load_lds_dwordx4 v[210:211], off
	v_lshl_add_u64 v[210:211], s[24:25], 0, v[146:147]
	s_add_i32 m0, s39, 0xe000
	s_nop 0
	global_load_lds_dwordx4 v[210:211], off
	s_waitcnt vmcnt(8)
	s_waitcnt lgkmcnt(0)
	s_barrier
	v_mfma_f32_16x16x32_bf16 v[126:129], v[130:133], v[178:181], 0
	v_mfma_f32_16x16x32_bf16 v[122:125], v[148:151], v[178:181], 0
	v_mfma_f32_16x16x32_bf16 v[110:113], v[130:133], v[186:189], 0
	v_mfma_f32_16x16x32_bf16 v[106:109], v[148:151], v[186:189], 0
	v_mfma_f32_16x16x32_bf16 v[94:97], v[130:133], v[194:197], 0
	v_mfma_f32_16x16x32_bf16 v[90:93], v[148:151], v[194:197], 0
	v_mfma_f32_16x16x32_bf16 v[78:81], v[130:133], v[202:205], 0
	v_mfma_f32_16x16x32_bf16 v[74:77], v[148:151], v[202:205], 0
	v_mfma_f32_16x16x32_bf16 v[126:129], v[134:137], v[182:185], v[126:129]
	v_mfma_f32_16x16x32_bf16 v[122:125], v[152:155], v[182:185], v[122:125]
	v_mfma_f32_16x16x32_bf16 v[110:113], v[134:137], v[190:193], v[110:113]
	v_mfma_f32_16x16x32_bf16 v[106:109], v[152:155], v[190:193], v[106:109]
	v_mfma_f32_16x16x32_bf16 v[94:97], v[134:137], v[198:201], v[94:97]
	v_mfma_f32_16x16x32_bf16 v[90:93], v[152:155], v[198:201], v[90:93]
	v_mfma_f32_16x16x32_bf16 v[78:81], v[134:137], v[206:209], v[78:81]
	v_mfma_f32_16x16x32_bf16 v[74:77], v[152:155], v[206:209], v[74:77]
	v_mfma_f32_16x16x32_bf16 v[118:121], v[162:165], v[178:181], 0
	v_mfma_f32_16x16x32_bf16 v[114:117], v[170:173], v[178:181], 0
	v_mfma_f32_16x16x32_bf16 v[102:105], v[162:165], v[186:189], 0
	v_mfma_f32_16x16x32_bf16 v[98:101], v[170:173], v[186:189], 0
	v_mfma_f32_16x16x32_bf16 v[86:89], v[162:165], v[194:197], 0
	v_mfma_f32_16x16x32_bf16 v[82:85], v[170:173], v[194:197], 0
	v_mfma_f32_16x16x32_bf16 v[70:73], v[162:165], v[202:205], 0
	v_mfma_f32_16x16x32_bf16 v[66:69], v[170:173], v[202:205], 0
	v_mfma_f32_16x16x32_bf16 v[118:121], v[166:169], v[182:185], v[118:121]
	v_mfma_f32_16x16x32_bf16 v[114:117], v[174:177], v[182:185], v[114:117]
	v_mfma_f32_16x16x32_bf16 v[102:105], v[166:169], v[190:193], v[102:105]
	v_mfma_f32_16x16x32_bf16 v[98:101], v[174:177], v[190:193], v[98:101]
	v_mfma_f32_16x16x32_bf16 v[86:89], v[166:169], v[198:201], v[86:89]
	v_mfma_f32_16x16x32_bf16 v[82:85], v[174:177], v[198:201], v[82:85]
	v_mfma_f32_16x16x32_bf16 v[70:73], v[166:169], v[206:209], v[70:73]
	v_mfma_f32_16x16x32_bf16 v[66:69], v[174:177], v[206:209], v[66:69]
	s_barrier
	s_add_i32 s83, s83, s38
	v_lshl_add_u64 v[210:211], s[16:17], 0, v[16:17]
	s_mov_b32 m0, s83
	ds_read_b128 v[178:181], v161 offset:16384
	ds_read_b128 v[182:185], v161 offset:17408
	ds_read_b128 v[186:189], v161 offset:18432
	ds_read_b128 v[190:193], v161 offset:19456
	ds_read_b128 v[194:197], v161 offset:20480
	ds_read_b128 v[198:201], v161 offset:21504
	ds_read_b128 v[202:205], v161 offset:22528
	ds_read_b128 v[206:209], v161 offset:23552
	global_load_lds_dwordx4 v[210:211], off
	s_add_i32 m0, s83, 0x2000
	s_add_u32 s90, s16, 0x4000
	v_lshl_add_u64 v[210:211], s[16:17], 0, v[138:139]
	s_addc_u32 s91, s17, 0
	s_add_i32 s83, s94, s38
	global_load_lds_dwordx4 v[210:211], off
	v_lshl_add_u64 v[210:211], s[90:91], 0, v[16:17]
	s_mov_b32 m0, s83
	s_nop 0
	global_load_lds_dwordx4 v[210:211], off
	v_lshl_add_u64 v[210:211], s[90:91], 0, v[138:139]
	s_add_i32 m0, s83, 0x2000
	s_nop 0
	global_load_lds_dwordx4 v[210:211], off
	v_lshl_add_u64 v[210:211], s[36:37], 0, v[142:143]
	s_mov_b32 m0, s39
	s_nop 0
	global_load_lds_dwordx4 v[210:211], off
	v_lshl_add_u64 v[210:211], s[36:37], 0, v[140:141]
	s_mov_b32 m0, s40
	s_nop 0
	global_load_lds_dwordx4 v[210:211], off
	s_waitcnt vmcnt(8)
	s_waitcnt lgkmcnt(0)
	s_nop 0
	s_barrier
; #define PG8_STAGEA(bufoff, gbase, voff) PG8_STAGE_X(bufoff, gbase, voff, AUXA)
; #define PG8_LDA(dst, b, h) do { _Pragma("unroll") for (int m = 0; m < 4; ++m) _Pragma("unroll") for (int k = 0; k < 2; ++k) dst[m][k] = *(const PG8_LAS bf16x8*)(lds + PG8_SA(b, h) + aoff + m * 2048 + k * 1024); } while (0)
; #define PG8_LDB(dst, b, h) do { _Pragma("unroll") for (int n = 0; n < 2; ++n) _Pragma("unroll") for (int k = 0; k < 2; ++k) dst[n][k] = *(const PG8_LAS bf16x8*)(lds + PG8_SB(b, h) + boff + n * 2048 + k * 1024); } while (0)
; #define PG8_MMA(ai, bj, At, Bt) do { if (GEMM_PRIO_MODE == 0) __builtin_amdgcn_s_setprio(1); PG8_MMA_LOOPS \
;         acc[ai][bj][m][n] = __builtin_amdgcn_mfma_f32_16x16x32_bf16(Bt[n][k], At[m][k], acc[ai][bj][m][n], 0, 0, 0); if (GEMM_PRIO_MODE == 0) __builtin_amdgcn_s_setprio(0); } while (0)
; #define PG8_WAIT_V(n) asm volatile("s_waitcnt vmcnt(" #n ")" ::: "memory")
; #define PG8_WAIT_VR(n, nr, flag) asm volatile("s_cmp_eq_u32 %0, 0\n\ts_cbranch_scc1 .Lpg8s%=\n\ts_waitcnt vmcnt(" #nr ")\n\ts_branch .Lpg8d%=\n.Lpg8s%=:\n\ts_waitcnt vmcnt(" #n ")\n.Lpg8d%=:" :: "s"(flag) : "memory", "scc")
; #define PG8_WAIT_L(n) asm volatile("s_waitcnt lgkmcnt(" #n ")" ::: "memory")
; #define PG8_BAR __builtin_amdgcn_s_barrier()
; #define PG8_SCHED __builtin_amdgcn_sched_barrier(0)
;     ...
;             PG8_WAIT_VR(8, 24, relax); PG8_WAIT_L(0); PG8_BAR; PG8_MMA(1, 0, At, B0); PG8_MMA(1, 1, At, B1); PG8_BAR; PG8_SCHED;
;     ...
;             PG8_WAIT_V(8); PG8_WAIT_L(0); PG8_BAR; PG8_MMA(1, 0, At, B0); PG8_MMA(1, 1, At, B1); PG8_BAR; PG8_SCHED;
;     ...
;             PG8_LDB(B0, 1, 0); PG8_LDB(B1, 1, 1); PG8_SCHED; PG8_LDA(At, 1, 0); PG8_STAGEA(PG8_SA(0, 1), a2 + hstepA, voffA);
;             PG8_WAIT_V(8); PG8_WAIT_L(0); PG8_BAR; PG8_MMA(0, 0, At, B0); PG8_MMA(0, 1, At, B1); PG8_BAR; PG8_SCHED;
	v_mfma_f32_16x16x32_bf16 v[62:65], v[130:133], v[178:181], 0
	v_mfma_f32_16x16x32_bf16 v[58:61], v[148:151], v[178:181], 0
	v_mfma_f32_16x16x32_bf16 v[46:49], v[130:133], v[186:189], 0
	v_mfma_f32_16x16x32_bf16 v[42:45], v[148:151], v[186:189], 0
	v_mfma_f32_16x16x32_bf16 v[30:33], v[130:133], v[194:197], 0
	v_mfma_f32_16x16x32_bf16 v[26:29], v[148:151], v[194:197], 0
	v_mfma_f32_16x16x32_bf16 v[12:15], v[130:133], v[202:205], 0
	v_mfma_f32_16x16x32_bf16 v[8:11], v[148:151], v[202:205], 0
	v_mfma_f32_16x16x32_bf16 v[62:65], v[134:137], v[182:185], v[62:65]
	v_mfma_f32_16x16x32_bf16 v[58:61], v[152:155], v[182:185], v[58:61]
	v_mfma_f32_16x16x32_bf16 v[46:49], v[134:137], v[190:193], v[46:49]
	v_mfma_f32_16x16x32_bf16 v[42:45], v[152:155], v[190:193], v[42:45]
	v_mfma_f32_16x16x32_bf16 v[30:33], v[134:137], v[198:201], v[30:33]
	v_mfma_f32_16x16x32_bf16 v[26:29], v[152:155], v[198:201], v[26:29]
	v_mfma_f32_16x16x32_bf16 v[12:15], v[134:137], v[206:209], v[12:15]
	v_mfma_f32_16x16x32_bf16 v[8:11], v[152:155], v[206:209], v[8:11]
	v_mfma_f32_16x16x32_bf16 v[54:57], v[162:165], v[178:181], 0
	v_mfma_f32_16x16x32_bf16 v[50:53], v[170:173], v[178:181], 0
	v_mfma_f32_16x16x32_bf16 v[38:41], v[162:165], v[186:189], 0
	v_mfma_f32_16x16x32_bf16 v[34:37], v[170:173], v[186:189], 0
	v_mfma_f32_16x16x32_bf16 v[22:25], v[162:165], v[194:197], 0
	v_mfma_f32_16x16x32_bf16 v[18:21], v[170:173], v[194:197], 0
	v_mfma_f32_16x16x32_bf16 v[4:7], v[162:165], v[202:205], 0
	v_mfma_f32_16x16x32_bf16 v[0:3], v[170:173], v[202:205], 0
	v_mfma_f32_16x16x32_bf16 v[54:57], v[166:169], v[182:185], v[54:57]
	v_mfma_f32_16x16x32_bf16 v[50:53], v[174:177], v[182:185], v[50:53]
	v_mfma_f32_16x16x32_bf16 v[38:41], v[166:169], v[190:193], v[38:41]
	v_mfma_f32_16x16x32_bf16 v[34:37], v[174:177], v[190:193], v[34:37]
	v_mfma_f32_16x16x32_bf16 v[22:25], v[166:169], v[198:201], v[22:25]
	v_mfma_f32_16x16x32_bf16 v[18:21], v[174:177], v[198:201], v[18:21]
	v_mfma_f32_16x16x32_bf16 v[4:7], v[166:169], v[206:209], v[4:7]
	v_mfma_f32_16x16x32_bf16 v[0:3], v[174:177], v[206:209], v[0:3]
	s_barrier
	s_add_i32 s83, 0, 0x18000
	s_add_i32 s90, 0, 0x1c000
	v_add_u32_e32 v152, s83, v157
	v_add_u32_e32 v174, s90, v157
	ds_read_b128 v[130:133], v152
	ds_read_b128 v[134:137], v152 offset:1024
	ds_read_b128 v[148:151], v152 offset:2048
	ds_read_b128 v[152:155], v152 offset:3072
	ds_read_b128 v[162:165], v174
	ds_read_b128 v[166:169], v174 offset:1024
	ds_read_b128 v[170:173], v174 offset:2048
	ds_read_b128 v[174:177], v174 offset:3072
	s_add_u32 s36, s36, 0x4000
	s_addc_u32 s37, s37, 0
	s_mov_b32 m0, s41
	v_lshl_add_u64 v[210:211], s[36:37], 0, v[142:143]
	ds_read_b128 v[178:181], v161 offset:32768
	ds_read_b128 v[182:185], v161 offset:33792
	ds_read_b128 v[186:189], v161 offset:34816
	ds_read_b128 v[190:193], v161 offset:35840
	ds_read_b128 v[194:197], v161 offset:36864
	ds_read_b128 v[198:201], v161 offset:37888
	ds_read_b128 v[202:205], v161 offset:38912
	ds_read_b128 v[206:209], v161 offset:39936
	global_load_lds_dwordx4 v[210:211], off
	v_lshl_add_u64 v[210:211], s[36:37], 0, v[140:141]
	s_mov_b32 m0, s42
	s_nop 0
	global_load_lds_dwordx4 v[210:211], off
	s_waitcnt vmcnt(8)
	s_waitcnt lgkmcnt(0)
	s_nop 0
	s_nop 0
	s_barrier
	v_mfma_f32_16x16x32_bf16 v[126:129], v[130:133], v[178:181], v[126:129]
	v_mfma_f32_16x16x32_bf16 v[122:125], v[148:151], v[178:181], v[122:125]
	v_mfma_f32_16x16x32_bf16 v[110:113], v[130:133], v[186:189], v[110:113]
	v_mfma_f32_16x16x32_bf16 v[106:109], v[148:151], v[186:189], v[106:109]
	v_mfma_f32_16x16x32_bf16 v[94:97], v[130:133], v[194:197], v[94:97]
	v_mfma_f32_16x16x32_bf16 v[90:93], v[148:151], v[194:197], v[90:93]
	v_mfma_f32_16x16x32_bf16 v[78:81], v[130:133], v[202:205], v[78:81]
	v_mfma_f32_16x16x32_bf16 v[74:77], v[148:151], v[202:205], v[74:77]
	v_mfma_f32_16x16x32_bf16 v[126:129], v[134:137], v[182:185], v[126:129]
	v_mfma_f32_16x16x32_bf16 v[122:125], v[152:155], v[182:185], v[122:125]
	v_mfma_f32_16x16x32_bf16 v[110:113], v[134:137], v[190:193], v[110:113]
	v_mfma_f32_16x16x32_bf16 v[106:109], v[152:155], v[190:193], v[106:109]
	v_mfma_f32_16x16x32_bf16 v[94:97], v[134:137], v[198:201], v[94:97]
	v_mfma_f32_16x16x32_bf16 v[90:93], v[152:155], v[198:201], v[90:93]
	v_mfma_f32_16x16x32_bf16 v[78:81], v[134:137], v[206:209], v[78:81]
	v_mfma_f32_16x16x32_bf16 v[74:77], v[152:155], v[206:209], v[74:77]
	v_mfma_f32_16x16x32_bf16 v[118:121], v[162:165], v[178:181], v[118:121]
	v_mfma_f32_16x16x32_bf16 v[114:117], v[170:173], v[178:181], v[114:117]
	v_mfma_f32_16x16x32_bf16 v[102:105], v[162:165], v[186:189], v[102:105]
	v_mfma_f32_16x16x32_bf16 v[98:101], v[170:173], v[186:189], v[98:101]
	v_mfma_f32_16x16x32_bf16 v[86:89], v[162:165], v[194:197], v[86:89]
	v_mfma_f32_16x16x32_bf16 v[82:85], v[170:173], v[194:197], v[82:85]
	v_mfma_f32_16x16x32_bf16 v[70:73], v[162:165], v[202:205], v[70:73]
	v_mfma_f32_16x16x32_bf16 v[66:69], v[170:173], v[202:205], v[66:69]
	v_mfma_f32_16x16x32_bf16 v[118:121], v[166:169], v[182:185], v[118:121]
	v_mfma_f32_16x16x32_bf16 v[114:117], v[174:177], v[182:185], v[114:117]
	v_mfma_f32_16x16x32_bf16 v[102:105], v[166:169], v[190:193], v[102:105]
	v_mfma_f32_16x16x32_bf16 v[98:101], v[174:177], v[190:193], v[98:101]
	v_mfma_f32_16x16x32_bf16 v[86:89], v[166:169], v[198:201], v[86:89]
	v_mfma_f32_16x16x32_bf16 v[82:85], v[174:177], v[198:201], v[82:85]
	v_mfma_f32_16x16x32_bf16 v[70:73], v[166:169], v[206:209], v[70:73]
	v_mfma_f32_16x16x32_bf16 v[66:69], v[174:177], v[206:209], v[66:69]
	s_barrier
; #define PG8_STAGEA(bufoff, gbase, voff) PG8_STAGE_X(bufoff, gbase, voff, AUXA)
; #define PG8_STAGEB(bufoff, gbase, voff) PG8_STAGE_X(bufoff, gbase, voff, AUXB)
; #define PG8_LDA(dst, b, h) do { _Pragma("unroll") for (int m = 0; m < 4; ++m) _Pragma("unroll") for (int k = 0; k < 2; ++k) dst[m][k] = *(const PG8_LAS bf16x8*)(lds + PG8_SA(b, h) + aoff + m * 2048 + k * 1024); } while (0)
; #define PG8_LDB(dst, b, h) do { _Pragma("unroll") for (int n = 0; n < 2; ++n) _Pragma("unroll") for (int k = 0; k < 2; ++k) dst[n][k] = *(const PG8_LAS bf16x8*)(lds + PG8_SB(b, h) + boff + n * 2048 + k * 1024); } while (0)
; #define PG8_MMA(ai, bj, At, Bt) do { if (GEMM_PRIO_MODE == 0) __builtin_amdgcn_s_setprio(1); PG8_MMA_LOOPS \
;         acc[ai][bj][m][n] = __builtin_amdgcn_mfma_f32_16x16x32_bf16(Bt[n][k], At[m][k], acc[ai][bj][m][n], 0, 0, 0); if (GEMM_PRIO_MODE == 0) __builtin_amdgcn_s_setprio(0); } while (0)
; #define PG8_WAIT_V(n) asm volatile("s_waitcnt vmcnt(" #n ")" ::: "memory")
; #define PG8_WAIT_L(n) asm volatile("s_waitcnt lgkmcnt(" #n ")" ::: "memory")
; #define PG8_BAR __builtin_amdgcn_s_barrier()
; #define PG8_SCHED __builtin_amdgcn_sched_barrier(0)
;     ...
;         for (int t = t0; t < nt; t += 2) {
;             const bool last = (t == nt - 2);
;             const char* a1 = cA + (size_t)(t + 1) * kstepA;
;             const char* a2 = last ? nA : cA + (size_t)(t + 2) * kstepA; const char* b2 = last ? nB : cB + (size_t)(t + 2) * kstepB;
;             const char* a3 = a2 + kstepA; const char* b3 = b2 + kstepB;
;             if (last && has_next) S.a_ready(nxt);
;             if constexpr (SP2) {
;             PG8_LDB(B0, 0, 0); PG8_LDB(B1, 0, 1); PG8_SCHED; PG8_LDA(At, 0, 0); PG8_STAGEA(PG8_SA(1, 1), a1 + hstepA, voffA);
;     ...
;             PG8_LDA(At, 1, 1); PG8_STAGEB(PG8_SB(1, 0), b3, voffB); PG8_STAGEB(PG8_SB(1, 1), b3 + hstepB, voffB); PG8_STAGEA(PG8_SA(1, 0), a3, voffA);
;             PG8_WAIT_V(8); PG8_WAIT_L(0); PG8_BAR; PG8_MMA(1, 0, At, B0); PG8_MMA(1, 1, At, B1); PG8_BAR; PG8_SCHED;
	s_add_u32 s36, s16, 0x8000
	s_addc_u32 s37, s17, 0
	s_add_i32 s83, s83, s38
	v_lshl_add_u64 v[210:211], s[36:37], 0, v[16:17]
	s_mov_b32 m0, s83
	ds_read_b128 v[178:181], v161 offset:49152
	ds_read_b128 v[182:185], v161 offset:50176
	ds_read_b128 v[186:189], v161 offset:51200
	ds_read_b128 v[190:193], v161 offset:52224
	ds_read_b128 v[194:197], v161 offset:53248
	ds_read_b128 v[198:201], v161 offset:54272
	ds_read_b128 v[202:205], v161 offset:55296
	ds_read_b128 v[206:209], v161 offset:56320
	global_load_lds_dwordx4 v[210:211], off
	s_add_i32 m0, s83, 0x2000
	s_add_u32 s16, s16, 0xc000
	v_lshl_add_u64 v[210:211], s[36:37], 0, v[138:139]
	s_addc_u32 s17, s17, 0
	s_add_i32 s36, s90, s38
	global_load_lds_dwordx4 v[210:211], off
	v_lshl_add_u64 v[210:211], s[16:17], 0, v[16:17]
	s_mov_b32 m0, s36
	s_nop 0
	global_load_lds_dwordx4 v[210:211], off
	v_lshl_add_u64 v[210:211], s[16:17], 0, v[138:139]
	s_add_i32 m0, s36, 0x2000
	s_nop 0
	global_load_lds_dwordx4 v[210:211], off
	v_lshl_add_u64 v[210:211], s[26:27], 0, v[142:143]
	s_mov_b32 m0, s50
	s_nop 0
	global_load_lds_dwordx4 v[210:211], off
	v_lshl_add_u64 v[210:211], s[26:27], 0, v[140:141]
	s_mov_b32 m0, s51
	s_nop 0
	global_load_lds_dwordx4 v[210:211], off
	s_waitcnt vmcnt(8)
	s_waitcnt lgkmcnt(0)
	s_barrier
	v_mfma_f32_16x16x32_bf16 v[62:65], v[130:133], v[178:181], v[62:65]
	v_mfma_f32_16x16x32_bf16 v[58:61], v[148:151], v[178:181], v[58:61]
	v_mfma_f32_16x16x32_bf16 v[46:49], v[130:133], v[186:189], v[46:49]
	v_mfma_f32_16x16x32_bf16 v[42:45], v[148:151], v[186:189], v[42:45]
	v_mfma_f32_16x16x32_bf16 v[30:33], v[130:133], v[194:197], v[30:33]
	v_mfma_f32_16x16x32_bf16 v[26:29], v[148:151], v[194:197], v[26:29]
	v_mfma_f32_16x16x32_bf16 v[12:15], v[130:133], v[202:205], v[12:15]
	v_mfma_f32_16x16x32_bf16 v[8:11], v[148:151], v[202:205], v[8:11]
	v_mfma_f32_16x16x32_bf16 v[62:65], v[134:137], v[182:185], v[62:65]
	v_mfma_f32_16x16x32_bf16 v[58:61], v[152:155], v[182:185], v[58:61]
	v_mfma_f32_16x16x32_bf16 v[46:49], v[134:137], v[190:193], v[46:49]
	v_mfma_f32_16x16x32_bf16 v[42:45], v[152:155], v[190:193], v[42:45]
	v_mfma_f32_16x16x32_bf16 v[30:33], v[134:137], v[198:201], v[30:33]
	v_mfma_f32_16x16x32_bf16 v[26:29], v[152:155], v[198:201], v[26:29]
	v_mfma_f32_16x16x32_bf16 v[12:15], v[134:137], v[206:209], v[12:15]
	v_mfma_f32_16x16x32_bf16 v[8:11], v[152:155], v[206:209], v[8:11]
	v_mfma_f32_16x16x32_bf16 v[54:57], v[162:165], v[178:181], v[54:57]
	v_mfma_f32_16x16x32_bf16 v[50:53], v[170:173], v[178:181], v[50:53]
	v_mfma_f32_16x16x32_bf16 v[38:41], v[162:165], v[186:189], v[38:41]
	v_mfma_f32_16x16x32_bf16 v[34:37], v[170:173], v[186:189], v[34:37]
	v_mfma_f32_16x16x32_bf16 v[22:25], v[162:165], v[194:197], v[22:25]
	v_mfma_f32_16x16x32_bf16 v[18:21], v[170:173], v[194:197], v[18:21]
	v_mfma_f32_16x16x32_bf16 v[4:7], v[162:165], v[202:205], v[4:7]
	v_mfma_f32_16x16x32_bf16 v[0:3], v[170:173], v[202:205], v[0:3]
	v_mfma_f32_16x16x32_bf16 v[54:57], v[166:169], v[182:185], v[54:57]
	v_mfma_f32_16x16x32_bf16 v[50:53], v[174:177], v[182:185], v[50:53]
	v_mfma_f32_16x16x32_bf16 v[38:41], v[166:169], v[190:193], v[38:41]
	v_mfma_f32_16x16x32_bf16 v[34:37], v[174:177], v[190:193], v[34:37]
	v_mfma_f32_16x16x32_bf16 v[22:25], v[166:169], v[198:201], v[22:25]
	v_mfma_f32_16x16x32_bf16 v[18:21], v[174:177], v[198:201], v[18:21]
	v_mfma_f32_16x16x32_bf16 v[4:7], v[166:169], v[206:209], v[4:7]
	v_mfma_f32_16x16x32_bf16 v[0:3], v[174:177], v[206:209], v[0:3]
	s_barrier
	s_add_i32 s82, s82, 2
	s_add_u32 s24, s24, 0x10000
	s_addc_u32 s25, s25, 0
	s_add_u32 s0, s0, 0x10000
	s_addc_u32 s1, s1, 0
	v_add_u32_e32 v212, 0x10000, v157
.LBB0_848:
	s_add_u32 s16, s24, 0x4000
	s_addc_u32 s17, s25, 0
	s_cmpk_eq_i32 s82, 0xfc
	s_cselect_b32 s36, s73, s16
	s_cselect_b32 s37, s11, s17
	s_cselect_b32 s16, s78, s0
	s_cselect_b32 s17, s15, s1
	s_add_u32 s26, s36, 0x8000
	s_addc_u32 s27, s37, 0
	s_add_i32 s83, 0, 0x10000
	s_add_i32 s94, 0, 0x14000
	ds_read_b128 v[130:133], v212
	ds_read_b128 v[134:137], v212 offset:1024
	ds_read_b128 v[148:151], v212 offset:2048
	ds_read_b128 v[152:155], v212 offset:3072
	ds_read_b128 v[162:165], v212 offset:16384
	ds_read_b128 v[166:169], v212 offset:17408
	ds_read_b128 v[170:173], v212 offset:18432
	ds_read_b128 v[174:177], v212 offset:19456
	s_add_i32 m0, s39, 0xc000
	ds_read_b128 v[178:181], v161
	ds_read_b128 v[182:185], v161 offset:1024
	ds_read_b128 v[186:189], v161 offset:2048
	ds_read_b128 v[190:193], v161 offset:3072
	ds_read_b128 v[194:197], v161 offset:4096
	ds_read_b128 v[198:201], v161 offset:5120
	ds_read_b128 v[202:205], v161 offset:6144
	ds_read_b128 v[206:209], v161 offset:7168
	global_load_lds_dwordx4 v144, s[24:25]
	s_add_i32 m0, s39, 0xe000
	s_nop 0
	global_load_lds_dwordx4 v146, s[24:25]
	s_waitcnt vmcnt(8)
	s_waitcnt lgkmcnt(0)
	s_nop 0
	s_barrier
; #define PG8_STAGEA(bufoff, gbase, voff) PG8_STAGE_X(bufoff, gbase, voff, AUXA)
; #define PG8_STAGEB(bufoff, gbase, voff) PG8_STAGE_X(bufoff, gbase, voff, AUXB)
; #define PG8_LDA(dst, b, h) do { _Pragma("unroll") for (int m = 0; m < 4; ++m) _Pragma("unroll") for (int k = 0; k < 2; ++k) dst[m][k] = *(const PG8_LAS bf16x8*)(lds + PG8_SA(b, h) + aoff + m * 2048 + k * 1024); } while (0)
; #define PG8_LDB(dst, b, h) do { _Pragma("unroll") for (int n = 0; n < 2; ++n) _Pragma("unroll") for (int k = 0; k < 2; ++k) dst[n][k] = *(const PG8_LAS bf16x8*)(lds + PG8_SB(b, h) + boff + n * 2048 + k * 1024); } while (0)
; #define PG8_MMA(ai, bj, At, Bt) do { if (GEMM_PRIO_MODE == 0) __builtin_amdgcn_s_setprio(1); PG8_MMA_LOOPS \
;         acc[ai][bj][m][n] = __builtin_amdgcn_mfma_f32_16x16x32_bf16(Bt[n][k], At[m][k], acc[ai][bj][m][n], 0, 0, 0); if (GEMM_PRIO_MODE == 0) __builtin_amdgcn_s_setprio(0); } while (0)
; #define PG8_WAIT_V(n) asm volatile("s_waitcnt vmcnt(" #n ")" ::: "memory")
; #define PG8_WAIT_VR(n, nr, flag) asm volatile("s_cmp_eq_u32 %0, 0\n\ts_cbranch_scc1 .Lpg8s%=\n\ts_waitcnt vmcnt(" #nr ")\n\ts_branch .Lpg8d%=\n.Lpg8s%=:\n\ts_waitcnt vmcnt(" #n ")\n.Lpg8d%=:" :: "s"(flag) : "memory", "scc")
; #define PG8_WAIT_L(n) asm volatile("s_waitcnt lgkmcnt(" #n ")" ::: "memory")
; #define PG8_BAR __builtin_amdgcn_s_barrier()
; #define PG8_SCHED __builtin_amdgcn_sched_barrier(0)
;     ...
;             PG8_LDB(B0, 0, 0); PG8_LDB(B1, 0, 1); PG8_SCHED; PG8_LDA(At, 0, 0); PG8_STAGEA(PG8_SA(1, 1), a1 + hstepA, voffA);
;     ...
;             const int relax = __builtin_amdgcn_readfirstlane((t == 0 && ui > 0) ? 1 : 0);
;             PG8_WAIT_VR(8, 24, relax); PG8_WAIT_L(0); PG8_BAR; PG8_MMA(0, 0, At, B0); PG8_MMA(0, 1, At, B1); PG8_BAR; PG8_SCHED;
;     ...
;             PG8_WAIT_V(8); PG8_WAIT_L(0); PG8_BAR; PG8_MMA(0, 0, At, B0); PG8_MMA(0, 1, At, B1); PG8_BAR; PG8_SCHED;
;     ...
;             PG8_LDA(At, 0, 1); PG8_STAGEB(PG8_SB(0, 0), b2, voffB); PG8_STAGEB(PG8_SB(0, 1), b2 + hstepB, voffB); PG8_STAGEA(PG8_SA(0, 0), a2, voffA);
;     ...
;             PG8_WAIT_VR(8, 24, relax); PG8_WAIT_L(0); PG8_BAR; PG8_MMA(1, 0, At, B0); PG8_MMA(1, 1, At, B1); PG8_BAR; PG8_SCHED;
;     ...
;             PG8_WAIT_V(8); PG8_WAIT_L(0); PG8_BAR; PG8_MMA(1, 0, At, B0); PG8_MMA(1, 1, At, B1); PG8_BAR; PG8_SCHED;
	v_mfma_f32_16x16x32_bf16 v[126:129], v[130:133], v[178:181], v[126:129]
	v_mfma_f32_16x16x32_bf16 v[122:125], v[148:151], v[178:181], v[122:125]
	v_mfma_f32_16x16x32_bf16 v[110:113], v[130:133], v[186:189], v[110:113]
	v_mfma_f32_16x16x32_bf16 v[106:109], v[148:151], v[186:189], v[106:109]
	v_mfma_f32_16x16x32_bf16 v[94:97], v[130:133], v[194:197], v[94:97]
	v_mfma_f32_16x16x32_bf16 v[90:93], v[148:151], v[194:197], v[90:93]
	v_mfma_f32_16x16x32_bf16 v[78:81], v[130:133], v[202:205], v[78:81]
	v_mfma_f32_16x16x32_bf16 v[74:77], v[148:151], v[202:205], v[74:77]
	v_mfma_f32_16x16x32_bf16 v[126:129], v[134:137], v[182:185], v[126:129]
	v_mfma_f32_16x16x32_bf16 v[122:125], v[152:155], v[182:185], v[122:125]
	v_mfma_f32_16x16x32_bf16 v[110:113], v[134:137], v[190:193], v[110:113]
	v_mfma_f32_16x16x32_bf16 v[106:109], v[152:155], v[190:193], v[106:109]
	v_mfma_f32_16x16x32_bf16 v[94:97], v[134:137], v[198:201], v[94:97]
	v_mfma_f32_16x16x32_bf16 v[90:93], v[152:155], v[198:201], v[90:93]
	v_mfma_f32_16x16x32_bf16 v[78:81], v[134:137], v[206:209], v[78:81]
	v_mfma_f32_16x16x32_bf16 v[74:77], v[152:155], v[206:209], v[74:77]
	v_mfma_f32_16x16x32_bf16 v[118:121], v[162:165], v[178:181], v[118:121]
	v_mfma_f32_16x16x32_bf16 v[114:117], v[170:173], v[178:181], v[114:117]
	v_mfma_f32_16x16x32_bf16 v[102:105], v[162:165], v[186:189], v[102:105]
	v_mfma_f32_16x16x32_bf16 v[98:101], v[170:173], v[186:189], v[98:101]
	v_mfma_f32_16x16x32_bf16 v[86:89], v[162:165], v[194:197], v[86:89]
	v_mfma_f32_16x16x32_bf16 v[82:85], v[170:173], v[194:197], v[82:85]
	v_mfma_f32_16x16x32_bf16 v[70:73], v[162:165], v[202:205], v[70:73]
	v_mfma_f32_16x16x32_bf16 v[66:69], v[170:173], v[202:205], v[66:69]
	v_mfma_f32_16x16x32_bf16 v[118:121], v[166:169], v[182:185], v[118:121]
	v_mfma_f32_16x16x32_bf16 v[114:117], v[174:177], v[182:185], v[114:117]
	v_mfma_f32_16x16x32_bf16 v[102:105], v[166:169], v[190:193], v[102:105]
	v_mfma_f32_16x16x32_bf16 v[98:101], v[174:177], v[190:193], v[98:101]
	v_mfma_f32_16x16x32_bf16 v[86:89], v[166:169], v[198:201], v[86:89]
	v_mfma_f32_16x16x32_bf16 v[82:85], v[174:177], v[198:201], v[82:85]
	v_mfma_f32_16x16x32_bf16 v[70:73], v[166:169], v[206:209], v[70:73]
	v_mfma_f32_16x16x32_bf16 v[66:69], v[174:177], v[206:209], v[66:69]
	s_barrier
	s_add_i32 s83, s83, s38
	s_mov_b32 m0, s83
	ds_read_b128 v[178:181], v161 offset:16384
	ds_read_b128 v[182:185], v161 offset:17408
	ds_read_b128 v[186:189], v161 offset:18432
	ds_read_b128 v[190:193], v161 offset:19456
	ds_read_b128 v[194:197], v161 offset:20480
	ds_read_b128 v[198:201], v161 offset:21504
	ds_read_b128 v[202:205], v161 offset:22528
	ds_read_b128 v[206:209], v161 offset:23552
	global_load_lds_dwordx4 v16, s[16:17]
	s_add_i32 m0, s83, 0x2000
	s_add_u32 s90, s16, 0x4000
	s_addc_u32 s91, s17, 0
	s_add_i32 s83, s94, s38
	global_load_lds_dwordx4 v138, s[16:17]
	s_mov_b32 m0, s83
	s_nop 0
	global_load_lds_dwordx4 v16, s[90:91]
	s_add_i32 m0, s83, 0x2000
	s_nop 0
	global_load_lds_dwordx4 v138, s[90:91]
	s_mov_b32 m0, s39
	s_nop 0
	global_load_lds_dwordx4 v142, s[36:37]
	s_mov_b32 m0, s40
	s_nop 0
	global_load_lds_dwordx4 v140, s[36:37]
	s_waitcnt vmcnt(8)
	s_waitcnt lgkmcnt(0)
	s_nop 0
	s_barrier
	v_mfma_f32_16x16x32_bf16 v[62:65], v[130:133], v[178:181], v[62:65]
	v_mfma_f32_16x16x32_bf16 v[58:61], v[148:151], v[178:181], v[58:61]
	v_mfma_f32_16x16x32_bf16 v[46:49], v[130:133], v[186:189], v[46:49]
	v_mfma_f32_16x16x32_bf16 v[42:45], v[148:151], v[186:189], v[42:45]
	v_mfma_f32_16x16x32_bf16 v[30:33], v[130:133], v[194:197], v[30:33]
	v_mfma_f32_16x16x32_bf16 v[26:29], v[148:151], v[194:197], v[26:29]
	v_mfma_f32_16x16x32_bf16 v[12:15], v[130:133], v[202:205], v[12:15]
	v_mfma_f32_16x16x32_bf16 v[8:11], v[148:151], v[202:205], v[8:11]
	v_mfma_f32_16x16x32_bf16 v[62:65], v[134:137], v[182:185], v[62:65]
	v_mfma_f32_16x16x32_bf16 v[58:61], v[152:155], v[182:185], v[58:61]
	v_mfma_f32_16x16x32_bf16 v[46:49], v[134:137], v[190:193], v[46:49]
	v_mfma_f32_16x16x32_bf16 v[42:45], v[152:155], v[190:193], v[42:45]
	v_mfma_f32_16x16x32_bf16 v[30:33], v[134:137], v[198:201], v[30:33]
	v_mfma_f32_16x16x32_bf16 v[26:29], v[152:155], v[198:201], v[26:29]
	v_mfma_f32_16x16x32_bf16 v[12:15], v[134:137], v[206:209], v[12:15]
	v_mfma_f32_16x16x32_bf16 v[8:11], v[152:155], v[206:209], v[8:11]
	v_mfma_f32_16x16x32_bf16 v[54:57], v[162:165], v[178:181], v[54:57]
	v_mfma_f32_16x16x32_bf16 v[50:53], v[170:173], v[178:181], v[50:53]
	v_mfma_f32_16x16x32_bf16 v[38:41], v[162:165], v[186:189], v[38:41]
	v_mfma_f32_16x16x32_bf16 v[34:37], v[170:173], v[186:189], v[34:37]
	v_mfma_f32_16x16x32_bf16 v[22:25], v[162:165], v[194:197], v[22:25]
	v_mfma_f32_16x16x32_bf16 v[18:21], v[170:173], v[194:197], v[18:21]
	v_mfma_f32_16x16x32_bf16 v[4:7], v[162:165], v[202:205], v[4:7]
	v_mfma_f32_16x16x32_bf16 v[0:3], v[170:173], v[202:205], v[0:3]
	v_mfma_f32_16x16x32_bf16 v[54:57], v[166:169], v[182:185], v[54:57]
	v_mfma_f32_16x16x32_bf16 v[50:53], v[174:177], v[182:185], v[50:53]
	v_mfma_f32_16x16x32_bf16 v[38:41], v[166:169], v[190:193], v[38:41]
	v_mfma_f32_16x16x32_bf16 v[34:37], v[174:177], v[190:193], v[34:37]
	v_mfma_f32_16x16x32_bf16 v[22:25], v[166:169], v[198:201], v[22:25]
	v_mfma_f32_16x16x32_bf16 v[18:21], v[174:177], v[198:201], v[18:21]
	v_mfma_f32_16x16x32_bf16 v[4:7], v[166:169], v[206:209], v[4:7]
	v_mfma_f32_16x16x32_bf16 v[0:3], v[174:177], v[206:209], v[0:3]
	s_barrier
; #define PG8_STAGEA(bufoff, gbase, voff) PG8_STAGE_X(bufoff, gbase, voff, AUXA)
; #define PG8_STAGEB(bufoff, gbase, voff) PG8_STAGE_X(bufoff, gbase, voff, AUXB)
; #define PG8_LDA(dst, b, h) do { _Pragma("unroll") for (int m = 0; m < 4; ++m) _Pragma("unroll") for (int k = 0; k < 2; ++k) dst[m][k] = *(const PG8_LAS bf16x8*)(lds + PG8_SA(b, h) + aoff + m * 2048 + k * 1024); } while (0)
; #define PG8_LDB(dst, b, h) do { _Pragma("unroll") for (int n = 0; n < 2; ++n) _Pragma("unroll") for (int k = 0; k < 2; ++k) dst[n][k] = *(const PG8_LAS bf16x8*)(lds + PG8_SB(b, h) + boff + n * 2048 + k * 1024); } while (0)
; #define PG8_MMA(ai, bj, At, Bt) do { if (GEMM_PRIO_MODE == 0) __builtin_amdgcn_s_setprio(1); PG8_MMA_LOOPS \
;         acc[ai][bj][m][n] = __builtin_amdgcn_mfma_f32_16x16x32_bf16(Bt[n][k], At[m][k], acc[ai][bj][m][n], 0, 0, 0); if (GEMM_PRIO_MODE == 0) __builtin_amdgcn_s_setprio(0); } while (0)
; #define PG8_WAIT_V(n) asm volatile("s_waitcnt vmcnt(" #n ")" ::: "memory")
; #define PG8_WAIT_L(n) asm volatile("s_waitcnt lgkmcnt(" #n ")" ::: "memory")
; #define PG8_BAR __builtin_amdgcn_s_barrier()
; #define PG8_SCHED __builtin_amdgcn_sched_barrier(0)
;     ...
;             PG8_LDB(B0, 1, 0); PG8_LDB(B1, 1, 1); PG8_SCHED; PG8_LDA(At, 1, 0); PG8_STAGEA(PG8_SA(0, 1), a2 + hstepA, voffA);
;             PG8_WAIT_V(8); PG8_WAIT_L(0); PG8_BAR; PG8_MMA(0, 0, At, B0); PG8_MMA(0, 1, At, B1); PG8_BAR; PG8_SCHED;
;             PG8_LDA(At, 1, 1); PG8_STAGEB(PG8_SB(1, 0), b3, voffB); PG8_STAGEB(PG8_SB(1, 1), b3 + hstepB, voffB); PG8_STAGEA(PG8_SA(1, 0), a3, voffA);
;             PG8_WAIT_V(8); PG8_WAIT_L(0); PG8_BAR; PG8_MMA(1, 0, At, B0); PG8_MMA(1, 1, At, B1); PG8_BAR; PG8_SCHED;
	s_add_i32 s83, 0, 0x18000
	s_add_i32 s90, 0, 0x1c000
	ds_read_b128 v[130:133], v212 offset:32768
	ds_read_b128 v[134:137], v212 offset:33792
	ds_read_b128 v[148:151], v212 offset:34816
	ds_read_b128 v[152:155], v212 offset:35840
	ds_read_b128 v[162:165], v212 offset:49152
	ds_read_b128 v[166:169], v212 offset:50176
	ds_read_b128 v[170:173], v212 offset:51200
	ds_read_b128 v[174:177], v212 offset:52224
	s_add_u32 s36, s36, 0x4000
	s_addc_u32 s37, s37, 0
	s_mov_b32 m0, s41
	ds_read_b128 v[178:181], v161 offset:32768
	ds_read_b128 v[182:185], v161 offset:33792
	ds_read_b128 v[186:189], v161 offset:34816
	ds_read_b128 v[190:193], v161 offset:35840
	ds_read_b128 v[194:197], v161 offset:36864
	ds_read_b128 v[198:201], v161 offset:37888
	ds_read_b128 v[202:205], v161 offset:38912
	ds_read_b128 v[206:209], v161 offset:39936
	global_load_lds_dwordx4 v142, s[36:37]
	s_mov_b32 m0, s42
	s_nop 0
	global_load_lds_dwordx4 v140, s[36:37]
	s_waitcnt vmcnt(8)
	s_waitcnt lgkmcnt(0)
	s_barrier
	v_mfma_f32_16x16x32_bf16 v[126:129], v[130:133], v[178:181], v[126:129]
	v_mfma_f32_16x16x32_bf16 v[122:125], v[148:151], v[178:181], v[122:125]
	v_mfma_f32_16x16x32_bf16 v[110:113], v[130:133], v[186:189], v[110:113]
	v_mfma_f32_16x16x32_bf16 v[106:109], v[148:151], v[186:189], v[106:109]
	v_mfma_f32_16x16x32_bf16 v[94:97], v[130:133], v[194:197], v[94:97]
	v_mfma_f32_16x16x32_bf16 v[90:93], v[148:151], v[194:197], v[90:93]
	v_mfma_f32_16x16x32_bf16 v[78:81], v[130:133], v[202:205], v[78:81]
	v_mfma_f32_16x16x32_bf16 v[74:77], v[148:151], v[202:205], v[74:77]
	v_mfma_f32_16x16x32_bf16 v[126:129], v[134:137], v[182:185], v[126:129]
	v_mfma_f32_16x16x32_bf16 v[122:125], v[152:155], v[182:185], v[122:125]
	v_mfma_f32_16x16x32_bf16 v[110:113], v[134:137], v[190:193], v[110:113]
	v_mfma_f32_16x16x32_bf16 v[106:109], v[152:155], v[190:193], v[106:109]
	v_mfma_f32_16x16x32_bf16 v[94:97], v[134:137], v[198:201], v[94:97]
	v_mfma_f32_16x16x32_bf16 v[90:93], v[152:155], v[198:201], v[90:93]
	v_mfma_f32_16x16x32_bf16 v[78:81], v[134:137], v[206:209], v[78:81]
	v_mfma_f32_16x16x32_bf16 v[74:77], v[152:155], v[206:209], v[74:77]
	v_mfma_f32_16x16x32_bf16 v[118:121], v[162:165], v[178:181], v[118:121]
	v_mfma_f32_16x16x32_bf16 v[114:117], v[170:173], v[178:181], v[114:117]
	v_mfma_f32_16x16x32_bf16 v[102:105], v[162:165], v[186:189], v[102:105]
	v_mfma_f32_16x16x32_bf16 v[98:101], v[170:173], v[186:189], v[98:101]
	v_mfma_f32_16x16x32_bf16 v[86:89], v[162:165], v[194:197], v[86:89]
	v_mfma_f32_16x16x32_bf16 v[82:85], v[170:173], v[194:197], v[82:85]
	v_mfma_f32_16x16x32_bf16 v[70:73], v[162:165], v[202:205], v[70:73]
	v_mfma_f32_16x16x32_bf16 v[66:69], v[170:173], v[202:205], v[66:69]
	v_mfma_f32_16x16x32_bf16 v[118:121], v[166:169], v[182:185], v[118:121]
	v_mfma_f32_16x16x32_bf16 v[114:117], v[174:177], v[182:185], v[114:117]
	v_mfma_f32_16x16x32_bf16 v[102:105], v[166:169], v[190:193], v[102:105]
	v_mfma_f32_16x16x32_bf16 v[98:101], v[174:177], v[190:193], v[98:101]
	v_mfma_f32_16x16x32_bf16 v[86:89], v[166:169], v[198:201], v[86:89]
	v_mfma_f32_16x16x32_bf16 v[82:85], v[174:177], v[198:201], v[82:85]
	v_mfma_f32_16x16x32_bf16 v[70:73], v[166:169], v[206:209], v[70:73]
	v_mfma_f32_16x16x32_bf16 v[66:69], v[174:177], v[206:209], v[66:69]
	s_barrier
	s_add_u32 s36, s16, 0x8000
	s_addc_u32 s37, s17, 0
	s_add_i32 s83, s83, s38
	s_mov_b32 m0, s83
	ds_read_b128 v[178:181], v161 offset:49152
	ds_read_b128 v[182:185], v161 offset:50176
	ds_read_b128 v[186:189], v161 offset:51200
	ds_read_b128 v[190:193], v161 offset:52224
	ds_read_b128 v[194:197], v161 offset:53248
	ds_read_b128 v[198:201], v161 offset:54272
	ds_read_b128 v[202:205], v161 offset:55296
	ds_read_b128 v[206:209], v161 offset:56320
	global_load_lds_dwordx4 v16, s[36:37]
	s_add_i32 m0, s83, 0x2000
	s_add_u32 s16, s16, 0xc000
	s_addc_u32 s17, s17, 0
	global_load_lds_dwordx4 v138, s[36:37]
	s_add_i32 s36, s90, s38
	s_mov_b32 m0, s36
	s_nop 0
	global_load_lds_dwordx4 v16, s[16:17]
	s_add_i32 m0, s36, 0x2000
	s_nop 0
	global_load_lds_dwordx4 v138, s[16:17]
	s_mov_b32 m0, s50
	s_nop 0
	global_load_lds_dwordx4 v142, s[26:27]
	s_mov_b32 m0, s51
	s_nop 0
	global_load_lds_dwordx4 v140, s[26:27]
	s_waitcnt vmcnt(8)
	s_waitcnt lgkmcnt(0)
	s_nop 0
	s_nop 0
	s_barrier
	v_mfma_f32_16x16x32_bf16 v[62:65], v[130:133], v[178:181], v[62:65]
	v_mfma_f32_16x16x32_bf16 v[58:61], v[148:151], v[178:181], v[58:61]
	v_mfma_f32_16x16x32_bf16 v[46:49], v[130:133], v[186:189], v[46:49]
	v_mfma_f32_16x16x32_bf16 v[42:45], v[148:151], v[186:189], v[42:45]
	v_mfma_f32_16x16x32_bf16 v[30:33], v[130:133], v[194:197], v[30:33]
	v_mfma_f32_16x16x32_bf16 v[26:29], v[148:151], v[194:197], v[26:29]
	v_mfma_f32_16x16x32_bf16 v[12:15], v[130:133], v[202:205], v[12:15]
	v_mfma_f32_16x16x32_bf16 v[8:11], v[148:151], v[202:205], v[8:11]
	v_mfma_f32_16x16x32_bf16 v[62:65], v[134:137], v[182:185], v[62:65]
	v_mfma_f32_16x16x32_bf16 v[58:61], v[152:155], v[182:185], v[58:61]
	v_mfma_f32_16x16x32_bf16 v[46:49], v[134:137], v[190:193], v[46:49]
	v_mfma_f32_16x16x32_bf16 v[42:45], v[152:155], v[190:193], v[42:45]
	v_mfma_f32_16x16x32_bf16 v[30:33], v[134:137], v[198:201], v[30:33]
	v_mfma_f32_16x16x32_bf16 v[26:29], v[152:155], v[198:201], v[26:29]
	v_mfma_f32_16x16x32_bf16 v[12:15], v[134:137], v[206:209], v[12:15]
	v_mfma_f32_16x16x32_bf16 v[8:11], v[152:155], v[206:209], v[8:11]
	v_mfma_f32_16x16x32_bf16 v[54:57], v[162:165], v[178:181], v[54:57]
	v_mfma_f32_16x16x32_bf16 v[50:53], v[170:173], v[178:181], v[50:53]
	v_mfma_f32_16x16x32_bf16 v[38:41], v[162:165], v[186:189], v[38:41]
	v_mfma_f32_16x16x32_bf16 v[34:37], v[170:173], v[186:189], v[34:37]
	v_mfma_f32_16x16x32_bf16 v[22:25], v[162:165], v[194:197], v[22:25]
	v_mfma_f32_16x16x32_bf16 v[18:21], v[170:173], v[194:197], v[18:21]
	v_mfma_f32_16x16x32_bf16 v[4:7], v[162:165], v[202:205], v[4:7]
	v_mfma_f32_16x16x32_bf16 v[0:3], v[170:173], v[202:205], v[0:3]
	v_mfma_f32_16x16x32_bf16 v[54:57], v[166:169], v[182:185], v[54:57]
	v_mfma_f32_16x16x32_bf16 v[50:53], v[174:177], v[182:185], v[50:53]
	v_mfma_f32_16x16x32_bf16 v[38:41], v[166:169], v[190:193], v[38:41]
	v_mfma_f32_16x16x32_bf16 v[34:37], v[174:177], v[190:193], v[34:37]
	v_mfma_f32_16x16x32_bf16 v[22:25], v[166:169], v[198:201], v[22:25]
	v_mfma_f32_16x16x32_bf16 v[18:21], v[174:177], v[198:201], v[18:21]
	v_mfma_f32_16x16x32_bf16 v[4:7], v[166:169], v[206:209], v[4:7]
	v_mfma_f32_16x16x32_bf16 v[0:3], v[174:177], v[206:209], v[0:3]
	s_barrier
	s_add_i32 s82, s82, 2
	s_add_u32 s24, s24, 0x10000
	s_addc_u32 s25, s25, 0
	s_add_u32 s0, s0, 0x10000
	s_addc_u32 s1, s1, 0
	s_cmpk_gt_u32 s82, 0xfd
	s_cbranch_scc0 .LBB0_848
	s_and_b64 vcc, exec, s[8:9]
	s_cbranch_vccz .LBB0_851
	s_barrier
